# stacked: phase-2 dead in-place q*exp stores removed, phase-3 decay via LDS copy, phase-1 SiLU-gate tile epilogue staged through LDS with 16-byte stores (f32 rcp-based SiLU)
# speedup vs baseline: 1.1146x; 1.0039x over previous
.LBB0_210:
	s_bfe_u32 s7, s6, 0x20004
	s_and_b32 s0, s6, 15
	s_lshl_b32 s8, s0, 5
	s_lshl_b32 s9, s7, 9
	s_or_b32 s8, s9, s8
	v_or_b32_e32 v0, s8, v178
	s_ashr_i32 s1, s6, 6
	s_lshl_b32 s17, s7, 22
	s_lshl_b32 s18, s1, 19
	s_or_b32 s17, s17, s18
	s_addk_i32 s17, 0x1000
	s_lshl_b32 s19, s7, 23
	s_lshl_b32 s18, s1, 20
	s_or_b32 s19, s19, s18
	s_lshl_b32 s18, s0, 12
	s_or_b32 s19, s19, s18
	s_mov_b64 s[20:21], 0x10000
	v_lshlrev_b32_e32 v186, 14, v0
	v_lshl_add_u32 v0, s7, 8, v179
	s_lshl_b32 s8, s1, 10
	v_ashrrev_i32_e32 v1, 31, v0
	s_ashr_i32 s9, s8, 31
	v_lshlrev_b64 v[0:1], 14, v[0:1]
	s_lshl_b64 s[8:9], s[8:9], 1
	v_lshl_add_u64 v[0:1], s[10:11], 0, v[0:1]
	v_lshl_add_u64 v[0:1], v[0:1], 0, s[8:9]
	v_mov_b32_e32 v161, v187
	v_lshl_add_u64 v[166:167], v[0:1], 0, v[160:161]
	v_lshrrev_b32_e32 v188, 6, v152
	v_and_b32_e32 v190, 63, v152
	v_lshlrev_b32_e32 v188, 13, v188
	v_lshl_or_b32 v188, v190, 4, v188
	v_add_u32_e32 v220, s17, v188
	v_mov_b32_e32 v221, 0
	v_lshl_add_u64 v[220:221], s[10:11], 0, v[220:221]
	v_add_co_u32_e32 v222, vcc, 0x8000, v220
	s_nop 1
	v_addc_co_u32_e32 v223, vcc, 0, v221, vcc
	v_add_co_u32_e32 v224, vcc, 0x8000, v222
	s_nop 1
	v_addc_co_u32_e32 v225, vcc, 0, v223, vcc
	v_add_co_u32_e32 v226, vcc, 0x8000, v224
	s_nop 1
	v_addc_co_u32_e32 v227, vcc, 0, v225, vcc
	v_add_co_u32_e32 v228, vcc, 0x8000, v226
	s_nop 1
	v_addc_co_u32_e32 v229, vcc, 0, v227, vcc
	v_add_co_u32_e32 v230, vcc, 0x8000, v228
	s_nop 1
	v_addc_co_u32_e32 v231, vcc, 0, v229, vcc
	v_add_co_u32_e32 v232, vcc, 0x8000, v230
	s_nop 1
	v_addc_co_u32_e32 v233, vcc, 0, v231, vcc
	v_add_co_u32_e32 v234, vcc, 0x8000, v232
	s_nop 1
	v_addc_co_u32_e32 v235, vcc, 0, v233, vcc
	v_add_co_u32_e32 v236, vcc, 0x8000, v234
	s_nop 1
	v_addc_co_u32_e32 v237, vcc, 0, v235, vcc
	v_add_co_u32_e32 v238, vcc, 0x8000, v236
	s_nop 1
	v_addc_co_u32_e32 v239, vcc, 0, v237, vcc
	v_add_co_u32_e32 v240, vcc, 0x8000, v238
	s_nop 1
	v_addc_co_u32_e32 v241, vcc, 0, v239, vcc
	v_add_co_u32_e32 v244, vcc, 0x8000, v240
	s_nop 1
	v_addc_co_u32_e32 v245, vcc, 0, v241, vcc
	v_add_co_u32_e32 v246, vcc, 0x8000, v244
	s_nop 1
	v_addc_co_u32_e32 v247, vcc, 0, v245, vcc
	v_add_co_u32_e32 v248, vcc, 0x8000, v246
	s_nop 1
	v_addc_co_u32_e32 v249, vcc, 0, v247, vcc
	v_add_co_u32_e32 v250, vcc, 0x8000, v248
	s_nop 1
	v_addc_co_u32_e32 v251, vcc, 0, v249, vcc
	v_add_co_u32_e32 v252, vcc, 0x8000, v250
	s_nop 1
	v_addc_co_u32_e32 v253, vcc, 0, v251, vcc
	global_load_dwordx4 v[0:3], v[220:221], off offset:-4096
	v_lshl_add_u64 v[4:5], s[2:3], 0, v[186:187]
	v_lshl_add_u64 v[4:5], v[4:5], 0, s[8:9]
	v_lshlrev_b32_e32 v188, 4, v190
	v_add_u32_e32 v168, s19, v188
	v_mov_b32_e32 v169, 0
	v_lshl_add_u64 v[168:169], s[2:3], 0, v[168:169]
	global_load_dwordx4 v[4:7], v[168:169], off
	v_add_co_u32_e32 v164, vcc, s79, v166
	s_lshl_b32 s8, s1, 4
	s_nop 0
	v_addc_co_u32_e32 v165, vcc, 0, v167, vcc
	global_load_dwordx4 v[8:11], v[220:221], off
	global_load_dwordx4 v[32:35], v[220:221], off offset:-3072
	global_load_dwordx4 v[36:39], v[168:169], off offset:1024
	global_load_dwordx4 v[40:43], v[220:221], off offset:1024
	global_load_dwordx4 v[44:47], v[220:221], off offset:-2048
	global_load_dwordx4 v[52:55], v[168:169], off offset:2048
	global_load_dwordx4 v[56:59], v[220:221], off offset:2048
	global_load_dwordx4 v[60:63], v[220:221], off offset:-1024
	global_load_dwordx4 v[64:67], v[168:169], off offset:3072
	v_lshl_add_u64 v[168:169], v[168:169], 0, s[20:21]
	s_ashr_i32 s9, s8, 31
	s_lshl_b64 s[8:9], s[8:9], 12
	s_add_u32 s14, s4, s8
	s_addc_u32 s15, s5, s9
	s_lshl_b32 s16, s7, 10
	global_load_dwordx4 v[68:71], v[220:221], off offset:3072
	s_add_u32 s14, s14, s16
	s_addc_u32 s15, s15, 0
	v_mov_b32_e32 v163, v187
	v_lshl_add_u64 v[12:13], v[154:155], 2, s[14:15]
	v_lshlrev_b32_e32 v170, 2, v152
	v_lshl_add_u32 v171, v154, 2, v162
	v_lshl_add_u64 v[96:97], v[152:153], 2, s[14:15]
	global_load_dword v72, v[96:97], off
	v_lshl_add_u64 v[96:97], v[96:97], 0, s[86:87]
	global_load_dword v73, v[96:97], off
	v_lshl_add_u64 v[96:97], v[96:97], 0, s[86:87]
	global_load_dword v74, v[96:97], off
	v_lshl_add_u64 v[96:97], v[96:97], 0, s[86:87]
	global_load_dword v75, v[96:97], off
	v_lshl_add_u64 v[96:97], v[96:97], 0, s[86:87]
	global_load_dword v76, v[96:97], off
	v_lshl_add_u64 v[96:97], v[96:97], 0, s[86:87]
	global_load_dword v77, v[96:97], off
	v_lshl_add_u64 v[96:97], v[96:97], 0, s[86:87]
	global_load_dword v78, v[96:97], off
	v_lshl_add_u64 v[96:97], v[96:97], 0, s[86:87]
	global_load_dword v79, v[96:97], off
	v_lshl_add_u64 v[96:97], v[96:97], 0, s[86:87]
	global_load_dword v84, v[96:97], off
	v_lshl_add_u64 v[96:97], v[96:97], 0, s[86:87]
	global_load_dword v85, v[96:97], off
	v_lshl_add_u64 v[96:97], v[96:97], 0, s[86:87]
	global_load_dword v86, v[96:97], off
	v_lshl_add_u64 v[96:97], v[96:97], 0, s[86:87]
	global_load_dword v87, v[96:97], off
	v_lshl_add_u64 v[96:97], v[96:97], 0, s[86:87]
	global_load_dword v88, v[96:97], off
	v_lshl_add_u64 v[96:97], v[96:97], 0, s[86:87]
	global_load_dword v89, v[96:97], off
	v_lshl_add_u64 v[96:97], v[96:97], 0, s[86:87]
	global_load_dword v90, v[96:97], off
	v_lshl_add_u64 v[96:97], v[96:97], 0, s[86:87]
	global_load_dword v91, v[96:97], off
	global_load_dwordx4 v[80:83], v[222:223], off offset:-4096
	global_load_dwordx4 v[92:95], v[168:169], off
	global_load_dwordx4 v[192:195], v[222:223], off
	global_load_dwordx4 v[204:207], v[222:223], off offset:-3072
	global_load_dwordx4 v[208:211], v[168:169], off offset:1024
	s_movk_i32 s14, 0x3000
	s_lshl_b32 s1, s1, 2
	s_or_b32 s7, s1, s7
	s_lshl_b32 s1, s7, 4
	s_waitcnt vmcnt(31) lgkmcnt(0)
	v_mfma_f32_32x32x16_bf16 v[16:31], v[0:3], v[4:7], 0
	s_waitcnt vmcnt(30)
	v_mfma_f32_32x32x16_bf16 v[0:15], v[8:11], v[4:7], 0
	s_waitcnt vmcnt(28)
	v_mfma_f32_32x32x16_bf16 v[16:31], v[32:35], v[36:39], v[16:31]
	global_load_dwordx4 v[32:35], v[222:223], off offset:1024
	s_waitcnt vmcnt(28)
	v_mfma_f32_32x32x16_bf16 v[0:15], v[40:43], v[36:39], v[0:15]
	global_load_dwordx4 v[40:43], v[222:223], off offset:-2048
	global_load_dwordx4 v[212:215], v[168:169], off offset:2048
	global_load_dwordx4 v[216:219], v[222:223], off offset:2048
	global_load_dwordx4 v[48:51], v[222:223], off offset:-1024
	global_load_dwordx4 v[108:111], v[224:225], off offset:-4096
	global_load_dwordx4 v[116:119], v[168:169], off offset:3072
	v_lshl_add_u64 v[168:169], v[168:169], 0, s[20:21]
	global_load_dwordx4 v[124:127], v[222:223], off offset:3072
	global_load_dwordx4 v[100:103], v[224:225], off
	global_load_dwordx4 v[104:107], v[168:169], off
	v_add_co_u32_e32 v36, vcc, s29, v170
	s_nop 1
	v_addc_co_u32_e32 v37, vcc, 0, v171, vcc
	s_waitcnt vmcnt(35)
	v_mfma_f32_32x32x16_bf16 v[16:31], v[44:47], v[52:55], v[16:31]
	v_add_co_u32_e32 v174, vcc, s76, v170
	s_nop 1
	v_addc_co_u32_e32 v175, vcc, 0, v171, vcc
	s_waitcnt vmcnt(32)
	v_mfma_f32_32x32x16_bf16 v[16:31], v[60:63], v[64:67], v[16:31]
	v_add_co_u32_e32 v176, vcc, s14, v170
	s_mov_b32 s14, 0xf000
	s_nop 0
	v_addc_co_u32_e32 v177, vcc, 0, v171, vcc
	v_add_co_u32_e32 v172, vcc, s14, v170
	v_mfma_f32_32x32x16_bf16 v[0:15], v[56:59], v[52:55], v[0:15]
	s_waitcnt vmcnt(31)
	s_nop 4
	s_waitcnt vmcnt(15)
	s_barrier
	ds_write_b32 v170, v72
	ds_write_b32 v170, v73 offset:1024
	ds_write_b32 v170, v74 offset:2048
	ds_write_b32 v170, v75 offset:3072
	ds_write_b32 v170, v76 offset:4096
	ds_write_b32 v170, v77 offset:5120
	ds_write_b32 v170, v78 offset:6144
	ds_write_b32 v170, v79 offset:7168
	ds_write_b32 v170, v84 offset:8192
	ds_write_b32 v170, v85 offset:9216
	ds_write_b32 v170, v86 offset:10240
	ds_write_b32 v170, v87 offset:11264
	ds_write_b32 v170, v88 offset:12288
	ds_write_b32 v170, v89 offset:13312
	ds_write_b32 v170, v90 offset:14336
	ds_write_b32 v170, v91 offset:15360
	s_waitcnt lgkmcnt(0)
	s_barrier
	ds_read_b128 v[72:75], v171 offset:96
	ds_read_b128 v[76:79], v171 offset:64
	ds_read_b128 v[84:87], v171 offset:32
	ds_read_b128 v[88:91], v171
	ds_read_b128 v[96:99], v171 offset:224
	ds_read_b128 v[180:183], v171 offset:192
	ds_read_b128 v[196:199], v171 offset:160
	ds_read_b128 v[200:203], v171 offset:128
	s_waitcnt lgkmcnt(7)
	v_mul_f32_e64 v30, v74, v30
	v_mul_f32_e64 v31, v75, v31
	v_mul_f32_e64 v28, v72, v28
	v_mul_f32_e64 v29, v73, v29
	global_load_dwordx4 v[36:39], v[224:225], off offset:-3072
	global_load_dwordx4 v[72:75], v[168:169], off offset:1024
	s_waitcnt vmcnt(33)
	s_waitcnt lgkmcnt(6)
	v_pk_mul_f32 v[26:27], v[78:79], v[26:27]
	v_pk_mul_f32 v[24:25], v[76:77], v[24:25]
	global_load_dwordx4 v[76:79], v[224:225], off offset:1024
	s_waitcnt vmcnt(17)
	s_waitcnt lgkmcnt(5)
	v_pk_mul_f32 v[22:23], v[86:87], v[22:23]
	v_mfma_f32_32x32x16_bf16 v[0:15], v[68:71], v[64:67], v[0:15]
	global_load_dwordx4 v[68:71], v[224:225], off offset:-2048
	global_load_dwordx4 v[52:55], v[168:169], off offset:2048
	global_load_dwordx4 v[64:67], v[224:225], off offset:-1024
	global_load_dwordx4 v[44:47], v[168:169], off offset:3072
	v_lshl_add_u64 v[168:169], v[168:169], 0, s[20:21]
	global_load_dwordx4 v[60:63], v[224:225], off offset:2048
	v_pk_mul_f32 v[20:21], v[84:85], v[20:21]
	s_waitcnt vmcnt(22)
	s_waitcnt lgkmcnt(4)
	v_pk_mul_f32 v[18:19], v[90:91], v[18:19]
	v_pk_mul_f32 v[16:17], v[88:89], v[16:17]
	ds_read_b128 v[148:151], v171 offset:1120
	v_addc_co_u32_e32 v173, vcc, 0, v171, vcc
	s_waitcnt vmcnt(21)
	v_mfma_f32_32x32x16_bf16 v[16:31], v[80:83], v[92:95], v[16:31]
	s_waitcnt vmcnt(21)
	ds_read_b128 v[144:147], v171 offset:1088
	s_waitcnt lgkmcnt(5)
	v_mul_f32_e64 v14, v98, v14
	v_mul_f32_e64 v15, v99, v15
	v_mul_f32_e64 v12, v96, v12
	v_mul_f32_e64 v13, v97, v13
	ds_read_b128 v[136:139], v171 offset:1056
	s_waitcnt vmcnt(21)
	s_waitcnt lgkmcnt(5)
	v_pk_mul_f32 v[10:11], v[182:183], v[10:11]
	ds_read_b128 v[128:131], v171 offset:1024
	v_pk_mul_f32 v[8:9], v[180:181], v[8:9]
	s_waitcnt vmcnt(20)
	s_waitcnt lgkmcnt(5)
	v_pk_mul_f32 v[6:7], v[198:199], v[6:7]
	v_pk_mul_f32 v[4:5], v[196:197], v[4:5]
	ds_read_b128 v[140:143], v171 offset:1248
	s_waitcnt vmcnt(20)
	s_waitcnt lgkmcnt(5)
	v_pk_mul_f32 v[2:3], v[202:203], v[2:3]
	v_pk_mul_f32 v[0:1], v[200:201], v[0:1]
	ds_read_b128 v[132:135], v171 offset:1216
	s_waitcnt vmcnt(18)
	v_mfma_f32_32x32x16_bf16 v[16:31], v[204:207], v[208:211], v[16:31]
	s_movk_i32 s14, 0x4000
	v_mfma_f32_32x32x16_bf16 v[0:15], v[192:195], v[92:95], v[0:15]
	ds_read_b128 v[120:123], v171 offset:1184
	s_waitcnt vmcnt(17)
	v_mfma_f32_32x32x16_bf16 v[0:15], v[32:35], v[208:211], v[0:15]
	s_waitcnt vmcnt(15)
	ds_read_b128 v[112:115], v171 offset:1152
	v_mfma_f32_32x32x16_bf16 v[16:31], v[40:43], v[212:215], v[16:31]
	global_load_dwordx4 v[56:59], v[224:225], off offset:3072
	global_load_dwordx4 v[40:43], v[226:227], off offset:-4096
	global_load_dwordx4 v[32:35], v[168:169], off
	s_waitcnt vmcnt(17)
	v_mfma_f32_32x32x16_bf16 v[0:15], v[216:219], v[212:215], v[0:15]
	s_waitcnt vmcnt(14)
	v_mfma_f32_32x32x16_bf16 v[16:31], v[48:51], v[116:119], v[16:31]
	s_waitcnt vmcnt(11)
	s_nop 4
	s_waitcnt lgkmcnt(7)
	v_pk_mul_f32 v[30:31], v[150:151], v[30:31]
	v_mfma_f32_32x32x16_bf16 v[0:15], v[124:127], v[116:119], v[0:15]
	v_mul_f32_e64 v28, v148, v28
	v_mul_f32_e64 v29, v149, v29
	s_waitcnt lgkmcnt(6)
	v_mul_f32_e64 v26, v146, v26
	v_mul_f32_e64 v27, v147, v27
	v_mul_f32_e64 v24, v144, v24
	v_mul_f32_e64 v25, v145, v25
	s_waitcnt lgkmcnt(5)
	v_pk_mul_f32 v[22:23], v[138:139], v[22:23]
	v_pk_mul_f32 v[20:21], v[136:137], v[20:21]
	s_waitcnt lgkmcnt(4)
	v_pk_mul_f32 v[18:19], v[130:131], v[18:19]
	v_pk_mul_f32 v[16:17], v[128:129], v[16:17]
	s_waitcnt vmcnt(11)
	s_nop 0
	s_waitcnt lgkmcnt(3)
	v_pk_mul_f32 v[14:15], v[142:143], v[14:15]
	v_pk_mul_f32 v[12:13], v[140:141], v[12:13]
	v_mfma_f32_32x32x16_bf16 v[16:31], v[108:111], v[104:107], v[16:31]
	ds_read_b128 v[92:95], v171 offset:2112
	s_waitcnt lgkmcnt(3)
	v_mul_f32_e64 v10, v134, v10
	v_mul_f32_e64 v11, v135, v11
	v_mul_f32_e64 v8, v132, v8
	v_mul_f32_e64 v9, v133, v9
	s_waitcnt lgkmcnt(2)
	v_mul_f32_e64 v6, v122, v6
	ds_read_b128 v[96:99], v171 offset:2144
	v_mul_f32_e64 v7, v123, v7
	v_pk_mul_f32 v[4:5], v[120:121], v[4:5]
	s_waitcnt lgkmcnt(2)
	v_pk_mul_f32 v[2:3], v[114:115], v[2:3]
	v_pk_mul_f32 v[0:1], v[112:113], v[0:1]
	v_add_co_u32_e32 v140, vcc, s14, v170
	s_nop 0
	v_mfma_f32_32x32x16_bf16 v[0:15], v[100:103], v[104:107], v[0:15]
	global_load_dwordx4 v[100:103], v[226:227], off offset:-3072
	ds_read_b128 v[88:91], v171 offset:2080
	global_load_dwordx4 v[104:107], v[168:169], off offset:1024
	v_addc_co_u32_e32 v141, vcc, 0, v171, vcc
	s_movk_i32 s14, 0x5000
	ds_read_b128 v[84:87], v171 offset:2048
	s_waitcnt vmcnt(11)
	v_mfma_f32_32x32x16_bf16 v[16:31], v[36:39], v[72:75], v[16:31]
	global_load_dwordx4 v[36:39], v[226:227], off offset:-2048
	global_load_dwordx4 v[108:111], v[168:169], off offset:2048
	s_waitcnt vmcnt(10)
	v_mfma_f32_32x32x16_bf16 v[16:31], v[68:71], v[52:55], v[16:31]
	v_mfma_f32_32x32x16_bf16 v[0:15], v[76:79], v[72:75], v[0:15]
	global_load_dwordx4 v[72:75], v[226:227], off offset:-1024
	global_load_dwordx4 v[76:79], v[168:169], off offset:3072
	v_lshl_add_u64 v[168:169], v[168:169], 0, s[20:21]
	ds_read_b128 v[112:115], v171 offset:2272
	ds_read_b128 v[116:119], v171 offset:2240
	global_load_dwordx4 v[68:71], v[226:227], off
	ds_read_b128 v[120:123], v171 offset:2208
	s_waitcnt vmcnt(11)
	v_mfma_f32_32x32x16_bf16 v[16:31], v[64:67], v[44:47], v[16:31]
	global_load_dwordx4 v[64:67], v[226:227], off offset:1024
	ds_read_b128 v[124:127], v171 offset:2176
	s_waitcnt vmcnt(11)
	v_mfma_f32_32x32x16_bf16 v[0:15], v[60:63], v[52:55], v[0:15]
	global_load_dwordx4 v[52:55], v[226:227], off offset:2048
	global_load_dwordx4 v[60:63], v[226:227], off offset:3072
	s_waitcnt vmcnt(10)
	s_nop 5
	s_waitcnt lgkmcnt(7)
	v_mul_f32_e64 v26, v94, v26
	v_mul_f32_e64 v27, v95, v27
	v_mfma_f32_32x32x16_bf16 v[0:15], v[56:59], v[44:47], v[0:15]
	global_load_dwordx4 v[44:47], v[228:229], off offset:-4096
	s_waitcnt vmcnt(11)
	s_waitcnt lgkmcnt(6)
	v_mul_f32_e64 v30, v98, v30
	v_mul_f32_e64 v31, v99, v31
	v_mul_f32_e64 v28, v96, v28
	v_mul_f32_e64 v29, v97, v29
	v_pk_mul_f32 v[24:25], v[92:93], v[24:25]
	s_waitcnt vmcnt(11)
	s_waitcnt lgkmcnt(5)
	v_pk_mul_f32 v[22:23], v[90:91], v[22:23]
	v_pk_mul_f32 v[20:21], v[88:89], v[20:21]
	ds_read_b128 v[92:95], v171 offset:3168
	s_waitcnt lgkmcnt(5)
	v_pk_mul_f32 v[18:19], v[86:87], v[18:19]
	v_pk_mul_f32 v[16:17], v[84:85], v[16:17]
	s_waitcnt vmcnt(5)
	s_waitcnt lgkmcnt(4)
	v_pk_mul_f32 v[14:15], v[114:115], v[14:15]
	ds_read_b128 v[56:59], v171 offset:3136
	v_mfma_f32_32x32x16_bf16 v[16:31], v[40:43], v[32:35], v[16:31]
	global_load_dwordx4 v[40:43], v[168:169], off
	ds_read_b128 v[80:83], v171 offset:3104
	global_load_dwordx4 v[84:87], v[228:229], off offset:-3072
	global_load_dwordx4 v[96:99], v[168:169], off offset:1024
	v_mul_f32_e64 v12, v112, v12
	v_mul_f32_e64 v13, v113, v13
	s_waitcnt vmcnt(8)
	s_waitcnt lgkmcnt(5)
	v_pk_mul_f32 v[10:11], v[118:119], v[10:11]
	ds_read_b128 v[88:91], v171 offset:3072
	v_pk_mul_f32 v[8:9], v[116:117], v[8:9]
	s_waitcnt vmcnt(8)
	s_waitcnt lgkmcnt(5)
	v_pk_mul_f32 v[6:7], v[122:123], v[6:7]
	v_pk_mul_f32 v[4:5], v[120:121], v[4:5]
	v_mfma_f32_32x32x16_bf16 v[16:31], v[100:103], v[104:107], v[16:31]
	s_waitcnt vmcnt(7)
	s_waitcnt lgkmcnt(4)
	v_mul_f32_e64 v2, v126, v2
	v_mul_f32_e64 v3, v127, v3
	v_mul_f32_e64 v0, v124, v0
	v_mul_f32_e64 v1, v125, v1
	v_mfma_f32_32x32x16_bf16 v[16:31], v[36:39], v[108:111], v[16:31]
	global_load_dwordx4 v[36:39], v[228:229], off offset:-2048
	global_load_dwordx4 v[100:103], v[168:169], off offset:2048
	global_load_dwordx4 v[128:131], v[228:229], off offset:-1024
	global_load_dwordx4 v[132:135], v[168:169], off offset:3072
	v_lshl_add_u64 v[168:169], v[168:169], 0, s[20:21]
	global_load_dwordx4 v[136:139], v[228:229], off
	v_mfma_f32_32x32x16_bf16 v[0:15], v[68:71], v[32:35], v[0:15]
	v_mfma_f32_32x32x16_bf16 v[16:31], v[72:75], v[76:79], v[16:31]
	ds_read_b128 v[72:75], v171 offset:3264
	s_waitcnt vmcnt(11)
	v_mfma_f32_32x32x16_bf16 v[0:15], v[64:67], v[104:107], v[0:15]
	ds_read_b128 v[112:115], v171 offset:3296
	global_load_dwordx4 v[64:67], v[228:229], off offset:1024
	s_waitcnt vmcnt(9)
	s_nop 3
	s_waitcnt lgkmcnt(5)
	v_mul_f32_e64 v30, v94, v30
	ds_read_b128 v[32:35], v171 offset:3232
	v_mul_f32_e64 v31, v95, v31
	v_mul_f32_e64 v28, v92, v28
	v_mul_f32_e64 v29, v93, v29
	ds_read_b128 v[68:71], v171 offset:3200
	s_waitcnt lgkmcnt(6)
	v_pk_mul_f32 v[26:27], v[58:59], v[26:27]
	v_pk_mul_f32 v[24:25], v[56:57], v[24:25]
	s_waitcnt lgkmcnt(5)
	v_pk_mul_f32 v[22:23], v[82:83], v[22:23]
	v_pk_mul_f32 v[20:21], v[80:81], v[20:21]
	v_mfma_f32_32x32x16_bf16 v[0:15], v[52:55], v[108:111], v[0:15]
	global_load_dwordx4 v[52:55], v[228:229], off offset:2048
	global_load_dwordx4 v[104:107], v[228:229], off offset:3072
	s_waitcnt vmcnt(11)
	s_waitcnt lgkmcnt(4)
	v_mul_f32_e64 v18, v90, v18
	v_mul_f32_e64 v19, v91, v19
	v_pk_mul_f32 v[16:17], v[88:89], v[16:17]
	ds_read_b128 v[56:59], v171 offset:4096
	s_waitcnt vmcnt(10)
	v_mfma_f32_32x32x16_bf16 v[16:31], v[44:47], v[40:43], v[16:31]
	v_mfma_f32_32x32x16_bf16 v[0:15], v[60:63], v[76:79], v[0:15]
	ds_read_b128 v[60:63], v171 offset:4192
	global_load_dwordx4 v[80:83], v[230:231], off offset:-4096
	s_waitcnt vmcnt(9)
	v_mfma_f32_32x32x16_bf16 v[16:31], v[84:87], v[96:99], v[16:31]
	global_load_dwordx4 v[84:87], v[168:169], off
	global_load_dwordx4 v[88:91], v[230:231], off offset:-3072
	s_waitcnt vmcnt(6)
	s_nop 2
	s_waitcnt lgkmcnt(5)
	v_mul_f32_e64 v10, v74, v10
	v_mul_f32_e64 v11, v75, v11
	v_mfma_f32_32x32x16_bf16 v[16:31], v[36:39], v[100:103], v[16:31]
	global_load_dwordx4 v[36:39], v[168:169], off offset:1024
	global_load_dwordx4 v[92:95], v[230:231], off offset:-2048
	global_load_dwordx4 v[108:111], v[168:169], off offset:2048
	global_load_dwordx4 v[116:119], v[230:231], off offset:-1024
	ds_read_b128 v[76:79], v171 offset:4160
	s_waitcnt vmcnt(10)
	s_waitcnt lgkmcnt(5)
	v_pk_mul_f32 v[14:15], v[114:115], v[14:15]
	v_pk_mul_f32 v[12:13], v[112:113], v[12:13]
	ds_read_b128 v[44:47], v171 offset:4128
	v_pk_mul_f32 v[8:9], v[72:73], v[8:9]
	s_waitcnt vmcnt(10)
	s_waitcnt lgkmcnt(5)
	v_pk_mul_f32 v[6:7], v[34:35], v[6:7]
	v_pk_mul_f32 v[4:5], v[32:33], v[4:5]
	s_waitcnt vmcnt(10)
	s_waitcnt lgkmcnt(4)
	v_pk_mul_f32 v[2:3], v[70:71], v[2:3]
	v_pk_mul_f32 v[0:1], v[68:69], v[0:1]
	v_mfma_f32_32x32x16_bf16 v[16:31], v[128:131], v[132:135], v[16:31]
	s_nop 0
	v_mfma_f32_32x32x16_bf16 v[0:15], v[136:139], v[40:43], v[0:15]
	global_load_dwordx4 v[32:35], v[168:169], off offset:3072
	v_lshl_add_u64 v[168:169], v[168:169], 0, s[20:21]
	s_waitcnt vmcnt(8)
	s_nop 4
	s_waitcnt lgkmcnt(3)
	v_pk_mul_f32 v[18:19], v[58:59], v[18:19]
	v_pk_mul_f32 v[16:17], v[56:57], v[16:17]
	s_waitcnt vmcnt(8)
	s_waitcnt lgkmcnt(2)
	v_pk_mul_f32 v[30:31], v[62:63], v[30:31]
	v_mfma_f32_32x32x16_bf16 v[0:15], v[64:67], v[96:99], v[0:15]
	global_load_dwordx4 v[64:67], v[230:231], off
	v_add_co_u32_e32 v140, vcc, s14, v170
	ds_read_b128 v[40:43], v171 offset:4320
	s_movk_i32 s14, 0x6000
	s_nop 0
	v_addc_co_u32_e32 v141, vcc, 0, v171, vcc
	v_add_co_u32_e32 v142, vcc, s14, v170
	ds_read_b128 v[68:71], v171 offset:4288
	v_mfma_f32_32x32x16_bf16 v[0:15], v[52:55], v[100:103], v[0:15]
	global_load_dwordx4 v[52:55], v[230:231], off offset:1024
	global_load_dwordx4 v[100:103], v[230:231], off offset:2048
	global_load_dwordx4 v[112:115], v[230:231], off offset:3072
	v_addc_co_u32_e32 v143, vcc, 0, v171, vcc
	ds_read_b128 v[72:75], v171 offset:4256
	v_mul_f32_e64 v28, v60, v28
	v_mul_f32_e64 v29, v61, v29
	s_waitcnt vmcnt(12)
	s_waitcnt lgkmcnt(4)
	v_pk_mul_f32 v[26:27], v[78:79], v[26:27]
	v_pk_mul_f32 v[24:25], v[76:77], v[24:25]
	s_waitcnt vmcnt(12)
	s_waitcnt lgkmcnt(3)
	v_pk_mul_f32 v[22:23], v[46:47], v[22:23]
	v_mfma_f32_32x32x16_bf16 v[0:15], v[104:107], v[132:135], v[0:15]
	global_load_dwordx4 v[104:107], v[232:233], off offset:-4096
	ds_read_b128 v[96:99], v171 offset:4224
	v_mul_f32_e64 v20, v44, v20
	v_mul_f32_e64 v21, v45, v21
	s_movk_i32 s14, 0x7000
	v_add_co_u32_e32 v174, vcc, s14, v170
	s_waitcnt vmcnt(11)
	v_mfma_f32_32x32x16_bf16 v[16:31], v[80:83], v[84:87], v[16:31]
	ds_read_b128 v[44:47], v171 offset:5216
	global_load_dwordx4 v[80:83], v[168:169], off
	global_load_dwordx4 v[120:123], v[232:233], off offset:-3072
	v_addc_co_u32_e32 v175, vcc, 0, v171, vcc
	s_mov_b32 s14, 0x8000
	v_add_co_u32_e32 v176, vcc, s14, v170
	s_mov_b32 s14, 0x9000
	s_waitcnt vmcnt(11)
	v_mfma_f32_32x32x16_bf16 v[16:31], v[88:91], v[36:39], v[16:31]
	global_load_dwordx4 v[88:91], v[168:169], off offset:1024
	ds_read_b128 v[60:63], v171 offset:5184
	global_load_dwordx4 v[124:127], v[232:233], off offset:-2048
	v_addc_co_u32_e32 v177, vcc, 0, v171, vcc
	ds_read_b128 v[56:59], v171 offset:5152
	s_waitcnt vmcnt(9)
	s_waitcnt lgkmcnt(6)
	v_mul_f32_e64 v14, v42, v14
	v_mul_f32_e64 v15, v43, v15
	v_pk_mul_f32 v[12:13], v[40:41], v[12:13]
	ds_read_b128 v[76:79], v171 offset:5120
	s_waitcnt vmcnt(9)
	s_waitcnt lgkmcnt(6)
	v_pk_mul_f32 v[10:11], v[70:71], v[10:11]
	v_mfma_f32_32x32x16_bf16 v[16:31], v[92:95], v[108:111], v[16:31]
	v_mul_f32_e64 v8, v68, v8
	v_mul_f32_e64 v9, v69, v9
	s_waitcnt vmcnt(9)
	s_waitcnt lgkmcnt(5)
	v_mul_f32_e64 v6, v74, v6
	v_mul_f32_e64 v7, v75, v7
	v_pk_mul_f32 v[4:5], v[72:73], v[4:5]
	global_load_dwordx4 v[92:95], v[168:169], off offset:2048
	global_load_dwordx4 v[128:131], v[232:233], off offset:-1024
	global_load_dwordx4 v[132:135], v[168:169], off offset:3072
	v_lshl_add_u64 v[168:169], v[168:169], 0, s[20:21]
	global_load_dwordx4 v[136:139], v[232:233], off
	s_waitcnt vmcnt(12)
	s_waitcnt lgkmcnt(4)
	v_pk_mul_f32 v[2:3], v[98:99], v[2:3]
	v_pk_mul_f32 v[0:1], v[96:97], v[0:1]
	v_mfma_f32_32x32x16_bf16 v[16:31], v[116:119], v[32:35], v[16:31]
	ds_read_b128 v[40:43], v171 offset:5344
	ds_read_b128 v[116:119], v171 offset:5312
	v_mfma_f32_32x32x16_bf16 v[0:15], v[64:67], v[84:87], v[0:15]
	ds_read_b128 v[68:71], v171 offset:5280
	s_waitcnt vmcnt(8)
	s_nop 5
	ds_read_b128 v[64:67], v171 offset:5248
	s_waitcnt lgkmcnt(7)
	v_mul_f32_e64 v30, v46, v30
	v_mul_f32_e64 v31, v47, v31
	v_mfma_f32_32x32x16_bf16 v[0:15], v[52:55], v[36:39], v[0:15]
	global_load_dwordx4 v[36:39], v[232:233], off offset:1024
	global_load_dwordx4 v[52:55], v[232:233], off offset:2048
	global_load_dwordx4 v[72:75], v[232:233], off offset:3072
	v_mul_f32_e64 v28, v44, v28
	v_mul_f32_e64 v29, v45, v29
	s_waitcnt vmcnt(11)
	s_waitcnt lgkmcnt(6)
	v_pk_mul_f32 v[26:27], v[62:63], v[26:27]
	v_pk_mul_f32 v[24:25], v[60:61], v[24:25]
	s_waitcnt lgkmcnt(5)
	v_pk_mul_f32 v[22:23], v[58:59], v[22:23]
	v_pk_mul_f32 v[20:21], v[56:57], v[20:21]
	v_mfma_f32_32x32x16_bf16 v[0:15], v[100:103], v[108:111], v[0:15]
	s_waitcnt vmcnt(11)
	s_waitcnt lgkmcnt(4)
	v_mul_f32_e64 v18, v78, v18
	v_mul_f32_e64 v19, v79, v19
	v_mul_f32_e64 v16, v76, v16
	v_mul_f32_e64 v17, v77, v17
	v_mfma_f32_32x32x16_bf16 v[0:15], v[112:115], v[32:35], v[0:15]
	global_load_dwordx4 v[56:59], v[234:235], off offset:-4096
	global_load_dwordx4 v[84:87], v[168:169], off
	global_load_dwordx4 v[96:99], v[234:235], off offset:-3072
	s_waitcnt vmcnt(6)
	s_nop 3
	s_waitcnt lgkmcnt(3)
	v_pk_mul_f32 v[14:15], v[42:43], v[14:15]
	ds_read_b128 v[32:35], v171 offset:6240
	v_mfma_f32_32x32x16_bf16 v[16:31], v[104:107], v[80:83], v[16:31]
	v_mul_f32_e64 v12, v40, v12
	v_mul_f32_e64 v13, v41, v13
	s_waitcnt vmcnt(6)
	s_waitcnt lgkmcnt(3)
	v_mul_f32_e64 v10, v118, v10
	ds_read_b128 v[44:47], v171 offset:6208
	v_mul_f32_e64 v11, v119, v11
	v_pk_mul_f32 v[8:9], v[116:117], v[8:9]
	s_waitcnt lgkmcnt(3)
	v_pk_mul_f32 v[6:7], v[70:71], v[6:7]
	ds_read_b128 v[60:63], v171 offset:6176
	v_pk_mul_f32 v[4:5], v[68:69], v[4:5]
	s_waitcnt vmcnt(6)
	s_waitcnt lgkmcnt(3)
	v_pk_mul_f32 v[2:3], v[66:67], v[2:3]
	ds_read_b128 v[76:79], v171 offset:6144
	v_mfma_f32_32x32x16_bf16 v[16:31], v[120:123], v[88:91], v[16:31]
	global_load_dwordx4 v[100:103], v[168:169], off offset:1024
	global_load_dwordx4 v[104:107], v[234:235], off offset:-2048
	global_load_dwordx4 v[108:111], v[168:169], off offset:2048
	global_load_dwordx4 v[112:115], v[168:169], off offset:3072
	v_lshl_add_u64 v[168:169], v[168:169], 0, s[20:21]
	global_load_dwordx4 v[120:123], v[234:235], off offset:-1024
	v_pk_mul_f32 v[0:1], v[64:65], v[0:1]
	s_nop 1
	v_mfma_f32_32x32x16_bf16 v[0:15], v[136:139], v[80:83], v[0:15]
	v_mfma_f32_32x32x16_bf16 v[16:31], v[124:127], v[92:95], v[16:31]
	ds_read_b128 v[40:43], v171 offset:6336
	ds_read_b128 v[116:119], v171 offset:6368
	ds_read_b128 v[64:67], v171 offset:6304
	global_load_dwordx4 v[68:71], v[234:235], off
	s_waitcnt vmcnt(11)
	v_mfma_f32_32x32x16_bf16 v[0:15], v[36:39], v[88:91], v[0:15]
	global_load_dwordx4 v[88:91], v[234:235], off offset:1024
	ds_read_b128 v[80:83], v171 offset:6272
	s_waitcnt vmcnt(11)
	v_mfma_f32_32x32x16_bf16 v[0:15], v[52:55], v[92:95], v[0:15]
	global_load_dwordx4 v[52:55], v[234:235], off offset:2048
	global_load_dwordx4 v[92:95], v[234:235], off offset:3072
	v_mfma_f32_32x32x16_bf16 v[16:31], v[128:131], v[132:135], v[16:31]
	s_waitcnt vmcnt(12)
	v_mfma_f32_32x32x16_bf16 v[0:15], v[72:75], v[132:135], v[0:15]
	s_waitcnt vmcnt(12)
	s_nop 8
	s_waitcnt lgkmcnt(7)
	v_mul_f32_e64 v30, v34, v30
	v_mul_f32_e64 v31, v35, v31
	v_mul_f32_e64 v28, v32, v28
	v_mul_f32_e64 v29, v33, v29
	s_waitcnt vmcnt(12)
	s_waitcnt lgkmcnt(6)
	v_pk_mul_f32 v[26:27], v[46:47], v[26:27]
	v_pk_mul_f32 v[24:25], v[44:45], v[24:25]
	s_waitcnt vmcnt(11)
	s_waitcnt lgkmcnt(5)
	v_pk_mul_f32 v[22:23], v[62:63], v[22:23]
	v_pk_mul_f32 v[20:21], v[60:61], v[20:21]
	s_waitcnt vmcnt(11)
	s_waitcnt lgkmcnt(4)
	v_pk_mul_f32 v[18:19], v[78:79], v[18:19]
	v_pk_mul_f32 v[16:17], v[76:77], v[16:17]
	s_waitcnt vmcnt(4)
	s_waitcnt lgkmcnt(3)
	v_pk_mul_f32 v[42:43], v[42:43], v[10:11]
	v_mfma_f32_32x32x16_bf16 v[16:31], v[56:59], v[84:87], v[16:31]
	ds_read_b128 v[124:127], v171 offset:7200
	global_load_dwordx4 v[72:75], v[236:237], off offset:-4096
	s_waitcnt vmcnt(5)
	s_waitcnt lgkmcnt(3)
	v_pk_mul_f32 v[46:47], v[118:119], v[14:15]
	v_pk_mul_f32 v[44:45], v[116:117], v[12:13]
	v_pk_mul_f32 v[40:41], v[40:41], v[8:9]
	s_waitcnt vmcnt(5)
	s_waitcnt lgkmcnt(2)
	v_pk_mul_f32 v[38:39], v[66:67], v[6:7]
	v_pk_mul_f32 v[36:37], v[64:65], v[4:5]
	v_mfma_f32_32x32x16_bf16 v[16:31], v[96:99], v[100:103], v[16:31]
	global_load_dwordx4 v[96:99], v[168:169], off
	global_load_dwordx4 v[128:131], v[236:237], off offset:-3072
	s_waitcnt vmcnt(6)
	ds_read_b128 v[56:59], v171 offset:7264
	s_waitcnt lgkmcnt(2)
	v_mul_f32_e64 v34, v82, v2
	v_mul_f32_e64 v35, v83, v3
	v_pk_mul_f32 v[32:33], v[80:81], v[0:1]
	s_nop 1
	ds_read_b128 v[60:63], v171 offset:7232
	v_mfma_f32_32x32x16_bf16 v[32:47], v[68:71], v[84:87], v[32:47]
	v_mfma_f32_32x32x16_bf16 v[16:31], v[104:107], v[108:111], v[16:31]
	global_load_dwordx4 v[104:107], v[168:169], off offset:1024
	ds_read_b128 v[76:79], v171 offset:7168
	global_load_dwordx4 v[132:135], v[236:237], off offset:-2048
	global_load_dwordx4 v[136:139], v[236:237], off offset:-1024
	global_load_dwordx4 v[140:143], v[236:237], off
	global_load_dwordx4 v[144:147], v[168:169], off offset:3072
	global_load_dwordx4 v[148:151], v[168:169], off offset:2048
	v_lshl_add_u64 v[168:169], v[168:169], 0, s[20:21]
	ds_read_b128 v[64:67], v171 offset:7360
	ds_read_b128 v[116:119], v171 offset:7392
	global_load_dwordx4 v[84:87], v[236:237], off offset:1024
	s_waitcnt vmcnt(12)
	v_mfma_f32_32x32x16_bf16 v[32:47], v[88:91], v[100:103], v[32:47]
	s_waitcnt vmcnt(11)
	ds_read_b128 v[68:71], v171 offset:7328
	v_mfma_f32_32x32x16_bf16 v[32:47], v[52:55], v[108:111], v[32:47]
	global_load_dwordx4 v[52:55], v[236:237], off offset:2048
	v_mfma_f32_32x32x16_bf16 v[16:31], v[120:123], v[112:115], v[16:31]
	ds_read_b128 v[80:83], v171 offset:7296
	s_waitcnt vmcnt(11)
	v_mfma_f32_32x32x16_bf16 v[32:47], v[92:95], v[112:115], v[32:47]
	s_nop 9
	s_waitcnt lgkmcnt(7)
	v_mul_f32_e64 v6, v126, v22
	v_mul_f32_e64 v7, v127, v23
	v_mul_f32_e64 v4, v124, v20
	v_mul_f32_e64 v5, v125, v21
	v_add_co_u32_e32 v124, vcc, s14, v170
	s_mov_b32 s14, 0xa000
	s_nop 0
	v_addc_co_u32_e32 v125, vcc, 0, v171, vcc
	v_add_co_u32_e32 v126, vcc, s14, v170
	s_mov_b32 s14, 0xb000
	s_nop 0
	v_addc_co_u32_e32 v127, vcc, 0, v171, vcc
	s_waitcnt vmcnt(11)
	s_waitcnt lgkmcnt(6)
	v_pk_mul_f32 v[14:15], v[58:59], v[30:31]
	v_pk_mul_f32 v[12:13], v[56:57], v[28:29]
	s_waitcnt vmcnt(11)
	s_waitcnt lgkmcnt(5)
	v_pk_mul_f32 v[10:11], v[62:63], v[26:27]
	v_pk_mul_f32 v[8:9], v[60:61], v[24:25]
	s_waitcnt vmcnt(10)
	s_waitcnt lgkmcnt(4)
	v_pk_mul_f32 v[2:3], v[78:79], v[18:19]
	v_pk_mul_f32 v[0:1], v[76:77], v[16:17]
	s_waitcnt vmcnt(2)
	s_waitcnt lgkmcnt(3)
	v_pk_mul_f32 v[26:27], v[66:67], v[42:43]
	v_mfma_f32_32x32x16_bf16 v[0:15], v[72:75], v[96:99], v[0:15]
	global_load_dwordx4 v[60:63], v[236:237], off offset:3072
	ds_read_b128 v[72:75], v171 offset:8288
	s_waitcnt vmcnt(3)
	ds_read_b128 v[56:59], v171 offset:8192
	s_waitcnt lgkmcnt(4)
	v_pk_mul_f32 v[30:31], v[118:119], v[46:47]
	v_pk_mul_f32 v[28:29], v[116:117], v[44:45]
	v_pk_mul_f32 v[24:25], v[64:65], v[40:41]
	s_waitcnt vmcnt(3)
	s_waitcnt lgkmcnt(3)
	v_pk_mul_f32 v[22:23], v[70:71], v[38:39]
	v_pk_mul_f32 v[20:21], v[68:69], v[36:37]
	ds_read_b128 v[88:91], v171 offset:8256
	s_waitcnt vmcnt(3)
	s_waitcnt lgkmcnt(3)
	v_pk_mul_f32 v[18:19], v[82:83], v[34:35]
	ds_read_b128 v[76:79], v171 offset:8224
	v_pk_mul_f32 v[16:17], v[80:81], v[32:33]
	global_load_dwordx4 v[92:95], v[238:239], off offset:-4096
	global_load_dwordx4 v[100:103], v[168:169], off
	v_mfma_f32_32x32x16_bf16 v[16:31], v[140:143], v[96:99], v[16:31]
	global_load_dwordx4 v[108:111], v[238:239], off offset:-3072
	global_load_dwordx4 v[112:115], v[168:169], off offset:1024
	global_load_dwordx4 v[120:123], v[238:239], off offset:-2048
	global_load_dwordx4 v[32:35], v[168:169], off offset:2048
	global_load_dwordx4 v[36:39], v[238:239], off offset:-1024
	global_load_dwordx4 v[40:43], v[168:169], off offset:3072
	v_lshl_add_u64 v[168:169], v[168:169], 0, s[20:21]
	ds_read_b128 v[44:47], v171 offset:8416
	ds_read_b128 v[64:67], v171 offset:8384
	ds_read_b128 v[68:71], v171 offset:8352
	global_load_dwordx4 v[80:83], v[238:239], off
	s_waitcnt vmcnt(11)
	v_mfma_f32_32x32x16_bf16 v[16:31], v[84:87], v[104:107], v[16:31]
	v_mfma_f32_32x32x16_bf16 v[0:15], v[128:131], v[104:107], v[0:15]
	s_waitcnt vmcnt(10)
	v_mfma_f32_32x32x16_bf16 v[16:31], v[52:55], v[148:151], v[16:31]
	ds_read_b128 v[52:55], v171 offset:8320
	global_load_dwordx4 v[84:87], v[238:239], off offset:1024
	v_mfma_f32_32x32x16_bf16 v[0:15], v[132:135], v[148:151], v[0:15]
	v_mfma_f32_32x32x16_bf16 v[0:15], v[136:139], v[144:147], v[0:15]
	s_waitcnt vmcnt(10)
	v_mfma_f32_32x32x16_bf16 v[16:31], v[60:63], v[144:147], v[16:31]
	s_waitcnt vmcnt(10)
	s_nop 8
	s_waitcnt lgkmcnt(7)
	v_mul_f32_e64 v14, v74, v14
	v_mul_f32_e64 v15, v75, v15
	v_mul_f32_e64 v12, v72, v12
	v_mul_f32_e64 v13, v73, v13
	s_waitcnt lgkmcnt(6)
	v_pk_mul_f32 v[2:3], v[58:59], v[2:3]
	v_pk_mul_f32 v[0:1], v[56:57], v[0:1]
	global_load_dwordx4 v[56:59], v[238:239], off offset:2048
	global_load_dwordx4 v[60:63], v[238:239], off offset:3072
	global_load_dwordx4 v[72:75], v[240:241], off offset:-4096
	s_waitcnt vmcnt(13)
	s_waitcnt lgkmcnt(5)
	v_pk_mul_f32 v[10:11], v[90:91], v[10:11]
	v_pk_mul_f32 v[8:9], v[88:89], v[8:9]
	s_waitcnt lgkmcnt(4)
	v_pk_mul_f32 v[6:7], v[78:79], v[6:7]
	v_pk_mul_f32 v[4:5], v[76:77], v[4:5]
	s_waitcnt vmcnt(5)
	s_waitcnt lgkmcnt(3)
	v_pk_mul_f32 v[30:31], v[46:47], v[30:31]
	v_mfma_f32_32x32x16_bf16 v[0:15], v[92:95], v[100:103], v[0:15]
	v_mul_f32_e64 v28, v44, v28
	v_mul_f32_e64 v29, v45, v29
	s_waitcnt vmcnt(5)
	s_waitcnt lgkmcnt(2)
	v_mul_f32_e64 v26, v66, v26
	v_mul_f32_e64 v27, v67, v27
	v_pk_mul_f32 v[24:25], v[64:65], v[24:25]
	s_waitcnt vmcnt(5)
	s_waitcnt lgkmcnt(1)
	v_pk_mul_f32 v[22:23], v[70:71], v[22:23]
	v_pk_mul_f32 v[20:21], v[68:69], v[20:21]
	ds_read_b128 v[76:79], v171 offset:9312
	ds_read_b128 v[88:91], v171 offset:9248
	ds_read_b128 v[92:95], v171 offset:9280
	ds_read_b128 v[96:99], v171 offset:9216
	v_mfma_f32_32x32x16_bf16 v[0:15], v[108:111], v[112:115], v[0:15]
	s_waitcnt vmcnt(4)
	s_waitcnt lgkmcnt(4)
	v_mul_f32_e64 v18, v54, v18
	v_mul_f32_e64 v19, v55, v19
	v_mul_f32_e64 v16, v52, v16
	v_mul_f32_e64 v17, v53, v17
	v_mfma_f32_32x32x16_bf16 v[0:15], v[120:123], v[32:35], v[0:15]
	global_load_dwordx4 v[104:107], v[168:169], off
	global_load_dwordx4 v[108:111], v[240:241], off offset:-3072
	global_load_dwordx4 v[116:119], v[168:169], off offset:1024
	global_load_dwordx4 v[120:123], v[240:241], off offset:-2048
	v_mfma_f32_32x32x16_bf16 v[16:31], v[80:83], v[100:103], v[16:31]
	s_waitcnt vmcnt(7)
	v_mfma_f32_32x32x16_bf16 v[16:31], v[84:87], v[112:115], v[16:31]
	v_mfma_f32_32x32x16_bf16 v[0:15], v[36:39], v[40:43], v[0:15]
	global_load_dwordx4 v[36:39], v[168:169], off offset:2048
	global_load_dwordx4 v[44:47], v[240:241], off offset:-1024
	global_load_dwordx4 v[52:55], v[168:169], off offset:3072
	v_lshl_add_u64 v[168:169], v[168:169], 0, s[20:21]
	ds_read_b128 v[64:67], v171 offset:9440
	ds_read_b128 v[68:71], v171 offset:9408
	ds_read_b128 v[80:83], v171 offset:9376
	global_load_dwordx4 v[84:87], v[240:241], off
	s_waitcnt vmcnt(8)
	s_nop 3
	s_waitcnt lgkmcnt(6)
	v_pk_mul_f32 v[14:15], v[78:79], v[14:15]
	v_mfma_f32_32x32x16_bf16 v[16:31], v[56:59], v[32:35], v[16:31]
	ds_read_b128 v[32:35], v171 offset:9344
	global_load_dwordx4 v[56:59], v[240:241], off offset:1024
	v_mul_f32_e64 v12, v76, v12
	v_mul_f32_e64 v13, v77, v13
	s_waitcnt vmcnt(9)
	s_waitcnt lgkmcnt(5)
	v_pk_mul_f32 v[10:11], v[94:95], v[10:11]
	v_pk_mul_f32 v[8:9], v[92:93], v[8:9]
	v_pk_mul_f32 v[6:7], v[90:91], v[6:7]
	v_pk_mul_f32 v[4:5], v[88:89], v[4:5]
	s_waitcnt vmcnt(9)
	s_waitcnt lgkmcnt(4)
	v_pk_mul_f32 v[2:3], v[98:99], v[2:3]
	v_mfma_f32_32x32x16_bf16 v[16:31], v[60:63], v[40:43], v[16:31]
	global_load_dwordx4 v[40:43], v[240:241], off offset:2048
	global_load_dwordx4 v[60:63], v[240:241], off offset:3072
	v_mul_f32_e64 v0, v96, v0
	v_mul_f32_e64 v1, v97, v1
	s_waitcnt vmcnt(10)
	s_nop 0
	v_mfma_f32_32x32x16_bf16 v[0:15], v[72:75], v[104:107], v[0:15]
	global_load_dwordx4 v[88:91], v[244:245], off offset:-4096
	s_waitcnt vmcnt(5)
	ds_read_b128 v[72:75], v171 offset:10336
	s_waitcnt lgkmcnt(4)
	v_pk_mul_f32 v[30:31], v[66:67], v[30:31]
	v_pk_mul_f32 v[28:29], v[64:65], v[28:29]
	s_waitcnt vmcnt(5)
	s_waitcnt lgkmcnt(3)
	v_pk_mul_f32 v[26:27], v[70:71], v[26:27]
	v_pk_mul_f32 v[24:25], v[68:69], v[24:25]
	s_waitcnt vmcnt(5)
	s_waitcnt lgkmcnt(2)
	v_pk_mul_f32 v[22:23], v[82:83], v[22:23]
	v_pk_mul_f32 v[20:21], v[80:81], v[20:21]
	ds_read_b128 v[76:79], v171 offset:10304
	v_mfma_f32_32x32x16_bf16 v[0:15], v[108:111], v[116:119], v[0:15]
	global_load_dwordx4 v[100:103], v[168:169], off
	global_load_dwordx4 v[108:111], v[168:169], off offset:1024
	ds_read_b128 v[92:95], v171 offset:10272
	global_load_dwordx4 v[112:115], v[244:245], off offset:-3072
	s_waitcnt vmcnt(7)
	s_waitcnt lgkmcnt(3)
	v_mul_f32_e64 v18, v34, v18
	ds_read_b128 v[96:99], v171 offset:10240
	v_mul_f32_e64 v19, v35, v19
	v_pk_mul_f32 v[16:17], v[32:33], v[16:17]
	v_mfma_f32_32x32x16_bf16 v[0:15], v[120:123], v[36:39], v[0:15]
	v_add_co_u32_e32 v120, vcc, s14, v170
	s_mov_b32 s14, 0xc000
	s_nop 0
	v_addc_co_u32_e32 v121, vcc, 0, v171, vcc
	v_add_co_u32_e32 v124, vcc, s14, v170
	v_mfma_f32_32x32x16_bf16 v[16:31], v[84:87], v[104:107], v[16:31]
	s_nop 0
	v_addc_co_u32_e32 v125, vcc, 0, v171, vcc
	s_mov_b32 s14, 0xd000
	s_waitcnt vmcnt(6)
	v_mfma_f32_32x32x16_bf16 v[16:31], v[56:59], v[116:119], v[16:31]
	v_mfma_f32_32x32x16_bf16 v[0:15], v[44:47], v[52:55], v[0:15]
	global_load_dwordx4 v[32:35], v[244:245], off offset:-2048
	global_load_dwordx4 v[64:67], v[168:169], off offset:2048
	global_load_dwordx4 v[56:59], v[244:245], off offset:-1024
	global_load_dwordx4 v[68:71], v[168:169], off offset:3072
	v_lshl_add_u64 v[168:169], v[168:169], 0, s[20:21]
	ds_read_b128 v[80:83], v171 offset:10464
	ds_read_b128 v[84:87], v171 offset:10432
	global_load_dwordx4 v[104:107], v[244:245], off
	s_waitcnt vmcnt(9)
	s_nop 2
	s_waitcnt lgkmcnt(5)
	v_pk_mul_f32 v[14:15], v[74:75], v[14:15]
	v_mfma_f32_32x32x16_bf16 v[16:31], v[40:43], v[36:39], v[16:31]
	ds_read_b128 v[36:39], v171 offset:10400
	ds_read_b128 v[40:43], v171 offset:10368
	global_load_dwordx4 v[116:119], v[244:245], off offset:1024
	v_mul_f32_e64 v12, v72, v12
	v_mul_f32_e64 v13, v73, v13
	s_waitcnt vmcnt(10)
	s_waitcnt lgkmcnt(6)
	v_pk_mul_f32 v[10:11], v[78:79], v[10:11]
	v_pk_mul_f32 v[8:9], v[76:77], v[8:9]
	s_waitcnt vmcnt(9)
	s_waitcnt lgkmcnt(5)
	v_pk_mul_f32 v[6:7], v[94:95], v[6:7]
	v_pk_mul_f32 v[4:5], v[92:93], v[4:5]
	s_waitcnt vmcnt(9)
	s_waitcnt lgkmcnt(4)
	v_pk_mul_f32 v[2:3], v[98:99], v[2:3]
	v_mfma_f32_32x32x16_bf16 v[16:31], v[60:63], v[52:55], v[16:31]
	global_load_dwordx4 v[52:55], v[244:245], off offset:2048
	global_load_dwordx4 v[60:63], v[244:245], off offset:3072
	v_mul_f32_e64 v0, v96, v0
	v_mul_f32_e64 v1, v97, v1
	ds_read_b128 v[44:47], v171 offset:11296
	s_waitcnt vmcnt(10)
	s_nop 0
	v_mfma_f32_32x32x16_bf16 v[0:15], v[88:91], v[100:103], v[0:15]
	global_load_dwordx4 v[88:91], v[246:247], off offset:-4096
	s_waitcnt vmcnt(5)
	s_waitcnt lgkmcnt(4)
	v_pk_mul_f32 v[30:31], v[82:83], v[30:31]
	ds_read_b128 v[72:75], v171 offset:11360
	v_mfma_f32_32x32x16_bf16 v[0:15], v[112:115], v[108:111], v[0:15]
	v_mul_f32_e64 v28, v80, v28
	v_mul_f32_e64 v29, v81, v29
	ds_read_b128 v[76:79], v171 offset:11328
	s_waitcnt vmcnt(5)
	s_waitcnt lgkmcnt(5)
	v_mul_f32_e64 v26, v86, v26
	v_mul_f32_e64 v27, v87, v27
	v_pk_mul_f32 v[24:25], v[84:85], v[24:25]
	s_waitcnt vmcnt(4)
	s_waitcnt lgkmcnt(4)
	v_pk_mul_f32 v[22:23], v[38:39], v[22:23]
	ds_read_b128 v[92:95], v171 offset:11264
	v_pk_mul_f32 v[20:21], v[36:37], v[20:21]
	s_waitcnt vmcnt(4)
	s_waitcnt lgkmcnt(4)
	v_pk_mul_f32 v[18:19], v[42:43], v[18:19]
	v_pk_mul_f32 v[16:17], v[40:41], v[16:17]
	v_mfma_f32_32x32x16_bf16 v[0:15], v[32:35], v[64:67], v[0:15]
	global_load_dwordx4 v[32:35], v[168:169], off
	global_load_dwordx4 v[96:99], v[246:247], off offset:-3072
	global_load_dwordx4 v[112:115], v[168:169], off offset:1024
	global_load_dwordx4 v[36:39], v[246:247], off offset:-2048
	global_load_dwordx4 v[40:43], v[168:169], off offset:2048
	v_mfma_f32_32x32x16_bf16 v[16:31], v[104:107], v[100:103], v[16:31]
	s_waitcnt vmcnt(8)
	v_mfma_f32_32x32x16_bf16 v[16:31], v[116:119], v[108:111], v[16:31]
	v_mfma_f32_32x32x16_bf16 v[0:15], v[56:59], v[68:71], v[0:15]
	global_load_dwordx4 v[56:59], v[246:247], off offset:-1024
	ds_read_b128 v[80:83], v171 offset:11488
	global_load_dwordx4 v[84:87], v[168:169], off offset:3072
	v_lshl_add_u64 v[168:169], v[168:169], 0, s[20:21]
	ds_read_b128 v[100:103], v171 offset:11456
	global_load_dwordx4 v[104:107], v[246:247], off
	ds_read_b128 v[108:111], v171 offset:11424
	s_nop 5
	s_waitcnt lgkmcnt(6)
	v_pk_mul_f32 v[6:7], v[46:47], v[6:7]
	s_waitcnt vmcnt(10)
	v_mfma_f32_32x32x16_bf16 v[16:31], v[52:55], v[64:67], v[16:31]
	ds_read_b128 v[52:55], v171 offset:11392
	global_load_dwordx4 v[64:67], v[246:247], off offset:1024
	v_mul_f32_e64 v4, v44, v4
	v_mul_f32_e64 v5, v45, v5
	s_waitcnt vmcnt(10)
	s_waitcnt lgkmcnt(6)
	v_pk_mul_f32 v[14:15], v[74:75], v[14:15]
	v_pk_mul_f32 v[12:13], v[72:73], v[12:13]
	s_waitcnt vmcnt(10)
	s_waitcnt lgkmcnt(5)
	v_pk_mul_f32 v[10:11], v[78:79], v[10:11]
	v_pk_mul_f32 v[8:9], v[76:77], v[8:9]
	v_mfma_f32_32x32x16_bf16 v[16:31], v[60:63], v[68:71], v[16:31]
	global_load_dwordx4 v[60:63], v[246:247], off offset:2048
	global_load_dwordx4 v[68:71], v[246:247], off offset:3072
	s_waitcnt vmcnt(11)
	s_waitcnt lgkmcnt(4)
	v_mul_f32_e64 v2, v94, v2
	v_mul_f32_e64 v3, v95, v3
	v_pk_mul_f32 v[0:1], v[92:93], v[0:1]
	s_waitcnt vmcnt(10)
	ds_read_b128 v[44:47], v171 offset:12288
	s_nop 0
	v_mfma_f32_32x32x16_bf16 v[0:15], v[88:91], v[32:35], v[0:15]
	global_load_dwordx4 v[92:95], v[248:249], off offset:-4096
	s_waitcnt vmcnt(6)
	s_waitcnt lgkmcnt(4)
	v_pk_mul_f32 v[30:31], v[82:83], v[30:31]
	v_mfma_f32_32x32x16_bf16 v[0:15], v[96:99], v[112:115], v[0:15]
	v_mul_f32_e64 v28, v80, v28
	v_mul_f32_e64 v29, v81, v29
	s_waitcnt vmcnt(5)
	s_waitcnt lgkmcnt(3)
	v_mul_f32_e64 v26, v102, v26
	v_mul_f32_e64 v27, v103, v27
	v_pk_mul_f32 v[24:25], v[100:101], v[24:25]
	s_waitcnt vmcnt(4)
	s_waitcnt lgkmcnt(2)
	v_pk_mul_f32 v[22:23], v[110:111], v[22:23]
	ds_read_b128 v[72:75], v171 offset:12384
	v_pk_mul_f32 v[20:21], v[108:109], v[20:21]
	s_waitcnt vmcnt(4)
	s_waitcnt lgkmcnt(2)
	v_pk_mul_f32 v[18:19], v[54:55], v[18:19]
	v_pk_mul_f32 v[16:17], v[52:53], v[16:17]
	ds_read_b128 v[76:79], v171 offset:12352
	v_mfma_f32_32x32x16_bf16 v[0:15], v[36:39], v[40:43], v[0:15]
	global_load_dwordx4 v[36:39], v[168:169], off
	global_load_dwordx4 v[96:99], v[168:169], off offset:1024
	ds_read_b128 v[88:91], v171 offset:12320
	global_load_dwordx4 v[116:119], v[248:249], off offset:-3072
	global_load_dwordx4 v[120:123], v[248:249], off offset:-2048
	v_mfma_f32_32x32x16_bf16 v[16:31], v[104:107], v[32:35], v[16:31]
	global_load_dwordx4 v[32:35], v[168:169], off offset:2048
	s_waitcnt vmcnt(8)
	v_mfma_f32_32x32x16_bf16 v[16:31], v[64:67], v[112:115], v[16:31]
	v_mfma_f32_32x32x16_bf16 v[0:15], v[56:59], v[84:87], v[0:15]
	global_load_dwordx4 v[52:55], v[248:249], off offset:-1024
	global_load_dwordx4 v[64:67], v[168:169], off offset:3072
	v_lshl_add_u64 v[168:169], v[168:169], 0, s[20:21]
	global_load_dwordx4 v[104:107], v[248:249], off
	s_waitcnt vmcnt(11)
	s_nop 4
	s_waitcnt lgkmcnt(3)
	v_pk_mul_f32 v[2:3], v[46:47], v[2:3]
	s_waitcnt vmcnt(10)
	v_mfma_f32_32x32x16_bf16 v[16:31], v[60:63], v[40:43], v[16:31]
	ds_read_b128 v[56:59], v171 offset:12512
	global_load_dwordx4 v[60:63], v[248:249], off offset:1024
	global_load_dwordx4 v[108:111], v[248:249], off offset:2048
	v_mul_f32_e64 v0, v44, v0
	ds_read_b128 v[80:83], v171 offset:12480
	v_mul_f32_e64 v1, v45, v1
	v_add_co_u32_e32 v124, vcc, s14, v170
	s_mov_b32 s14, 0xe000
	ds_read_b128 v[100:103], v171 offset:12448
	s_nop 0
	v_addc_co_u32_e32 v125, vcc, 0, v171, vcc
	s_waitcnt vmcnt(11)
	v_mfma_f32_32x32x16_bf16 v[16:31], v[68:71], v[84:87], v[16:31]
	ds_read_b128 v[40:43], v171 offset:12416
	global_load_dwordx4 v[44:47], v[248:249], off offset:3072
	global_load_dwordx4 v[68:71], v[250:251], off offset:-4096
	s_waitcnt vmcnt(13)
	s_waitcnt lgkmcnt(6)
	v_mul_f32_e64 v14, v74, v14
	v_mul_f32_e64 v15, v75, v15
	v_pk_mul_f32 v[12:13], v[72:73], v[12:13]
	s_waitcnt vmcnt(13)
	s_waitcnt lgkmcnt(5)
	v_pk_mul_f32 v[10:11], v[78:79], v[10:11]
	v_pk_mul_f32 v[8:9], v[76:77], v[8:9]
	s_waitcnt vmcnt(13)
	s_waitcnt lgkmcnt(4)
	v_pk_mul_f32 v[6:7], v[90:91], v[6:7]
	v_pk_mul_f32 v[4:5], v[88:89], v[4:5]
	v_add_co_u32_e32 v126, vcc, s14, v170
	s_waitcnt vmcnt(11)
	v_mfma_f32_32x32x16_bf16 v[0:15], v[92:95], v[36:39], v[0:15]
	v_addc_co_u32_e32 v127, vcc, 0, v171, vcc
	ds_read_b128 v[72:75], v171 offset:13408
	s_or_b32 s14, s1, s0
	s_ashr_i32 s15, s14, 31
	s_waitcnt vmcnt(9)
	ds_read_b128 v[84:87], v171 offset:13376
	v_mfma_f32_32x32x16_bf16 v[0:15], v[116:119], v[96:99], v[0:15]
	global_load_dwordx4 v[92:95], v[168:169], off
	ds_read_b128 v[76:79], v171 offset:13344
	global_load_dwordx4 v[112:115], v[250:251], off offset:-3072
	global_load_dwordx4 v[116:119], v[168:169], off offset:1024
	s_lshl_b64 s[14:15], s[14:15], 15
	ds_read_b128 v[88:91], v171 offset:13312
	s_cmp_lg_u32 s0, 0
	s_waitcnt vmcnt(9)
	s_waitcnt lgkmcnt(7)
	v_pk_mul_f32 v[30:31], v[58:59], v[30:31]
	v_pk_mul_f32 v[28:29], v[56:57], v[28:29]
	s_waitcnt vmcnt(8)
	s_waitcnt lgkmcnt(6)
	v_pk_mul_f32 v[26:27], v[82:83], v[26:27]
	v_pk_mul_f32 v[24:25], v[80:81], v[24:25]
	s_waitcnt vmcnt(8)
	s_waitcnt lgkmcnt(5)
	v_pk_mul_f32 v[22:23], v[102:103], v[22:23]
	v_pk_mul_f32 v[20:21], v[100:101], v[20:21]
	v_mfma_f32_32x32x16_bf16 v[0:15], v[120:123], v[32:35], v[0:15]
	s_waitcnt vmcnt(7)
	s_waitcnt lgkmcnt(4)
	v_mul_f32_e64 v18, v42, v18
	v_mul_f32_e64 v19, v43, v19
	v_mul_f32_e64 v16, v40, v16
	v_mul_f32_e64 v17, v41, v17
	v_mfma_f32_32x32x16_bf16 v[0:15], v[52:55], v[64:67], v[0:15]
	s_nop 0
	v_mfma_f32_32x32x16_bf16 v[16:31], v[104:107], v[36:39], v[16:31]
	global_load_dwordx4 v[36:39], v[250:251], off offset:-2048
	global_load_dwordx4 v[40:43], v[168:169], off offset:2048
	global_load_dwordx4 v[52:55], v[250:251], off offset:-1024
	s_waitcnt vmcnt(6)
	s_nop 5
	s_waitcnt lgkmcnt(3)
	v_mul_f32_e64 v14, v74, v14
	v_mul_f32_e64 v15, v75, v15
	v_mfma_f32_32x32x16_bf16 v[16:31], v[60:63], v[96:99], v[16:31]
	ds_read_b128 v[56:59], v171 offset:13536
	global_load_dwordx4 v[60:63], v[168:169], off offset:3072
	v_lshl_add_u64 v[168:169], v[168:169], 0, s[20:21]
	ds_read_b128 v[80:83], v171 offset:13504
	ds_read_b128 v[96:99], v171 offset:13472
	global_load_dwordx4 v[100:103], v[250:251], off
	v_pk_mul_f32 v[12:13], v[72:73], v[12:13]
	s_waitcnt vmcnt(8)
	s_waitcnt lgkmcnt(5)
	v_pk_mul_f32 v[10:11], v[86:87], v[10:11]
	v_pk_mul_f32 v[8:9], v[84:85], v[8:9]
	s_waitcnt lgkmcnt(4)
	v_pk_mul_f32 v[6:7], v[78:79], v[6:7]
	v_pk_mul_f32 v[4:5], v[76:77], v[4:5]
	s_waitcnt vmcnt(8)
	s_waitcnt lgkmcnt(3)
	v_pk_mul_f32 v[2:3], v[90:91], v[2:3]
	v_mfma_f32_32x32x16_bf16 v[16:31], v[108:111], v[32:35], v[16:31]
	ds_read_b128 v[32:35], v171 offset:13440
	global_load_dwordx4 v[104:107], v[250:251], off offset:1024
	v_mul_f32_e64 v0, v88, v0
	v_mul_f32_e64 v1, v89, v1
	v_mfma_f32_32x32x16_bf16 v[16:31], v[44:47], v[64:67], v[16:31]
	global_load_dwordx4 v[44:47], v[250:251], off offset:2048
	global_load_dwordx4 v[64:67], v[250:251], off offset:3072
	s_waitcnt vmcnt(10)
	v_mfma_f32_32x32x16_bf16 v[0:15], v[68:71], v[92:95], v[0:15]
	ds_read_b128 v[68:71], v171 offset:14432
	global_load_dwordx4 v[76:79], v[252:253], off offset:-4096
	s_waitcnt vmcnt(6)
	ds_read_b128 v[72:75], v171 offset:14400
	s_nop 1
	s_waitcnt lgkmcnt(5)
	v_pk_mul_f32 v[30:31], v[58:59], v[30:31]
	v_mfma_f32_32x32x16_bf16 v[0:15], v[112:115], v[116:119], v[0:15]
	v_mul_f32_e64 v28, v56, v28
	ds_read_b128 v[84:87], v171 offset:14368
	v_mul_f32_e64 v29, v57, v29
	s_waitcnt vmcnt(5)
	s_waitcnt lgkmcnt(5)
	v_mul_f32_e64 v26, v82, v26
	ds_read_b128 v[88:91], v171 offset:14336
	v_mul_f32_e64 v27, v83, v27
	v_pk_mul_f32 v[24:25], v[80:81], v[24:25]
	s_waitcnt vmcnt(5)
	s_waitcnt lgkmcnt(5)
	v_pk_mul_f32 v[22:23], v[98:99], v[22:23]
	v_pk_mul_f32 v[20:21], v[96:97], v[20:21]
	s_waitcnt vmcnt(4)
	s_waitcnt lgkmcnt(4)
	v_pk_mul_f32 v[18:19], v[34:35], v[18:19]
	v_pk_mul_f32 v[16:17], v[32:33], v[16:17]
	v_mfma_f32_32x32x16_bf16 v[0:15], v[36:39], v[40:43], v[0:15]
	global_load_dwordx4 v[36:39], v[168:169], off
	global_load_dwordx4 v[108:111], v[252:253], off offset:-3072
	global_load_dwordx4 v[112:115], v[168:169], off offset:1024
	global_load_dwordx4 v[32:35], v[168:169], off offset:2048
	v_mfma_f32_32x32x16_bf16 v[16:31], v[100:103], v[92:95], v[16:31]
	s_waitcnt vmcnt(7)
	v_mfma_f32_32x32x16_bf16 v[16:31], v[104:107], v[116:119], v[16:31]
	v_mfma_f32_32x32x16_bf16 v[0:15], v[52:55], v[60:63], v[0:15]
	global_load_dwordx4 v[52:55], v[252:253], off offset:-2048
	global_load_dwordx4 v[56:59], v[252:253], off offset:-1024
	ds_read_b128 v[80:83], v171 offset:14560
	global_load_dwordx4 v[92:95], v[168:169], off offset:3072
	ds_read_b128 v[96:99], v171 offset:14528
	ds_read_b128 v[100:103], v171 offset:14496
	global_load_dwordx4 v[104:107], v[252:253], off
	s_waitcnt vmcnt(9)
	s_nop 3
	s_waitcnt lgkmcnt(6)
	v_pk_mul_f32 v[14:15], v[14:15], v[70:71]
	v_mfma_f32_32x32x16_bf16 v[16:31], v[44:47], v[40:43], v[16:31]
	ds_read_b128 v[40:43], v171 offset:14464
	v_mul_f32_e64 v12, v12, v68
	v_mul_f32_e64 v13, v13, v69
	s_waitcnt vmcnt(9)
	s_waitcnt lgkmcnt(6)
	v_mul_f32_e64 v10, v10, v74
	v_mul_f32_e64 v11, v11, v75
	v_pk_mul_f32 v[8:9], v[8:9], v[72:73]
	s_waitcnt vmcnt(8)
	s_waitcnt lgkmcnt(5)
	v_pk_mul_f32 v[6:7], v[6:7], v[86:87]
	v_pk_mul_f32 v[4:5], v[4:5], v[84:85]
	s_waitcnt vmcnt(8)
	s_waitcnt lgkmcnt(4)
	v_pk_mul_f32 v[2:3], v[2:3], v[90:91]
	ds_read_b128 v[120:123], v171 offset:15360
	v_mfma_f32_32x32x16_bf16 v[16:31], v[64:67], v[60:63], v[16:31]
	global_load_dwordx4 v[44:47], v[252:253], off offset:1024
	v_mul_f32_e64 v0, v0, v88
	v_mul_f32_e64 v1, v1, v89
	ds_read_b128 v[60:63], v171 offset:15392
	global_load_dwordx4 v[64:67], v[252:253], off offset:2048
	global_load_dwordx4 v[72:75], v[252:253], off offset:3072
	s_waitcnt vmcnt(5)
	ds_read_b128 v[68:71], v171 offset:15424
	s_nop 3
	s_waitcnt lgkmcnt(6)
	v_pk_mul_f32 v[30:31], v[30:31], v[82:83]
	v_mfma_f32_32x32x16_bf16 v[0:15], v[76:79], v[36:39], v[0:15]
	v_mul_f32_e64 v28, v28, v80
	ds_read_b128 v[48:51], v171 offset:15584
	v_mul_f32_e64 v29, v29, v81
	s_waitcnt vmcnt(4)
	s_waitcnt lgkmcnt(6)
	v_mul_f32_e64 v26, v26, v98
	v_mul_f32_e64 v27, v27, v99
	v_pk_mul_f32 v[24:25], v[24:25], v[96:97]
	s_waitcnt vmcnt(4)
	s_waitcnt lgkmcnt(5)
	v_pk_mul_f32 v[22:23], v[22:23], v[102:103]
	v_pk_mul_f32 v[20:21], v[20:21], v[100:101]
	s_waitcnt vmcnt(3)
	s_waitcnt lgkmcnt(4)
	v_pk_mul_f32 v[18:19], v[18:19], v[42:43]
	v_mfma_f32_32x32x16_bf16 v[0:15], v[108:111], v[112:115], v[0:15]
	v_mul_f32_e64 v16, v16, v40
	v_mul_f32_e64 v17, v17, v41
	v_mfma_f32_32x32x16_bf16 v[0:15], v[52:55], v[32:35], v[0:15]
	ds_read_b128 v[52:55], v171 offset:15456
	v_mfma_f32_32x32x16_bf16 v[16:31], v[104:107], v[36:39], v[16:31]
	s_waitcnt vmcnt(2)
	v_mfma_f32_32x32x16_bf16 v[16:31], v[44:47], v[112:115], v[16:31]
	s_waitcnt vmcnt(1)
	v_mfma_f32_32x32x16_bf16 v[16:31], v[64:67], v[32:35], v[16:31]
	v_mfma_f32_32x32x16_bf16 v[0:15], v[56:59], v[92:95], v[0:15]
	s_waitcnt vmcnt(0)
	v_mfma_f32_32x32x16_bf16 v[16:31], v[72:75], v[92:95], v[16:31]
	s_nop 9
	ds_read_b128 v[76:79], v171 offset:15488
	s_waitcnt lgkmcnt(5)
	v_mul_f32_e32 v40, v120, v0
	v_mul_f32_e32 v41, v121, v1
	v_lshl_add_u64 v[0:1], v[156:157], 0, s[14:15]
	v_mul_f32_e32 v2, v122, v2
	v_mul_f32_e32 v3, v123, v3
	s_waitcnt lgkmcnt(4)
	v_mul_f32_e32 v4, v60, v4
	ds_read_b128 v[84:87], v171 offset:15520
	v_mul_f32_e32 v5, v61, v5
	v_mul_f32_e32 v6, v62, v6
	v_mul_f32_e32 v7, v63, v7
	s_waitcnt lgkmcnt(4)
	v_mul_f32_e32 v8, v68, v8
	v_mul_f32_e32 v9, v69, v9
	ds_read_b128 v[36:39], v171 offset:15552
	v_mul_f32_e32 v10, v70, v10
	v_mul_f32_e32 v11, v71, v11
	s_waitcnt lgkmcnt(4)
	v_mul_f32_e32 v31, v51, v31
	v_mul_f32_e32 v28, v48, v28
	v_mul_f32_e32 v29, v49, v29
	v_mul_f32_e32 v30, v50, v30
	s_waitcnt vmcnt(0)
	s_waitcnt lgkmcnt(3)
	v_mul_f32_e32 v12, v52, v12
	v_mul_f32_e32 v13, v53, v13
	v_mul_f32_e32 v14, v54, v14
	v_mul_f32_e32 v15, v55, v15
	global_store_dword v[0:1], v40, off
	global_store_dword v[0:1], v41, off offset:256
	global_store_dword v[0:1], v2, off offset:512
	global_store_dword v[0:1], v3, off offset:768
	global_store_dword v[0:1], v4, off offset:1024
	global_store_dword v[0:1], v5, off offset:1280
	global_store_dword v[0:1], v6, off offset:1536
	global_store_dword v[0:1], v7, off offset:1792
	global_store_dword v[0:1], v8, off offset:2048
	global_store_dword v[0:1], v9, off offset:2304
	global_store_dword v[0:1], v10, off offset:2560
	global_store_dword v[0:1], v11, off offset:2816
	global_store_dword v[0:1], v12, off offset:3072
	global_store_dword v[0:1], v13, off offset:3328
	global_store_dword v[0:1], v14, off offset:3584
	global_store_dword v[0:1], v15, off offset:3840
	v_add_co_u32_e32 v0, vcc, s29, v0
	s_waitcnt vmcnt(16)
	s_waitcnt lgkmcnt(2)
	v_mul_f32_e32 v16, v76, v16
	v_addc_co_u32_e32 v1, vcc, 0, v1, vcc
	v_mul_f32_e32 v17, v77, v17
	v_mul_f32_e32 v18, v78, v18
	v_mul_f32_e32 v19, v79, v19
	s_waitcnt vmcnt(16)
	s_waitcnt lgkmcnt(1)
	v_mul_f32_e32 v20, v84, v20
	v_mul_f32_e32 v21, v85, v21
	v_mul_f32_e32 v22, v86, v22
	v_mul_f32_e32 v23, v87, v23
	s_waitcnt vmcnt(16)
	s_waitcnt lgkmcnt(0)
	v_mul_f32_e32 v24, v36, v24
	v_mul_f32_e32 v25, v37, v25
	v_mul_f32_e32 v26, v38, v26
	v_mul_f32_e32 v27, v39, v27
	global_store_dword v[0:1], v16, off
	global_store_dword v[0:1], v17, off offset:256
	global_store_dword v[0:1], v18, off offset:512
	global_store_dword v[0:1], v19, off offset:768
	global_store_dword v[0:1], v20, off offset:1024
	global_store_dword v[0:1], v21, off offset:1280
	global_store_dword v[0:1], v22, off offset:1536
	global_store_dword v[0:1], v23, off offset:1792
	global_store_dword v[0:1], v24, off offset:2048
	global_store_dword v[0:1], v25, off offset:2304
	global_store_dword v[0:1], v26, off offset:2560
	global_store_dword v[0:1], v27, off offset:2816
	global_store_dword v[0:1], v28, off offset:3072
	global_store_dword v[0:1], v29, off offset:3328
	global_store_dword v[0:1], v30, off offset:3584
	global_store_dword v[0:1], v31, off offset:3840
	s_cbranch_scc1 .LBB0_209
	s_lshr_b32 s0, s6, 4
	s_and_b32 s0, s0, 3
	s_lshl_b32 s0, s0, 10
	s_add_u32 s0, s8, s0
	s_addc_u32 s1, s9, 0
	v_lshl_add_u64 v[0:1], v[158:159], 0, s[0:1]
	v_add_co_u32_e32 v4, vcc, 0x3d80000, v0
	s_nop 1
	v_addc_co_u32_e32 v5, vcc, 0, v1, vcc
	global_load_dword v40, v[4:5], off
	v_lshl_add_u64 v[4:5], v[4:5], 0, s[86:87]
	global_load_dword v41, v[4:5], off
	v_lshl_add_u64 v[4:5], v[4:5], 0, s[86:87]
	global_load_dword v42, v[4:5], off
	v_lshl_add_u64 v[4:5], v[4:5], 0, s[86:87]
	global_load_dword v43, v[4:5], off
	v_lshl_add_u64 v[4:5], v[4:5], 0, s[86:87]
	global_load_dword v44, v[4:5], off
	v_lshl_add_u64 v[4:5], v[4:5], 0, s[86:87]
	global_load_dword v45, v[4:5], off
	v_lshl_add_u64 v[4:5], v[4:5], 0, s[86:87]
	global_load_dword v46, v[4:5], off
	v_lshl_add_u64 v[4:5], v[4:5], 0, s[86:87]
	global_load_dword v47, v[4:5], off
	v_lshl_add_u64 v[4:5], v[4:5], 0, s[86:87]
	global_load_dword v48, v[4:5], off
	v_lshl_add_u64 v[4:5], v[4:5], 0, s[86:87]
	global_load_dword v49, v[4:5], off
	v_lshl_add_u64 v[4:5], v[4:5], 0, s[86:87]
	global_load_dword v50, v[4:5], off
	v_lshl_add_u64 v[4:5], v[4:5], 0, s[86:87]
	global_load_dword v51, v[4:5], off
	v_lshl_add_u64 v[4:5], v[4:5], 0, s[86:87]
	global_load_dword v52, v[4:5], off
	v_lshl_add_u64 v[4:5], v[4:5], 0, s[86:87]
	global_load_dword v53, v[4:5], off
	v_lshl_add_u64 v[4:5], v[4:5], 0, s[86:87]
	global_load_dword v54, v[4:5], off
	v_lshl_add_u64 v[4:5], v[4:5], 0, s[86:87]
	global_load_dword v55, v[4:5], off
	s_waitcnt vmcnt(15)
	v_mul_f32_e32 v2, 1.0, v40
	s_waitcnt vmcnt(14)
	v_mul_f32_e32 v2, v2, v41
	s_waitcnt vmcnt(13)
	v_mul_f32_e32 v2, v2, v42
	s_waitcnt vmcnt(12)
	v_mul_f32_e32 v2, v2, v43
	s_waitcnt vmcnt(11)
	v_mul_f32_e32 v2, v2, v44
	s_waitcnt vmcnt(10)
	v_mul_f32_e32 v2, v2, v45
	s_waitcnt vmcnt(9)
	v_mul_f32_e32 v2, v2, v46
	s_waitcnt vmcnt(8)
	v_mul_f32_e32 v2, v2, v47
	s_waitcnt vmcnt(7)
	v_mul_f32_e32 v2, v2, v48
	s_waitcnt vmcnt(6)
	v_mul_f32_e32 v2, v2, v49
	s_waitcnt vmcnt(5)
	v_mul_f32_e32 v2, v2, v50
	s_waitcnt vmcnt(4)
	v_mul_f32_e32 v2, v2, v51
	s_waitcnt vmcnt(3)
	v_mul_f32_e32 v2, v2, v52
	s_waitcnt vmcnt(2)
	v_mul_f32_e32 v2, v2, v53
	s_waitcnt vmcnt(1)
	v_mul_f32_e32 v2, v2, v54
	s_waitcnt vmcnt(0)
	v_mul_f32_e32 v2, v2, v55
	v_lshl_add_u32 v0, s7, 8, v152
	v_ashrrev_i32_e32 v1, 31, v0
	v_lshl_add_u64 v[0:1], v[0:1], 2, s[12:13]
	global_store_dword v[0:1], v2, off
	s_branch .LBB0_209

.LBB0_224:
	s_lshl_b32 s0, s3, 4
	s_or_b32 s0, s0, s72
	s_lshl_b32 s0, s0, 12
	s_mov_b32 s1, 0
	v_lshl_add_u64 v[218:219], v[12:13], 0, s[0:1]
	global_load_ushort v220, v[218:219], off
	v_lshl_add_u64 v[218:219], v[218:219], 0, s[86:87]
	global_load_ushort v220, v[218:219], off
	v_lshl_add_u64 v[218:219], v[218:219], 0, s[86:87]
	global_load_ushort v220, v[218:219], off
	v_lshl_add_u64 v[218:219], v[218:219], 0, s[86:87]
	global_load_ushort v220, v[218:219], off
	v_lshl_add_u64 v[218:219], v[218:219], 0, s[86:87]
	global_load_ushort v220, v[218:219], off
	v_lshl_add_u64 v[218:219], v[218:219], 0, s[86:87]
	global_load_ushort v220, v[218:219], off
	v_lshl_add_u64 v[218:219], v[218:219], 0, s[86:87]
	global_load_ushort v220, v[218:219], off
	v_lshl_add_u64 v[218:219], v[218:219], 0, s[86:87]
	global_load_ushort v220, v[218:219], off
	v_lshl_add_u64 v[218:219], v[218:219], 0, s[86:87]
	global_load_ushort v220, v[218:219], off
	v_lshl_add_u64 v[218:219], v[218:219], 0, s[86:87]
	global_load_ushort v220, v[218:219], off
	v_lshl_add_u64 v[218:219], v[218:219], 0, s[86:87]
	global_load_ushort v220, v[218:219], off
	v_lshl_add_u64 v[218:219], v[218:219], 0, s[86:87]
	global_load_ushort v220, v[218:219], off
	v_lshl_add_u64 v[218:219], v[218:219], 0, s[86:87]
	global_load_ushort v220, v[218:219], off
	v_lshl_add_u64 v[218:219], v[218:219], 0, s[86:87]
	global_load_ushort v220, v[218:219], off
	v_lshl_add_u64 v[218:219], v[218:219], 0, s[86:87]
	global_load_ushort v220, v[218:219], off
	v_lshl_add_u64 v[218:219], v[218:219], 0, s[86:87]
	global_load_ushort v220, v[218:219], off
	s_lshl_b32 s0, s3, 10
	s_add_i32 s0, s0, 0x10000
	v_mov_b32_e32 v14, s0
	ds_read_b128 v[60:63], v14
	ds_read_b128 v[64:67], v14 offset:16
	ds_read_b128 v[68:71], v14 offset:32
	ds_read_b128 v[72:75], v14 offset:48
	s_lshl_b32 s20, s3, 4
	s_waitcnt vmcnt(0) lgkmcnt(3)
	v_fma_f32 v56, v133, v60, v134
	v_fmac_f32_e32 v56, v126, v61
	v_fmac_f32_e32 v56, v127, v62
	v_fmac_f32_e32 v56, v128, v63
	s_waitcnt lgkmcnt(2)
	v_fmac_f32_e32 v56, v129, v64
	v_fmac_f32_e32 v56, v130, v65
	v_fmac_f32_e32 v56, v131, v66
	v_fmac_f32_e32 v56, v132, v67
	s_waitcnt lgkmcnt(1)
	v_fmac_f32_e32 v56, v0, v68
	v_fmac_f32_e32 v56, v1, v69
	v_pk_mul_f32 v[14:15], v[2:3], v[70:71]
	s_or_b32 s50, s20, s72
	v_add_f32_e32 v14, v56, v14
	v_add_f32_e32 v56, v14, v15
	s_waitcnt lgkmcnt(0)
	v_pk_mul_f32 v[14:15], v[4:5], v[72:73]
	s_ashr_i32 s51, s50, 31
	v_add_f32_e32 v14, v56, v14
	v_add_f32_e32 v56, v14, v15
	v_pk_mul_f32 v[14:15], v[6:7], v[74:75]
	s_lshl_b64 s[0:1], s[50:51], 12
	v_add_f32_e32 v14, v56, v14
	v_add_f32_e32 v14, v14, v15
	v_min_f32_e32 v15, 0, v14
	v_mul_f32_e64 v14, |v14|, s65
	v_exp_f32_e32 v14, v14
	s_or_b32 s66, s20, 1
	s_or_b32 s74, s66, s72
	s_ashr_i32 s75, s74, 31
	v_add_f32_e32 v14, 1.0, v14
	v_cmp_gt_f32_e64 s[42:43], s80, v14
	s_or_b32 s73, s20, 2
	s_or_b32 s76, s73, s72
	v_cndmask_b32_e64 v56, 0, 32, s[42:43]
	v_ldexp_f32 v14, v14, v56
	v_log_f32_e32 v14, v14
	s_ashr_i32 s77, s76, 31
	s_or_b32 s68, s20, 3
	s_or_b32 s82, s68, s72
	v_mul_f32_e32 v56, 0x3f317217, v14
	v_fma_f32 v56, v14, s81, -v56
	v_fmac_f32_e32 v56, 0x3377d1cf, v14
	v_fmac_f32_e32 v56, 0x3f317217, v14
	v_cmp_lt_f32_e64 s[44:45], |v14|, s71
	s_ashr_i32 s83, s82, 31
	s_or_b32 s69, s20, 4
	v_cndmask_b32_e64 v14, v14, v56, s[44:45]
	v_cndmask_b32_e64 v56, 0, v236, s[42:43]
	v_sub_f32_e32 v14, v14, v56
	v_sub_f32_e32 v14, v15, v14
	v_fmac_f32_e32 v58, 0x3d800000, v14
	v_lshl_add_u64 v[14:15], v[12:13], 0, s[0:1]
	global_load_ushort v56, v[14:15], off
	s_lshl_b32 s0, s66, 6
	s_add_i32 s0, s0, 0x10000
	s_or_b32 s96, s69, s72
	s_ashr_i32 s97, s96, 31
	s_or_b32 s10, s20, 5
	s_or_b32 s8, s10, s72
	s_ashr_i32 s9, s8, 31
	s_or_b32 s11, s20, 6
	s_or_b32 s46, s11, s72
	s_ashr_i32 s47, s46, 31
	s_or_b32 s12, s20, 7
	s_or_b32 s60, s12, s72
	s_ashr_i32 s61, s60, 31
	s_or_b32 s13, s20, 8
	s_or_b32 s62, s13, s72
	s_ashr_i32 s63, s62, 31
	s_or_b32 s14, s20, 9
	s_or_b32 s56, s14, s72
	s_ashr_i32 s57, s56, 31
	s_or_b32 s15, s20, 10
	s_or_b32 s16, s20, 11
	s_or_b32 s6, s16, s72
	s_ashr_i32 s7, s6, 31
	s_or_b32 s17, s20, 12
	s_or_b32 s54, s17, s72
	s_ashr_i32 s55, s54, 31
	s_or_b32 s18, s20, 13
	s_or_b32 s48, s18, s72
	s_ashr_i32 s49, s48, 31
	s_or_b32 s19, s20, 14
	s_or_b32 s20, s20, 15
	s_lshl_b32 s21, s20, 6
	s_add_i32 s21, s21, 0x10000
	v_mul_f32_e32 v161, 0x3fb8aa3b, v58
	v_exp_f32_e32 v161, v161
	v_lshl_add_u32 v179, s73, 9, v112
	v_lshl_add_u32 v181, s68, 9, v113
	v_lshl_add_u32 v192, s12, 9, v117
	s_waitcnt vmcnt(0)
	v_lshlrev_b32_e32 v160, 16, v56
	v_mov_b32_e32 v56, s0
	ds_read_b128 v[60:63], v56
	ds_read_b128 v[64:67], v56 offset:16
	ds_read_b128 v[68:71], v56 offset:32
	ds_read_b128 v[72:75], v56 offset:48
	s_lshl_b64 s[0:1], s[74:75], 12
	s_waitcnt lgkmcnt(3)
	v_fma_f32 v59, v133, v60, v134
	v_fmac_f32_e32 v59, v126, v61
	v_fmac_f32_e32 v59, v127, v62
	v_fmac_f32_e32 v59, v128, v63
	s_waitcnt lgkmcnt(2)
	v_fmac_f32_e32 v59, v129, v64
	v_fmac_f32_e32 v59, v130, v65
	v_fmac_f32_e32 v59, v131, v66
	v_fmac_f32_e32 v59, v132, v67
	s_waitcnt lgkmcnt(1)
	v_fmac_f32_e32 v59, v0, v68
	v_fmac_f32_e32 v59, v1, v69
	v_pk_mul_f32 v[56:57], v[2:3], v[70:71]
	v_mul_f32_e32 v160, 0x3d800000, v160
	v_add_f32_e32 v56, v59, v56
	v_add_f32_e32 v59, v56, v57
	s_waitcnt lgkmcnt(0)
	v_pk_mul_f32 v[56:57], v[4:5], v[72:73]
	v_mul_f32_e32 v160, v160, v161
	v_add_f32_e32 v56, v59, v56
	v_add_f32_e32 v59, v56, v57
	v_pk_mul_f32 v[56:57], v[6:7], v[74:75]
	s_nop 0
	v_add_f32_e32 v56, v59, v56
	v_add_f32_e32 v56, v56, v57
	v_min_f32_e32 v57, 0, v56
	v_mul_f32_e64 v56, |v56|, s65
	v_exp_f32_e32 v56, v56
	s_nop 0
	v_add_f32_e32 v56, 1.0, v56
	v_cmp_gt_f32_e64 s[42:43], s80, v56
	s_nop 1
	v_cndmask_b32_e64 v59, 0, 32, s[42:43]
	v_ldexp_f32 v56, v56, v59
	v_log_f32_e32 v56, v56
	s_nop 0
	v_mul_f32_e32 v59, 0x3f317217, v56
	v_fma_f32 v59, v56, s81, -v59
	v_fmac_f32_e32 v59, 0x3377d1cf, v56
	v_fmac_f32_e32 v59, 0x3f317217, v56
	v_cmp_lt_f32_e64 s[44:45], |v56|, s71
	s_nop 1
	v_cndmask_b32_e64 v56, v56, v59, s[44:45]
	v_cndmask_b32_e64 v59, 0, v236, s[42:43]
	v_sub_f32_e32 v56, v56, v59
	v_sub_f32_e32 v56, v57, v56
	v_fmamk_f32 v59, v56, 0x3d800000, v58
	v_lshl_add_u64 v[56:57], v[12:13], 0, s[0:1]
	global_load_ushort v60, v[56:57], off
	s_lshl_b32 s0, s73, 6
	s_add_i32 s0, s0, 0x10000
	v_mov_b32_e32 v72, s0
	s_lshl_b64 s[0:1], s[76:77], 12
	v_mul_f32_e32 v58, 0xbfb8aa3b, v58
	v_exp_f32_e32 v58, v58
	s_waitcnt vmcnt(0)
	v_lshlrev_b32_e32 v88, 16, v60
	ds_read_b128 v[60:63], v72
	ds_read_b128 v[64:67], v72 offset:16
	ds_read_b128 v[68:71], v72 offset:32
	ds_read_b128 v[72:75], v72 offset:48
	s_waitcnt lgkmcnt(3)
	v_fma_f32 v76, v133, v60, v134
	v_fmac_f32_e32 v76, v126, v61
	v_fmac_f32_e32 v76, v127, v62
	v_fmac_f32_e32 v76, v128, v63
	s_waitcnt lgkmcnt(2)
	v_fmac_f32_e32 v76, v129, v64
	v_fmac_f32_e32 v76, v130, v65
	v_fmac_f32_e32 v76, v131, v66
	v_fmac_f32_e32 v76, v132, v67
	s_waitcnt lgkmcnt(1)
	v_fmac_f32_e32 v76, v0, v68
	v_fmac_f32_e32 v76, v1, v69
	v_pk_mul_f32 v[60:61], v[2:3], v[70:71]
	s_nop 0
	v_add_f32_e32 v60, v76, v60
	v_add_f32_e32 v62, v60, v61
	s_waitcnt lgkmcnt(0)
	v_pk_mul_f32 v[60:61], v[4:5], v[72:73]
	s_nop 0
	v_add_f32_e32 v60, v62, v60
	v_add_f32_e32 v62, v60, v61
	v_pk_mul_f32 v[60:61], v[6:7], v[74:75]
	s_nop 0
	v_add_f32_e32 v60, v62, v60
	v_add_f32_e32 v60, v60, v61
	v_min_f32_e32 v61, 0, v60
	v_mul_f32_e64 v60, |v60|, s65
	v_exp_f32_e32 v60, v60
	s_nop 0
	v_add_f32_e32 v60, 1.0, v60
	v_cmp_gt_f32_e64 s[42:43], s80, v60
	s_nop 1
	v_cndmask_b32_e64 v62, 0, 32, s[42:43]
	v_ldexp_f32 v60, v60, v62
	v_log_f32_e32 v60, v60
	s_nop 0
	v_mul_f32_e32 v62, 0x3f317217, v60
	v_fma_f32 v62, v60, s81, -v62
	v_fmac_f32_e32 v62, 0x3377d1cf, v60
	v_fmac_f32_e32 v62, 0x3f317217, v60
	v_cmp_lt_f32_e64 s[44:45], |v60|, s71
	s_nop 1
	v_cndmask_b32_e64 v60, v60, v62, s[44:45]
	v_cndmask_b32_e64 v62, 0, v236, s[42:43]
	v_sub_f32_e32 v60, v60, v62
	v_sub_f32_e32 v60, v61, v60
	v_fmamk_f32 v89, v60, 0x3d800000, v59
	v_lshl_add_u64 v[60:61], v[12:13], 0, s[0:1]
	global_load_ushort v62, v[60:61], off
	s_lshl_b32 s0, s68, 6
	s_add_i32 s0, s0, 0x10000
	v_mov_b32_e32 v74, s0
	s_lshl_b64 s[0:1], s[82:83], 12
	s_waitcnt vmcnt(0)
	v_lshlrev_b32_e32 v90, 16, v62
	ds_read_b128 v[62:65], v74
	ds_read_b128 v[66:69], v74 offset:16
	ds_read_b128 v[70:73], v74 offset:32
	ds_read_b128 v[74:77], v74 offset:48
	s_waitcnt lgkmcnt(3)
	v_fma_f32 v78, v133, v62, v134
	v_fmac_f32_e32 v78, v126, v63
	v_fmac_f32_e32 v78, v127, v64
	v_fmac_f32_e32 v78, v128, v65
	s_waitcnt lgkmcnt(2)
	v_fmac_f32_e32 v78, v129, v66
	v_fmac_f32_e32 v78, v130, v67
	v_fmac_f32_e32 v78, v131, v68
	v_fmac_f32_e32 v78, v132, v69
	s_waitcnt lgkmcnt(1)
	v_fmac_f32_e32 v78, v0, v70
	v_fmac_f32_e32 v78, v1, v71
	v_pk_mul_f32 v[62:63], v[2:3], v[72:73]
	s_nop 0
	v_add_f32_e32 v62, v78, v62
	v_add_f32_e32 v64, v62, v63
	s_waitcnt lgkmcnt(0)
	v_pk_mul_f32 v[62:63], v[4:5], v[74:75]
	s_nop 0
	v_add_f32_e32 v62, v64, v62
	v_add_f32_e32 v64, v62, v63
	v_pk_mul_f32 v[62:63], v[6:7], v[76:77]
	s_nop 0
	v_add_f32_e32 v62, v64, v62
	v_add_f32_e32 v62, v62, v63
	v_min_f32_e32 v63, 0, v62
	v_mul_f32_e64 v62, |v62|, s65
	v_exp_f32_e32 v62, v62
	s_nop 0
	v_add_f32_e32 v62, 1.0, v62
	v_cmp_gt_f32_e64 s[42:43], s80, v62
	s_nop 1
	v_cndmask_b32_e64 v64, 0, 32, s[42:43]
	v_ldexp_f32 v62, v62, v64
	v_log_f32_e32 v62, v62
	s_nop 0
	v_mul_f32_e32 v64, 0x3f317217, v62
	v_fma_f32 v64, v62, s81, -v64
	v_fmac_f32_e32 v64, 0x3377d1cf, v62
	v_fmac_f32_e32 v64, 0x3f317217, v62
	v_cmp_lt_f32_e64 s[44:45], |v62|, s71
	s_nop 1
	v_cndmask_b32_e64 v62, v62, v64, s[44:45]
	v_cndmask_b32_e64 v64, 0, v236, s[42:43]
	v_sub_f32_e32 v62, v62, v64
	v_sub_f32_e32 v62, v63, v62
	v_fmamk_f32 v91, v62, 0x3d800000, v89
	v_lshl_add_u64 v[62:63], v[12:13], 0, s[0:1]
	global_load_ushort v64, v[62:63], off
	s_lshl_b32 s0, s69, 6
	s_add_i32 s0, s0, 0x10000
	v_mov_b32_e32 v76, s0
	s_lshl_b64 s[0:1], s[96:97], 12
	s_waitcnt vmcnt(0)
	v_lshlrev_b32_e32 v136, 16, v64
	ds_read_b128 v[64:67], v76
	ds_read_b128 v[68:71], v76 offset:16
	ds_read_b128 v[72:75], v76 offset:32
	ds_read_b128 v[76:79], v76 offset:48
	s_waitcnt lgkmcnt(3)
	v_fma_f32 v80, v133, v64, v134
	v_fmac_f32_e32 v80, v126, v65
	v_fmac_f32_e32 v80, v127, v66
	v_fmac_f32_e32 v80, v128, v67
	s_waitcnt lgkmcnt(2)
	v_fmac_f32_e32 v80, v129, v68
	v_fmac_f32_e32 v80, v130, v69
	v_fmac_f32_e32 v80, v131, v70
	v_fmac_f32_e32 v80, v132, v71
	s_waitcnt lgkmcnt(1)
	v_fmac_f32_e32 v80, v0, v72
	v_fmac_f32_e32 v80, v1, v73
	v_pk_mul_f32 v[64:65], v[2:3], v[74:75]
	s_nop 0
	v_add_f32_e32 v64, v80, v64
	v_add_f32_e32 v66, v64, v65
	s_waitcnt lgkmcnt(0)
	v_pk_mul_f32 v[64:65], v[4:5], v[76:77]
	s_nop 0
	v_add_f32_e32 v64, v66, v64
	v_add_f32_e32 v66, v64, v65
	v_pk_mul_f32 v[64:65], v[6:7], v[78:79]
	s_nop 0
	v_add_f32_e32 v64, v66, v64
	v_add_f32_e32 v64, v64, v65
	v_min_f32_e32 v65, 0, v64
	v_mul_f32_e64 v64, |v64|, s65
	v_exp_f32_e32 v64, v64
	s_nop 0
	v_add_f32_e32 v64, 1.0, v64
	v_cmp_gt_f32_e64 s[42:43], s80, v64
	s_nop 1
	v_cndmask_b32_e64 v66, 0, 32, s[42:43]
	v_ldexp_f32 v64, v64, v66
	v_log_f32_e32 v64, v64
	s_nop 0
	v_mul_f32_e32 v66, 0x3f317217, v64
	v_fma_f32 v66, v64, s81, -v66
	v_fmac_f32_e32 v66, 0x3377d1cf, v64
	v_fmac_f32_e32 v66, 0x3f317217, v64
	v_cmp_lt_f32_e64 s[44:45], |v64|, s71
	s_nop 1
	v_cndmask_b32_e64 v64, v64, v66, s[44:45]
	v_cndmask_b32_e64 v66, 0, v236, s[42:43]
	v_sub_f32_e32 v64, v64, v66
	v_sub_f32_e32 v64, v65, v64
	v_fmamk_f32 v137, v64, 0x3d800000, v91
	v_lshl_add_u64 v[64:65], v[12:13], 0, s[0:1]
	global_load_ushort v66, v[64:65], off
	s_lshl_b32 s0, s10, 6
	s_add_i32 s0, s0, 0x10000
	v_mov_b32_e32 v78, s0
	s_lshl_b64 s[0:1], s[8:9], 12
	s_lshl_b64 s[8:9], s[8:9], 11
	s_waitcnt vmcnt(0)
	v_lshlrev_b32_e32 v138, 16, v66
	ds_read_b128 v[66:69], v78
	ds_read_b128 v[70:73], v78 offset:16
	ds_read_b128 v[74:77], v78 offset:32
	ds_read_b128 v[78:81], v78 offset:48
	s_waitcnt lgkmcnt(3)
	v_fma_f32 v82, v133, v66, v134
	v_fmac_f32_e32 v82, v126, v67
	v_fmac_f32_e32 v82, v127, v68
	v_fmac_f32_e32 v82, v128, v69
	s_waitcnt lgkmcnt(2)
	v_fmac_f32_e32 v82, v129, v70
	v_fmac_f32_e32 v82, v130, v71
	v_fmac_f32_e32 v82, v131, v72
	v_fmac_f32_e32 v82, v132, v73
	s_waitcnt lgkmcnt(1)
	v_fmac_f32_e32 v82, v0, v74
	v_fmac_f32_e32 v82, v1, v75
	v_pk_mul_f32 v[66:67], v[2:3], v[76:77]
	s_nop 0
	v_add_f32_e32 v66, v82, v66
	v_add_f32_e32 v68, v66, v67
	s_waitcnt lgkmcnt(0)
	v_pk_mul_f32 v[66:67], v[4:5], v[78:79]
	s_nop 0
	v_add_f32_e32 v66, v68, v66
	v_add_f32_e32 v68, v66, v67
	v_pk_mul_f32 v[66:67], v[6:7], v[80:81]
	s_nop 0
	v_add_f32_e32 v66, v68, v66
	v_add_f32_e32 v66, v66, v67
	v_min_f32_e32 v67, 0, v66
	v_mul_f32_e64 v66, |v66|, s65
	v_exp_f32_e32 v66, v66
	s_nop 0
	v_add_f32_e32 v66, 1.0, v66
	v_cmp_gt_f32_e64 s[42:43], s80, v66
	s_nop 1
	v_cndmask_b32_e64 v68, 0, 32, s[42:43]
	v_ldexp_f32 v66, v66, v68
	v_log_f32_e32 v66, v66
	s_nop 0
	v_mul_f32_e32 v68, 0x3f317217, v66
	v_fma_f32 v68, v66, s81, -v68
	v_fmac_f32_e32 v68, 0x3377d1cf, v66
	v_fmac_f32_e32 v68, 0x3f317217, v66
	v_cmp_lt_f32_e64 s[44:45], |v66|, s71
	s_nop 1
	v_cndmask_b32_e64 v66, v66, v68, s[44:45]
	v_cndmask_b32_e64 v68, 0, v236, s[42:43]
	v_sub_f32_e32 v66, v66, v68
	v_sub_f32_e32 v66, v67, v66
	v_fmamk_f32 v139, v66, 0x3d800000, v137
	v_lshl_add_u64 v[66:67], v[12:13], 0, s[0:1]
	global_load_ushort v68, v[66:67], off
	s_lshl_b32 s0, s11, 6
	s_add_i32 s0, s0, 0x10000
	v_mov_b32_e32 v80, s0
	s_lshl_b64 s[0:1], s[46:47], 12
	s_waitcnt vmcnt(0)
	v_lshlrev_b32_e32 v140, 16, v68
	ds_read_b128 v[68:71], v80
	ds_read_b128 v[72:75], v80 offset:16
	ds_read_b128 v[76:79], v80 offset:32
	ds_read_b128 v[80:83], v80 offset:48
	s_waitcnt lgkmcnt(3)
	v_fma_f32 v84, v133, v68, v134
	v_fmac_f32_e32 v84, v126, v69
	v_fmac_f32_e32 v84, v127, v70
	v_fmac_f32_e32 v84, v128, v71
	s_waitcnt lgkmcnt(2)
	v_fmac_f32_e32 v84, v129, v72
	v_fmac_f32_e32 v84, v130, v73
	v_fmac_f32_e32 v84, v131, v74
	v_fmac_f32_e32 v84, v132, v75
	s_waitcnt lgkmcnt(1)
	v_fmac_f32_e32 v84, v0, v76
	v_fmac_f32_e32 v84, v1, v77
	v_pk_mul_f32 v[68:69], v[2:3], v[78:79]
	s_nop 0
	v_add_f32_e32 v68, v84, v68
	v_add_f32_e32 v70, v68, v69
	s_waitcnt lgkmcnt(0)
	v_pk_mul_f32 v[68:69], v[4:5], v[80:81]
	s_nop 0
	v_add_f32_e32 v68, v70, v68
	v_add_f32_e32 v70, v68, v69
	v_pk_mul_f32 v[68:69], v[6:7], v[82:83]
	s_nop 0
	v_add_f32_e32 v68, v70, v68
	v_add_f32_e32 v68, v68, v69
	v_min_f32_e32 v69, 0, v68
	v_mul_f32_e64 v68, |v68|, s65
	v_exp_f32_e32 v68, v68
	s_nop 0
	v_add_f32_e32 v68, 1.0, v68
	v_cmp_gt_f32_e64 s[42:43], s80, v68
	s_nop 1
	v_cndmask_b32_e64 v70, 0, 32, s[42:43]
	v_ldexp_f32 v68, v68, v70
	v_log_f32_e32 v68, v68
	s_nop 0
	v_mul_f32_e32 v70, 0x3f317217, v68
	v_fma_f32 v70, v68, s81, -v70
	v_fmac_f32_e32 v70, 0x3377d1cf, v68
	v_fmac_f32_e32 v70, 0x3f317217, v68
	v_cmp_lt_f32_e64 s[44:45], |v68|, s71
	s_nop 1
	v_cndmask_b32_e64 v68, v68, v70, s[44:45]
	v_cndmask_b32_e64 v70, 0, v236, s[42:43]
	v_sub_f32_e32 v68, v68, v70
	v_sub_f32_e32 v68, v69, v68
	v_fmamk_f32 v141, v68, 0x3d800000, v139
	v_lshl_add_u64 v[68:69], v[12:13], 0, s[0:1]
	global_load_ushort v70, v[68:69], off
	s_lshl_b32 s0, s12, 6
	s_add_i32 s0, s0, 0x10000
	v_mov_b32_e32 v82, s0
	s_lshl_b64 s[0:1], s[60:61], 12
	s_waitcnt vmcnt(0)
	v_lshlrev_b32_e32 v142, 16, v70
	ds_read_b128 v[70:73], v82
	ds_read_b128 v[74:77], v82 offset:16
	ds_read_b128 v[78:81], v82 offset:32
	ds_read_b128 v[82:85], v82 offset:48
	s_waitcnt lgkmcnt(3)
	v_fma_f32 v86, v133, v70, v134
	v_fmac_f32_e32 v86, v126, v71
	v_fmac_f32_e32 v86, v127, v72
	v_fmac_f32_e32 v86, v128, v73
	s_waitcnt lgkmcnt(2)
	v_fmac_f32_e32 v86, v129, v74
	v_fmac_f32_e32 v86, v130, v75
	v_fmac_f32_e32 v86, v131, v76
	v_fmac_f32_e32 v86, v132, v77
	s_waitcnt lgkmcnt(1)
	v_fmac_f32_e32 v86, v0, v78
	v_fmac_f32_e32 v86, v1, v79
	v_pk_mul_f32 v[70:71], v[2:3], v[80:81]
	s_nop 0
	v_add_f32_e32 v70, v86, v70
	v_add_f32_e32 v72, v70, v71
	s_waitcnt lgkmcnt(0)
	v_pk_mul_f32 v[70:71], v[4:5], v[82:83]
	s_nop 0
	v_add_f32_e32 v70, v72, v70
	v_add_f32_e32 v72, v70, v71
	v_pk_mul_f32 v[70:71], v[6:7], v[84:85]
	s_nop 0
	v_add_f32_e32 v70, v72, v70
	v_add_f32_e32 v70, v70, v71
	v_min_f32_e32 v71, 0, v70
	v_mul_f32_e64 v70, |v70|, s65
	v_exp_f32_e32 v70, v70
	s_nop 0
	v_add_f32_e32 v70, 1.0, v70
	v_cmp_gt_f32_e64 s[42:43], s80, v70
	s_nop 1
	v_cndmask_b32_e64 v72, 0, 32, s[42:43]
	v_ldexp_f32 v70, v70, v72
	v_log_f32_e32 v70, v70
	s_nop 0
	v_mul_f32_e32 v72, 0x3f317217, v70
	v_fma_f32 v72, v70, s81, -v72
	v_fmac_f32_e32 v72, 0x3377d1cf, v70
	v_fmac_f32_e32 v72, 0x3f317217, v70
	v_cmp_lt_f32_e64 s[44:45], |v70|, s71
	s_nop 1
	v_cndmask_b32_e64 v70, v70, v72, s[44:45]
	v_cndmask_b32_e64 v72, 0, v236, s[42:43]
	v_sub_f32_e32 v70, v70, v72
	v_sub_f32_e32 v70, v71, v70
	v_fmamk_f32 v143, v70, 0x3d800000, v141
	v_lshl_add_u64 v[70:71], v[12:13], 0, s[0:1]
	global_load_ushort v72, v[70:71], off
	s_lshl_b32 s0, s13, 6
	s_add_i32 s0, s0, 0x10000
	v_mov_b32_e32 v84, s0
	s_lshl_b64 s[0:1], s[62:63], 12
	s_waitcnt vmcnt(0)
	v_lshlrev_b32_e32 v144, 16, v72
	ds_read_b128 v[72:75], v84
	ds_read_b128 v[76:79], v84 offset:16
	ds_read_b128 v[80:83], v84 offset:32
	ds_read_b128 v[84:87], v84 offset:48
	s_waitcnt lgkmcnt(3)
	v_fma_f32 v135, v133, v72, v134
	v_fmac_f32_e32 v135, v126, v73
	v_fmac_f32_e32 v135, v127, v74
	v_fmac_f32_e32 v135, v128, v75
	s_waitcnt lgkmcnt(2)
	v_fmac_f32_e32 v135, v129, v76
	v_fmac_f32_e32 v135, v130, v77
	v_fmac_f32_e32 v135, v131, v78
	v_fmac_f32_e32 v135, v132, v79
	s_waitcnt lgkmcnt(1)
	v_fmac_f32_e32 v135, v0, v80
	v_fmac_f32_e32 v135, v1, v81
	v_pk_mul_f32 v[72:73], v[2:3], v[82:83]
	s_nop 0
	v_add_f32_e32 v72, v135, v72
	v_add_f32_e32 v74, v72, v73
	s_waitcnt lgkmcnt(0)
	v_pk_mul_f32 v[72:73], v[4:5], v[84:85]
	s_nop 0
	v_add_f32_e32 v72, v74, v72
	v_add_f32_e32 v74, v72, v73
	v_pk_mul_f32 v[72:73], v[6:7], v[86:87]
	s_nop 0
	v_add_f32_e32 v72, v74, v72
	v_add_f32_e32 v72, v72, v73
	v_min_f32_e32 v73, 0, v72
	v_mul_f32_e64 v72, |v72|, s65
	v_exp_f32_e32 v72, v72
	s_nop 0
	v_add_f32_e32 v72, 1.0, v72
	v_cmp_gt_f32_e64 s[42:43], s80, v72
	s_nop 1
	v_cndmask_b32_e64 v74, 0, 32, s[42:43]
	v_ldexp_f32 v72, v72, v74
	v_log_f32_e32 v72, v72
	s_nop 0
	v_mul_f32_e32 v74, 0x3f317217, v72
	v_fma_f32 v74, v72, s81, -v74
	v_fmac_f32_e32 v74, 0x3377d1cf, v72
	v_fmac_f32_e32 v74, 0x3f317217, v72
	v_cmp_lt_f32_e64 s[44:45], |v72|, s71
	s_nop 1
	v_cndmask_b32_e64 v72, v72, v74, s[44:45]
	v_cndmask_b32_e64 v74, 0, v236, s[42:43]
	v_sub_f32_e32 v72, v72, v74
	v_sub_f32_e32 v72, v73, v72
	v_fmamk_f32 v145, v72, 0x3d800000, v143
	v_lshl_add_u64 v[72:73], v[12:13], 0, s[0:1]
	global_load_ushort v74, v[72:73], off
	s_lshl_b32 s0, s14, 6
	s_add_i32 s0, s0, 0x10000
	v_mov_b32_e32 v86, s0
	s_lshl_b64 s[0:1], s[56:57], 12
	s_waitcnt vmcnt(0)
	v_lshlrev_b32_e32 v146, 16, v74
	ds_read_b128 v[74:77], v86
	ds_read_b128 v[78:81], v86 offset:16
	ds_read_b128 v[82:85], v86 offset:32
	ds_read_b128 v[148:151], v86 offset:48
	s_waitcnt lgkmcnt(3)
	v_fma_f32 v86, v133, v74, v134
	v_fmac_f32_e32 v86, v126, v75
	v_fmac_f32_e32 v86, v127, v76
	v_fmac_f32_e32 v86, v128, v77
	s_waitcnt lgkmcnt(2)
	v_fmac_f32_e32 v86, v129, v78
	v_fmac_f32_e32 v86, v130, v79
	v_fmac_f32_e32 v86, v131, v80
	v_fmac_f32_e32 v86, v132, v81
	s_waitcnt lgkmcnt(1)
	v_fmac_f32_e32 v86, v0, v82
	v_fmac_f32_e32 v86, v1, v83
	v_pk_mul_f32 v[74:75], v[2:3], v[84:85]
	s_nop 0
	v_add_f32_e32 v74, v86, v74
	v_add_f32_e32 v76, v74, v75
	s_waitcnt lgkmcnt(0)
	v_pk_mul_f32 v[74:75], v[4:5], v[148:149]
	s_nop 0
	v_add_f32_e32 v74, v76, v74
	v_add_f32_e32 v76, v74, v75
	v_pk_mul_f32 v[74:75], v[6:7], v[150:151]
	s_nop 0
	v_add_f32_e32 v74, v76, v74
	v_add_f32_e32 v74, v74, v75
	v_min_f32_e32 v75, 0, v74
	v_mul_f32_e64 v74, |v74|, s65
	v_exp_f32_e32 v74, v74
	s_nop 0
	v_add_f32_e32 v74, 1.0, v74
	v_cmp_gt_f32_e64 s[42:43], s80, v74
	s_nop 1
	v_cndmask_b32_e64 v76, 0, 32, s[42:43]
	v_ldexp_f32 v74, v74, v76
	v_log_f32_e32 v74, v74
	s_nop 0
	v_mul_f32_e32 v76, 0x3f317217, v74
	v_fma_f32 v76, v74, s81, -v76
	v_fmac_f32_e32 v76, 0x3377d1cf, v74
	v_fmac_f32_e32 v76, 0x3f317217, v74
	v_cmp_lt_f32_e64 s[44:45], |v74|, s71
	s_nop 1
	v_cndmask_b32_e64 v74, v74, v76, s[44:45]
	v_cndmask_b32_e64 v76, 0, v236, s[42:43]
	v_sub_f32_e32 v74, v74, v76
	v_sub_f32_e32 v74, v75, v74
	v_fmamk_f32 v147, v74, 0x3d800000, v145
	v_lshl_add_u64 v[74:75], v[12:13], 0, s[0:1]
	global_load_ushort v76, v[74:75], off
	s_lshl_b32 s0, s15, 6
	s_add_i32 s0, s0, 0x10000
	v_mov_b32_e32 v135, s0
	s_or_b32 s0, s15, s72
	s_ashr_i32 s1, s0, 31
	s_lshl_b64 s[4:5], s[0:1], 12
	v_cvt_pk_bf16_f32 v160, v160, s0
	s_waitcnt vmcnt(0)
	v_lshlrev_b32_e32 v148, 16, v76
	ds_read_b128 v[76:79], v135
	ds_read_b128 v[80:83], v135 offset:16
	ds_read_b128 v[84:87], v135 offset:32
	ds_read_b128 v[150:153], v135 offset:48
	s_waitcnt lgkmcnt(3)
	v_fma_f32 v135, v133, v76, v134
	v_fmac_f32_e32 v135, v126, v77
	v_fmac_f32_e32 v135, v127, v78
	v_fmac_f32_e32 v135, v128, v79
	s_waitcnt lgkmcnt(2)
	v_fmac_f32_e32 v135, v129, v80
	v_fmac_f32_e32 v135, v130, v81
	v_fmac_f32_e32 v135, v131, v82
	v_fmac_f32_e32 v135, v132, v83
	s_waitcnt lgkmcnt(1)
	v_fmac_f32_e32 v135, v0, v84
	v_fmac_f32_e32 v135, v1, v85
	v_pk_mul_f32 v[76:77], v[2:3], v[86:87]
	s_nop 0
	v_add_f32_e32 v76, v135, v76
	v_add_f32_e32 v78, v76, v77
	s_waitcnt lgkmcnt(0)
	v_pk_mul_f32 v[76:77], v[4:5], v[150:151]
	s_nop 0
	v_add_f32_e32 v76, v78, v76
	v_add_f32_e32 v78, v76, v77
	v_pk_mul_f32 v[76:77], v[6:7], v[152:153]
	s_nop 0
	v_add_f32_e32 v76, v78, v76
	v_add_f32_e32 v76, v76, v77
	v_min_f32_e32 v77, 0, v76
	v_mul_f32_e64 v76, |v76|, s65
	v_exp_f32_e32 v76, v76
	s_nop 0
	v_add_f32_e32 v76, 1.0, v76
	v_cmp_gt_f32_e64 s[42:43], s80, v76
	s_nop 1
	v_cndmask_b32_e64 v78, 0, 32, s[42:43]
	v_ldexp_f32 v76, v76, v78
	v_log_f32_e32 v76, v76
	s_nop 0
	v_mul_f32_e32 v78, 0x3f317217, v76
	v_fma_f32 v78, v76, s81, -v78
	v_fmac_f32_e32 v78, 0x3377d1cf, v76
	v_fmac_f32_e32 v78, 0x3f317217, v76
	v_cmp_lt_f32_e64 s[44:45], |v76|, s71
	s_nop 1
	v_cndmask_b32_e64 v76, v76, v78, s[44:45]
	v_cndmask_b32_e64 v78, 0, v236, s[42:43]
	v_sub_f32_e32 v76, v76, v78
	v_sub_f32_e32 v76, v77, v76
	v_fmamk_f32 v149, v76, 0x3d800000, v147
	v_lshl_add_u64 v[76:77], v[12:13], 0, s[4:5]
	global_load_ushort v78, v[76:77], off
	s_lshl_b32 s4, s16, 6
	s_add_i32 s4, s4, 0x10000
	v_mov_b32_e32 v86, s4
	s_lshl_b64 s[4:5], s[6:7], 12
	s_waitcnt vmcnt(0)
	v_lshlrev_b32_e32 v150, 16, v78
	ds_read_b128 v[78:81], v86
	ds_read_b128 v[82:85], v86 offset:16
	ds_read_b128 v[152:155], v86 offset:32
	ds_read_b128 v[156:159], v86 offset:48
	s_waitcnt lgkmcnt(3)
	v_fma_f32 v86, v133, v78, v134
	v_fmac_f32_e32 v86, v126, v79
	v_fmac_f32_e32 v86, v127, v80
	v_fmac_f32_e32 v86, v128, v81
	s_waitcnt lgkmcnt(2)
	v_fmac_f32_e32 v86, v129, v82
	v_fmac_f32_e32 v86, v130, v83
	v_fmac_f32_e32 v86, v131, v84
	v_fmac_f32_e32 v86, v132, v85
	s_waitcnt lgkmcnt(1)
	v_fmac_f32_e32 v86, v0, v152
	v_fmac_f32_e32 v86, v1, v153
	v_pk_mul_f32 v[78:79], v[2:3], v[154:155]
	s_nop 0
	v_add_f32_e32 v78, v86, v78
	v_add_f32_e32 v80, v78, v79
	s_waitcnt lgkmcnt(0)
	v_pk_mul_f32 v[78:79], v[4:5], v[156:157]
	s_nop 0
	v_add_f32_e32 v78, v80, v78
	v_add_f32_e32 v80, v78, v79
	v_pk_mul_f32 v[78:79], v[6:7], v[158:159]
	s_nop 0
	v_add_f32_e32 v78, v80, v78
	v_add_f32_e32 v78, v78, v79
	v_min_f32_e32 v79, 0, v78
	v_mul_f32_e64 v78, |v78|, s65
	v_exp_f32_e32 v78, v78
	s_nop 0
	v_add_f32_e32 v78, 1.0, v78
	v_cmp_gt_f32_e64 s[42:43], s80, v78
	s_nop 1
	v_cndmask_b32_e64 v80, 0, 32, s[42:43]
	v_ldexp_f32 v78, v78, v80
	v_log_f32_e32 v78, v78
	s_nop 0
	v_mul_f32_e32 v80, 0x3f317217, v78
	v_fma_f32 v80, v78, s81, -v80
	v_fmac_f32_e32 v80, 0x3377d1cf, v78
	v_fmac_f32_e32 v80, 0x3f317217, v78
	v_cmp_lt_f32_e64 s[44:45], |v78|, s71
	s_nop 1
	v_cndmask_b32_e64 v78, v78, v80, s[44:45]
	v_cndmask_b32_e64 v80, 0, v236, s[42:43]
	v_sub_f32_e32 v78, v78, v80
	v_sub_f32_e32 v78, v79, v78
	v_fmamk_f32 v151, v78, 0x3d800000, v149
	v_lshl_add_u64 v[78:79], v[12:13], 0, s[4:5]
	global_load_ushort v80, v[78:79], off
	s_lshl_b32 s4, s17, 6
	s_add_i32 s4, s4, 0x10000
	v_mov_b32_e32 v135, s4
	s_lshl_b64 s[4:5], s[54:55], 12
	s_waitcnt vmcnt(0)
	v_lshlrev_b32_e32 v152, 16, v80
	ds_read_b128 v[80:83], v135
	ds_read_b128 v[84:87], v135 offset:16
	ds_read_b128 v[154:157], v135 offset:32
	ds_read_b128 v[162:165], v135 offset:48
	s_waitcnt lgkmcnt(3)
	v_fma_f32 v135, v133, v80, v134
	v_fmac_f32_e32 v135, v126, v81
	v_fmac_f32_e32 v135, v127, v82
	v_fmac_f32_e32 v135, v128, v83
	s_waitcnt lgkmcnt(2)
	v_fmac_f32_e32 v135, v129, v84
	v_fmac_f32_e32 v135, v130, v85
	v_fmac_f32_e32 v135, v131, v86
	v_fmac_f32_e32 v135, v132, v87
	s_waitcnt lgkmcnt(1)
	v_fmac_f32_e32 v135, v0, v154
	v_fmac_f32_e32 v135, v1, v155
	v_pk_mul_f32 v[80:81], v[2:3], v[156:157]
	s_nop 0
	v_add_f32_e32 v80, v135, v80
	v_add_f32_e32 v82, v80, v81
	s_waitcnt lgkmcnt(0)
	v_pk_mul_f32 v[80:81], v[4:5], v[162:163]
	s_nop 0
	v_add_f32_e32 v80, v82, v80
	v_add_f32_e32 v82, v80, v81
	v_pk_mul_f32 v[80:81], v[6:7], v[164:165]
	s_nop 0
	v_add_f32_e32 v80, v82, v80
	v_add_f32_e32 v80, v80, v81
	v_min_f32_e32 v81, 0, v80
	v_mul_f32_e64 v80, |v80|, s65
	v_exp_f32_e32 v80, v80
	s_nop 0
	v_add_f32_e32 v80, 1.0, v80
	v_cmp_gt_f32_e64 s[42:43], s80, v80
	s_nop 1
	v_cndmask_b32_e64 v82, 0, 32, s[42:43]
	v_ldexp_f32 v80, v80, v82
	v_log_f32_e32 v80, v80
	s_nop 0
	v_mul_f32_e32 v82, 0x3f317217, v80
	v_fma_f32 v82, v80, s81, -v82
	v_fmac_f32_e32 v82, 0x3377d1cf, v80
	v_fmac_f32_e32 v82, 0x3f317217, v80
	v_cmp_lt_f32_e64 s[44:45], |v80|, s71
	s_nop 1
	v_cndmask_b32_e64 v80, v80, v82, s[44:45]
	v_cndmask_b32_e64 v82, 0, v236, s[42:43]
	v_sub_f32_e32 v80, v80, v82
	v_sub_f32_e32 v80, v81, v80
	v_fmamk_f32 v153, v80, 0x3d800000, v151
	v_lshl_add_u64 v[80:81], v[12:13], 0, s[4:5]
	global_load_ushort v82, v[80:81], off
	s_lshl_b32 s4, s18, 6
	s_add_i32 s4, s4, 0x10000
	v_mov_b32_e32 v86, s4
	s_lshl_b64 s[4:5], s[48:49], 12
	s_waitcnt vmcnt(0)
	v_lshlrev_b32_e32 v154, 16, v82
	ds_read_b128 v[82:85], v86
	ds_read_b128 v[156:159], v86 offset:16
	ds_read_b128 v[162:165], v86 offset:32
	ds_read_b128 v[166:169], v86 offset:48
	s_waitcnt lgkmcnt(3)
	v_fma_f32 v86, v133, v82, v134
	v_fmac_f32_e32 v86, v126, v83
	v_fmac_f32_e32 v86, v127, v84
	v_fmac_f32_e32 v86, v128, v85
	s_waitcnt lgkmcnt(2)
	v_fmac_f32_e32 v86, v129, v156
	v_fmac_f32_e32 v86, v130, v157
	v_fmac_f32_e32 v86, v131, v158
	v_fmac_f32_e32 v86, v132, v159
	s_waitcnt lgkmcnt(1)
	v_fmac_f32_e32 v86, v0, v162
	v_fmac_f32_e32 v86, v1, v163
	v_pk_mul_f32 v[82:83], v[2:3], v[164:165]
	s_nop 0
	v_add_f32_e32 v82, v86, v82
	v_add_f32_e32 v84, v82, v83
	s_waitcnt lgkmcnt(0)
	v_pk_mul_f32 v[82:83], v[4:5], v[166:167]
	s_nop 0
	v_add_f32_e32 v82, v84, v82
	v_add_f32_e32 v84, v82, v83
	v_pk_mul_f32 v[82:83], v[6:7], v[168:169]
	s_nop 0
	v_add_f32_e32 v82, v84, v82
	v_add_f32_e32 v82, v82, v83
	v_min_f32_e32 v83, 0, v82
	v_mul_f32_e64 v82, |v82|, s65
	v_exp_f32_e32 v82, v82
	s_nop 0
	v_add_f32_e32 v82, 1.0, v82
	v_cmp_gt_f32_e64 s[42:43], s80, v82
	s_nop 1
	v_cndmask_b32_e64 v84, 0, 32, s[42:43]
	v_ldexp_f32 v82, v82, v84
	v_log_f32_e32 v82, v82
	s_nop 0
	v_mul_f32_e32 v84, 0x3f317217, v82
	v_fma_f32 v84, v82, s81, -v84
	v_fmac_f32_e32 v84, 0x3377d1cf, v82
	v_fmac_f32_e32 v84, 0x3f317217, v82
	v_cmp_lt_f32_e64 s[44:45], |v82|, s71
	s_nop 1
	v_cndmask_b32_e64 v82, v82, v84, s[44:45]
	v_cndmask_b32_e64 v84, 0, v236, s[42:43]
	v_sub_f32_e32 v82, v82, v84
	v_sub_f32_e32 v82, v83, v82
	v_fmamk_f32 v155, v82, 0x3d800000, v153
	v_lshl_add_u64 v[82:83], v[12:13], 0, s[4:5]
	global_load_ushort v84, v[82:83], off
	s_lshl_b32 s4, s19, 6
	s_add_i32 s4, s4, 0x10000
	v_mov_b32_e32 v135, s4
	s_or_b32 s4, s19, s72
	s_ashr_i32 s5, s4, 31
	s_waitcnt vmcnt(0)
	v_lshlrev_b32_e32 v156, 16, v84
	ds_read_b128 v[84:87], v135
	ds_read_b128 v[162:165], v135 offset:16
	ds_read_b128 v[166:169], v135 offset:32
	ds_read_b128 v[170:173], v135 offset:48
	s_waitcnt lgkmcnt(3)
	v_fma_f32 v135, v133, v84, v134
	v_fmac_f32_e32 v135, v126, v85
	v_fmac_f32_e32 v135, v127, v86
	v_fmac_f32_e32 v135, v128, v87
	s_waitcnt lgkmcnt(2)
	v_fmac_f32_e32 v135, v129, v162
	v_fmac_f32_e32 v135, v130, v163
	v_fmac_f32_e32 v135, v131, v164
	v_fmac_f32_e32 v135, v132, v165
	s_waitcnt lgkmcnt(1)
	v_pk_mul_f32 v[84:85], v[0:1], v[166:167]
	s_nop 0
	v_add_f32_e32 v84, v135, v84
	v_add_f32_e32 v86, v84, v85
	v_pk_mul_f32 v[84:85], v[2:3], v[168:169]
	s_nop 0
	v_add_f32_e32 v84, v86, v84
	v_add_f32_e32 v86, v84, v85
	s_waitcnt lgkmcnt(0)
	v_pk_mul_f32 v[84:85], v[4:5], v[170:171]
	s_nop 0
	v_add_f32_e32 v84, v86, v84
	v_add_f32_e32 v86, v84, v85
	v_pk_mul_f32 v[84:85], v[6:7], v[172:173]
	s_nop 0
	v_add_f32_e32 v84, v86, v84
	v_add_f32_e32 v84, v84, v85
	v_min_f32_e32 v85, 0, v84
	v_mul_f32_e64 v84, |v84|, s65
	v_exp_f32_e32 v84, v84
	s_nop 0
	v_add_f32_e32 v84, 1.0, v84
	v_cmp_gt_f32_e64 s[42:43], s80, v84
	s_nop 1
	v_cndmask_b32_e64 v86, 0, 32, s[42:43]
	v_ldexp_f32 v84, v84, v86
	v_log_f32_e32 v84, v84
	s_nop 0
	v_mul_f32_e32 v86, 0x3f317217, v84
	v_fma_f32 v86, v84, s81, -v86
	v_fmac_f32_e32 v86, 0x3377d1cf, v84
	v_fmac_f32_e32 v86, 0x3f317217, v84
	v_cmp_lt_f32_e64 s[44:45], |v84|, s71
	s_nop 1
	v_cndmask_b32_e64 v84, v84, v86, s[44:45]
	v_cndmask_b32_e64 v86, 0, v236, s[42:43]
	v_sub_f32_e32 v84, v84, v86
	v_sub_f32_e32 v84, v85, v84
	s_lshl_b64 s[42:43], s[4:5], 12
	v_fmamk_f32 v157, v84, 0x3d800000, v155
	v_lshl_add_u64 v[84:85], v[12:13], 0, s[42:43]
	global_load_ushort v86, v[84:85], off
	s_waitcnt vmcnt(0)
	v_lshlrev_b32_e32 v158, 16, v86
	v_mov_b32_e32 v86, s21
	ds_read_b128 v[162:165], v86
	ds_read_b128 v[166:169], v86 offset:16
	ds_read_b128 v[170:173], v86 offset:32
	ds_read_b128 v[174:177], v86 offset:48
	s_waitcnt lgkmcnt(3)
	v_fma_f32 v135, v133, v162, v134
	v_fmac_f32_e32 v135, v126, v163
	v_fmac_f32_e32 v135, v127, v164
	v_fmac_f32_e32 v135, v128, v165
	s_waitcnt lgkmcnt(2)
	v_fmac_f32_e32 v135, v129, v166
	v_fmac_f32_e32 v135, v130, v167
	v_fmac_f32_e32 v135, v131, v168
	v_fmac_f32_e32 v135, v132, v169
	s_waitcnt lgkmcnt(1)
	v_pk_mul_f32 v[86:87], v[0:1], v[170:171]
	s_nop 0
	v_add_f32_e32 v86, v135, v86
	v_add_f32_e32 v135, v86, v87
	v_pk_mul_f32 v[86:87], v[2:3], v[172:173]
	v_lshl_add_u32 v173, s3, 13, v93
	v_add_f32_e32 v86, v135, v86
	v_add_f32_e32 v135, v86, v87
	s_waitcnt lgkmcnt(0)
	v_pk_mul_f32 v[86:87], v[4:5], v[174:175]
	s_nop 0
	v_add_f32_e32 v86, v135, v86
	v_add_f32_e32 v135, v86, v87
	v_pk_mul_f32 v[86:87], v[6:7], v[176:177]
	s_nop 0
	v_add_f32_e32 v86, v135, v86
	v_add_f32_e32 v86, v86, v87
	v_min_f32_e32 v87, 0, v86
	v_mul_f32_e64 v86, |v86|, s65
	v_exp_f32_e32 v86, v86
	s_nop 0
	v_add_f32_e32 v86, 1.0, v86
	v_cmp_gt_f32_e64 s[42:43], s80, v86
	s_nop 1
	v_cndmask_b32_e64 v135, 0, 32, s[42:43]
	v_ldexp_f32 v86, v86, v135
	v_log_f32_e32 v86, v86
	s_nop 0
	v_mul_f32_e32 v135, 0x3f317217, v86
	v_fma_f32 v135, v86, s81, -v135
	v_fmac_f32_e32 v135, 0x3377d1cf, v86
	v_fmac_f32_e32 v135, 0x3f317217, v86
	v_cmp_lt_f32_e64 s[44:45], |v86|, s71
	s_nop 1
	v_cndmask_b32_e64 v86, v86, v135, s[44:45]
	v_cndmask_b32_e64 v135, 0, v236, s[42:43]
	s_or_b32 s42, s20, s72
	v_sub_f32_e32 v86, v86, v135
	s_ashr_i32 s43, s42, 31
	v_sub_f32_e32 v86, v87, v86
	s_lshl_b64 s[44:45], s[42:43], 12
	v_fmamk_f32 v135, v86, 0x3d800000, v157
	v_lshl_add_u64 v[86:87], v[12:13], 0, s[44:45]
	global_load_ushort v159, v[86:87], off
	global_load_ushort v174, v[60:61], off offset:2048
	global_load_ushort v176, v[14:15], off offset:2048
	global_load_ushort v175, v[56:57], off offset:2048
	global_load_ushort v177, v[62:63], off offset:2048
	global_load_ushort v169, v[64:65], off offset:2048
	global_load_ushort v171, v[68:69], off offset:2048
	global_load_ushort v170, v[66:67], off offset:2048
	global_load_ushort v172, v[70:71], off offset:2048
	global_load_ushort v165, v[72:73], off offset:2048
	global_load_ushort v167, v[76:77], off offset:2048
	global_load_ushort v166, v[74:75], off offset:2048
	global_load_ushort v168, v[78:79], off offset:2048
	global_load_ushort v161, v[80:81], off offset:2048
	global_load_ushort v163, v[84:85], off offset:2048
	global_load_ushort v162, v[82:83], off offset:2048
	global_load_ushort v164, v[86:87], off offset:2048
	s_lshl_b64 s[44:45], s[50:51], 11
	v_lshl_add_u64 v[14:15], v[8:9], 0, s[44:45]
	v_mul_f32_e32 v15, 0x3fb8aa3b, v59
	v_exp_f32_e32 v15, v15
	v_mul_f32_e32 v14, 0x3d800000, v88
	s_lshl_b64 s[44:45], s[74:75], 11
	v_lshl_add_u64 v[56:57], v[8:9], 0, s[44:45]
	v_mul_f32_e32 v15, v14, v15
	v_cvt_pk_bf16_f32 v178, v15, s0
	v_mul_f32_e32 v56, 0x3fb8aa3b, v89
	v_exp_f32_e32 v56, v56
	v_mul_f32_e32 v15, 0x3d800000, v90
	s_lshl_b64 s[44:45], s[76:77], 11
	v_mul_f32_e32 v14, 0xbfb8aa3b, v59
	v_mul_f32_e32 v15, v15, v56
	v_mul_f32_e32 v56, 0xbfb8aa3b, v89
	v_exp_f32_e32 v59, v56
	v_cvt_pk_bf16_f32 v180, v15, s0
	v_lshl_add_u64 v[56:57], v[8:9], 0, s[44:45]
	v_mul_f32_e32 v56, 0x3fb8aa3b, v91
	v_exp_f32_e32 v56, v56
	v_mul_f32_e32 v15, 0x3d800000, v136
	s_lshl_b64 s[44:45], s[82:83], 11
	v_mul_f32_e32 v62, 0x3fb8aa3b, v143
	v_mul_f32_e32 v56, v15, v56
	v_cvt_pk_bf16_f32 v182, v56, s0
	v_lshl_add_u64 v[56:57], v[8:9], 0, s[44:45]
	v_mul_f32_e32 v57, 0x3fb8aa3b, v137
	v_exp_f32_e32 v57, v57
	v_mul_f32_e32 v56, 0x3d800000, v138
	s_lshl_b64 s[44:45], s[96:97], 11
	v_lshl_add_u64 v[60:61], v[8:9], 0, s[44:45]
	v_mul_f32_e32 v57, v56, v57
	v_cvt_pk_bf16_f32 v183, v57, s0
	v_mul_f32_e32 v60, 0x3fb8aa3b, v139
	v_exp_f32_e32 v60, v60
	v_mul_f32_e32 v61, 0x3fb8aa3b, v141
	v_exp_f32_e32 v61, v61
	v_mul_f32_e32 v57, 0x3d800000, v140
	v_mul_f32_e32 v57, v57, v60
	v_exp_f32_e32 v62, v62
	v_cvt_pk_bf16_f32 v138, v57, s0
	v_mul_f32_e32 v57, 0x3d800000, v142
	v_mul_f32_e32 v63, 0x3fb8aa3b, v145
	v_mul_f32_e32 v61, v57, v61
	v_exp_f32_e32 v63, v63
	v_mul_f32_e32 v57, 0xbfb8aa3b, v141
	v_cvt_pk_bf16_f32 v141, v61, s0
	v_mul_f32_e32 v61, 0x3d800000, v144
	v_mul_f32_e32 v64, 0x3fb8aa3b, v147
	v_mul_f32_e32 v15, 0xbfb8aa3b, v91
	v_mul_f32_e32 v62, v61, v62
	v_exp_f32_e32 v64, v64
	v_exp_f32_e32 v14, v14
	v_exp_f32_e32 v15, v15
	v_cvt_pk_bf16_f32 v186, v62, s0
	v_mul_f32_e32 v62, 0x3d800000, v146
	v_mul_f32_e32 v65, 0x3fb8aa3b, v149
	v_mul_f32_e32 v63, v62, v63
	v_exp_f32_e32 v65, v65
	v_cvt_pk_bf16_f32 v193, v63, s0
	v_mul_f32_e32 v63, 0x3d800000, v148
	v_mul_f32_e32 v68, 0x3fb8aa3b, v151
	v_mul_f32_e32 v63, v63, v64
	v_exp_f32_e32 v68, v68
	s_waitcnt vmcnt(14)
	v_lshlrev_b32_e32 v194, 16, v176
	v_lshlrev_b32_e32 v195, 16, v174
	s_waitcnt vmcnt(12)
	v_lshlrev_b32_e32 v177, 16, v177
	v_lshlrev_b32_e32 v176, 16, v175
	v_mul_f32_e32 v56, 0xbfb8aa3b, v137
	v_mul_f32_e32 v61, 0xbfb8aa3b, v143
	v_cvt_pk_bf16_f32 v143, v63, s0
	v_mul_f32_e32 v63, 0x3d800000, v150
	v_mul_f32_e32 v69, 0x3fb8aa3b, v153
	v_pk_mul_f32 v[58:59], v[58:59], v[194:195]
	v_pk_mul_f32 v[14:15], v[14:15], v[176:177]
	v_exp_f32_e32 v56, v56
	v_mul_f32_e32 v60, 0xbfb8aa3b, v139
	v_exp_f32_e32 v57, v57
	v_mul_f32_e32 v65, v63, v65
	v_exp_f32_e32 v69, v69
	v_cvt_pk_bf16_f32 v58, v58, v59
	v_cvt_pk_bf16_f32 v14, v14, v15
	ds_write_b16 v173, v160
	v_lshl_add_u32 v160, s66, 9, v111
	v_exp_f32_e32 v60, v60
	v_lshl_add_u64 v[66:67], v[8:9], 0, s[8:9]
	s_lshl_b64 s[8:9], s[46:47], 11
	v_exp_f32_e32 v61, v61
	v_cvt_pk_bf16_f32 v146, v65, s0
	v_mul_f32_e32 v65, 0x3d800000, v152
	v_mul_f32_e32 v72, 0x3fb8aa3b, v155
	v_lshrrev_b32_e32 v15, 16, v58
	v_lshrrev_b32_e32 v59, 16, v14
	v_lshl_add_u64 v[70:71], v[8:9], 0, s[8:9]
	s_lshl_b64 s[8:9], s[60:61], 11
	s_lshl_b64 s[0:1], s[0:1], 11
	v_mul_f32_e32 v68, v65, v68
	v_exp_f32_e32 v72, v72
	ds_write_b16 v173, v58 offset:32768
	ds_write_b16 v160, v178
	ds_write_b16 v160, v14 offset:32768
	ds_write_b16 v179, v180
	ds_write_b16 v179, v15 offset:32768
	ds_write_b16 v181, v182
	ds_write_b16 v181, v59 offset:32768
	v_and_b32_e32 v59, 0xffff0000, v14
	v_lshlrev_b32_e32 v14, 16, v14
	v_lshl_add_u32 v137, s69, 9, v114
	v_lshl_add_u64 v[76:77], v[8:9], 0, s[8:9]
	s_lshl_b64 s[8:9], s[62:63], 11
	v_cvt_pk_bf16_f32 v150, v68, s0
	v_mul_f32_e32 v68, 0x3d800000, v154
	v_mul_f32_e32 v73, 0x3fb8aa3b, v157
	v_or_b32_e32 v59, v59, v15
	v_or_b32_sdwa v58, v14, v58 dst_sel:DWORD dst_unused:UNUSED_PAD src0_sel:DWORD src1_sel:WORD_0
	s_waitcnt vmcnt(10)
	v_lshlrev_b32_e32 v15, 16, v171
	v_lshlrev_b32_e32 v14, 16, v169
	v_mul_f32_e32 v62, 0xbfb8aa3b, v145
	v_lshl_add_u64 v[80:81], v[8:9], 0, s[8:9]
	v_mul_f32_e32 v63, 0xbfb8aa3b, v149
	v_lshl_add_u64 v[78:79], v[8:9], 0, s[0:1]
	s_lshl_b64 s[0:1], s[6:7], 11
	v_mul_f32_e32 v69, v68, v69
	v_exp_f32_e32 v73, v73
	ds_write_b16 v137, v183
	s_waitcnt vmcnt(8)
	v_lshlrev_b32_e32 v67, 16, v172
	v_lshlrev_b32_e32 v66, 16, v170
	v_pk_mul_f32 v[14:15], v[56:57], v[14:15]
	v_exp_f32_e32 v62, v62
	v_mul_f32_e32 v64, 0xbfb8aa3b, v147
	v_exp_f32_e32 v63, v63
	v_mul_f32_e32 v65, 0xbfb8aa3b, v151
	v_cvt_pk_bf16_f32 v154, v69, s0
	v_mul_f32_e32 v69, 0x3d800000, v156
	v_mul_f32_e32 v90, 0x3fb8aa3b, v135
	v_cvt_pk_bf16_f32 v56, v14, v15
	v_pk_mul_f32 v[14:15], v[60:61], v[66:67]
	v_exp_f32_e32 v64, v64
	v_exp_f32_e32 v65, v65
	v_lshl_add_u64 v[84:85], v[8:9], 0, s[0:1]
	s_lshl_b64 s[0:1], s[54:55], 11
	v_mul_f32_e32 v69, v69, v72
	v_exp_f32_e32 v136, v90
	v_cvt_pk_bf16_f32 v14, v14, v15
	v_cvt_pk_bf16_f32 v148, v69, s0
	v_mul_f32_e32 v69, 0x3d800000, v158
	v_lshrrev_b32_e32 v15, 16, v14
	v_lshlrev_b32_e32 v159, 16, v159
	v_lshl_add_u32 v139, s10, 9, v115
	v_lshl_add_u32 v142, s11, 9, v116
	v_lshl_add_u32 v140, s13, 9, v118
	v_lshl_add_u64 v[88:89], v[8:9], 0, s[0:1]
	s_lshl_b64 s[0:1], s[48:49], 11
	v_mul_f32_e32 v73, v69, v73
	v_lshrrev_b32_e32 v57, 16, v56
	v_and_b32_e32 v60, 0xffff0000, v14
	v_lshlrev_b32_e32 v66, 16, v14
	ds_write_b16 v137, v56 offset:32768
	ds_write_b16 v139, v138
	ds_write_b16 v139, v14 offset:32768
	ds_write_b16 v142, v141
	ds_write_b16 v142, v57 offset:32768
	ds_write_b16 v192, v186
	ds_write_b16 v192, v15 offset:32768
	ds_write_b16 v140, v193
	s_waitcnt vmcnt(6)
	v_lshlrev_b32_e32 v15, 16, v167
	v_lshlrev_b32_e32 v14, 16, v165
	v_mul_f32_e32 v68, 0xbfb8aa3b, v153
	v_mul_f32_e32 v69, 0xbfb8aa3b, v157
	v_cvt_pk_bf16_f32 v152, v73, s0
	v_mul_f32_e32 v73, 0x3d800000, v159
	v_or_b32_e32 v61, v60, v57
	v_or_b32_sdwa v60, v66, v56 dst_sel:DWORD dst_unused:UNUSED_PAD src0_sel:DWORD src1_sel:WORD_0
	s_waitcnt vmcnt(4)
	v_lshlrev_b32_e32 v57, 16, v168
	v_lshlrev_b32_e32 v56, 16, v166
	v_pk_mul_f32 v[14:15], v[62:63], v[14:15]
	v_exp_f32_e32 v68, v68
	v_mul_f32_e32 v72, 0xbfb8aa3b, v155
	v_exp_f32_e32 v69, v69
	v_mul_f32_e32 v90, v73, v136
	v_mul_f32_e32 v73, 0xbfb8aa3b, v135
	v_cvt_pk_bf16_f32 v62, v14, v15
	v_pk_mul_f32 v[14:15], v[64:65], v[56:57]
	s_lshl_b64 s[8:9], s[56:57], 11
	v_exp_f32_e32 v72, v72
	v_exp_f32_e32 v73, v73
	v_cvt_pk_bf16_f32 v14, v14, v15
	v_lshl_add_u64 v[74:75], v[8:9], 0, s[8:9]
	v_lshl_add_u64 v[82:83], v[8:9], 0, s[0:1]
	s_lshl_b64 s[0:1], s[4:5], 11
	v_lshrrev_b32_e32 v15, 16, v14
	v_lshl_add_u32 v144, s14, 9, v119
	v_lshl_add_u32 v147, s15, 9, v120
	v_lshl_add_u32 v151, s16, 9, v121
	v_lshl_add_u32 v145, s17, 9, v122
	v_lshl_add_u64 v[86:87], v[8:9], 0, s[0:1]
	v_cvt_pk_bf16_f32 v155, v90, s0
	s_lshl_b64 s[0:1], s[42:43], 11
	s_lshl_b32 s66, s3, 10
	v_lshrrev_b32_e32 v63, 16, v62
	v_and_b32_e32 v56, 0xffff0000, v14
	v_lshlrev_b32_e32 v64, 16, v14
	ds_write_b16 v140, v62 offset:32768
	ds_write_b16 v144, v143
	ds_write_b16 v144, v14 offset:32768
	ds_write_b16 v147, v146
	ds_write_b16 v147, v63 offset:32768
	ds_write_b16 v151, v150
	ds_write_b16 v151, v15 offset:32768
	ds_write_b16 v145, v154
	s_waitcnt vmcnt(2)
	v_lshlrev_b32_e32 v15, 16, v163
	v_lshlrev_b32_e32 v14, 16, v161
	v_lshl_add_u64 v[90:91], v[8:9], 0, s[0:1]
	v_lshl_add_u64 v[158:159], v[10:11], 0, s[66:67]
	global_store_dwordx4 v[158:159], v[58:61], off
	v_pk_mul_f32 v[14:15], v[68:69], v[14:15]
	v_or_b32_e32 v57, v56, v63
	s_waitcnt vmcnt(1)
	v_lshlrev_b32_e32 v59, 16, v164
	v_lshlrev_b32_e32 v58, 16, v162
	v_cvt_pk_bf16_f32 v60, v14, v15
	v_pk_mul_f32 v[14:15], v[72:73], v[58:59]
	v_or_b32_sdwa v56, v64, v62 dst_sel:DWORD dst_unused:UNUSED_PAD src0_sel:DWORD src1_sel:WORD_0
	v_cvt_pk_bf16_f32 v14, v14, v15
	v_lshrrev_b32_e32 v61, 16, v60
	v_and_b32_e32 v58, 0xffff0000, v14
	v_lshlrev_b32_e32 v62, 16, v14
	v_or_b32_e32 v59, v58, v61
	v_or_b32_sdwa v58, v62, v60 dst_sel:DWORD dst_unused:UNUSED_PAD src0_sel:DWORD src1_sel:WORD_0
	s_add_i32 s3, s3, 1
	v_lshl_add_u32 v149, s18, 9, v123
	v_lshl_add_u32 v153, s19, 9, v124
	v_lshl_add_u32 v156, s20, 9, v125
	v_lshrrev_b32_e32 v15, 16, v14
	ds_write_b16 v145, v60 offset:32768
	ds_write_b16 v149, v148
	ds_write_b16 v149, v14 offset:32768
	ds_write_b16 v153, v152
	ds_write_b16 v153, v61 offset:32768
	ds_write_b16 v156, v155
	ds_write_b16 v156, v15 offset:32768
	global_store_dwordx4 v[158:159], v[56:59], off offset:512
	s_cmp_eq_u32 s3, 4
	s_nop 0
	v_mov_b32_e32 v58, v135
	s_cbranch_scc0 .LBB0_224
	s_ashr_i32 s3, s2, 31
	s_lshl_b64 s[0:1], s[2:3], 10
	v_lshl_add_u64 v[0:1], v[22:23], 0, s[0:1]
	global_store_dword v[0:1], v136, off
	v_mov_b32_e32 v0, 0
	v_mov_b32_e32 v1, 0
	v_mov_b32_e32 v2, 0
	v_mov_b32_e32 v3, 0
	v_mov_b32_e32 v4, 0
	v_mov_b32_e32 v5, 0
	v_mov_b32_e32 v6, 0
	v_mov_b32_e32 v7, 0
	v_mov_b32_e32 v8, 0
	v_mov_b32_e32 v9, 0
	v_mov_b32_e32 v10, 0
	v_mov_b32_e32 v11, 0
	v_mov_b32_e32 v12, 0
	v_mov_b32_e32 v13, 0
	v_mov_b32_e32 v14, 0
	v_mov_b32_e32 v15, 0
	s_waitcnt lgkmcnt(0)
	s_barrier
	s_and_b32 s4, s2, 3
	s_lshl_b32 s4, s4, 22
	s_lshr_b32 s5, s2, 2
	s_lshl_b32 s5, s5, 15
	s_or_b32 s4, s4, s5
	s_add_u32 s4, s4, 0xe800000
	v_lshlrev_b32_e32 v196, 4, v16
	v_mov_b32_e32 v197, 0
	v_add_u32_e32 v196, s4, v196
	v_lshl_add_u64 v[196:197], v[184:185], 0, v[196:197]
	v_and_b32_e32 v198, 31, v16
	v_bfe_u32 v199, v16, 5, 1
	v_lshrrev_b32_e32 v200, 6, v16
	v_lshlrev_b32_e32 v201, 9, v198
	v_lshl_add_u32 v201, v199, 3, v201
	v_and_b32_e32 v202, 15, v198
	v_lshlrev_b32_e32 v200, 1, v200
	v_xor_b32_e32 v203, v200, v202
	v_lshl_add_u32 v203, v203, 4, v201
	v_xor_b32_e32 v204, 16, v203
	ds_read_b64 v[208:209], v203
	ds_read_b64 v[210:211], v204
	s_waitcnt lgkmcnt(0)
	global_store_dwordx4 v[196:197], v[208:211], off
	v_lshl_add_u64 v[196:197], v[196:197], 0, s[86:87]
	ds_read_b64 v[212:213], v203 offset:16384
	ds_read_b64 v[214:215], v204 offset:16384
	s_waitcnt lgkmcnt(0)
	global_store_dwordx4 v[196:197], v[212:215], off
	v_lshl_add_u64 v[196:197], v[196:197], 0, s[86:87]
	v_add_u32_e32 v205, 8, v200
	v_xor_b32_e32 v203, v205, v202
	v_lshl_add_u32 v203, v203, 4, v201
	v_xor_b32_e32 v204, 16, v203
	ds_read_b64 v[208:209], v203
	ds_read_b64 v[210:211], v204
	s_waitcnt lgkmcnt(0)
	global_store_dwordx4 v[196:197], v[208:211], off
	v_lshl_add_u64 v[196:197], v[196:197], 0, s[86:87]
	ds_read_b64 v[212:213], v203 offset:16384
	ds_read_b64 v[214:215], v204 offset:16384
	s_waitcnt lgkmcnt(0)
	global_store_dwordx4 v[196:197], v[212:215], off
	v_lshl_add_u64 v[196:197], v[196:197], 0, s[86:87]
	v_add_u32_e32 v205, 16, v200
	v_xor_b32_e32 v203, v205, v202
	v_lshl_add_u32 v203, v203, 4, v201
	v_xor_b32_e32 v204, 16, v203
	ds_read_b64 v[208:209], v203
	ds_read_b64 v[210:211], v204
	s_waitcnt lgkmcnt(0)
	global_store_dwordx4 v[196:197], v[208:211], off
	v_lshl_add_u64 v[196:197], v[196:197], 0, s[86:87]
	ds_read_b64 v[212:213], v203 offset:16384
	ds_read_b64 v[214:215], v204 offset:16384
	s_waitcnt lgkmcnt(0)
	global_store_dwordx4 v[196:197], v[212:215], off
	v_lshl_add_u64 v[196:197], v[196:197], 0, s[86:87]
	v_add_u32_e32 v205, 24, v200
	v_xor_b32_e32 v203, v205, v202
	v_lshl_add_u32 v203, v203, 4, v201
	v_xor_b32_e32 v204, 16, v203
	ds_read_b64 v[208:209], v203
	ds_read_b64 v[210:211], v204
	s_waitcnt lgkmcnt(0)
	global_store_dwordx4 v[196:197], v[208:211], off
	v_lshl_add_u64 v[196:197], v[196:197], 0, s[86:87]
	ds_read_b64 v[212:213], v203 offset:16384
	ds_read_b64 v[214:215], v204 offset:16384
	s_waitcnt lgkmcnt(0)
	global_store_dwordx4 v[196:197], v[212:215], off
	s_mov_b64 s[0:1], exec
	v_readlane_b32 s4, v255, 19
	v_readlane_b32 s5, v255, 20
	s_and_b64 s[4:5], s[0:1], s[4:5]
	s_mov_b64 exec, s[4:5]
	s_cbranch_execz .LBB0_222
	v_add_u32_e32 v0, v17, v95
	ds_read_b128 v[0:3], v0
	v_add_u32_e32 v4, v94, v95
	ds_read_b128 v[4:7], v4 offset:32768
	v_add_u32_e32 v56, v17, v96
	ds_read_b128 v[56:59], v56
	v_add_u32_e32 v60, v94, v96
	ds_read_b128 v[60:63], v60 offset:32768
	v_add_u32_e32 v64, v17, v97
	s_waitcnt lgkmcnt(2)
	v_mfma_f32_32x32x16_bf16 v[0:15], v[0:3], v[4:7], 0
	s_waitcnt lgkmcnt(0)
	v_mfma_f32_32x32x16_bf16 v[0:15], v[56:59], v[60:63], v[0:15]
	ds_read_b128 v[56:59], v64
	v_add_u32_e32 v60, v94, v97
	ds_read_b128 v[60:63], v60 offset:32768
	v_add_u32_e32 v64, v17, v98
	s_waitcnt lgkmcnt(0)
	v_mfma_f32_32x32x16_bf16 v[0:15], v[56:59], v[60:63], v[0:15]
	ds_read_b128 v[56:59], v64
	v_add_u32_e32 v60, v94, v98
	ds_read_b128 v[60:63], v60 offset:32768
	v_add_u32_e32 v64, v17, v99
	s_waitcnt lgkmcnt(0)
	v_mfma_f32_32x32x16_bf16 v[0:15], v[56:59], v[60:63], v[0:15]
	ds_read_b128 v[56:59], v64
	v_add_u32_e32 v60, v94, v99
	ds_read_b128 v[60:63], v60 offset:32768
	v_add_u32_e32 v64, v17, v100
	s_waitcnt lgkmcnt(0)
	v_mfma_f32_32x32x16_bf16 v[0:15], v[56:59], v[60:63], v[0:15]
	ds_read_b128 v[56:59], v64
	v_add_u32_e32 v60, v94, v100
	ds_read_b128 v[60:63], v60 offset:32768
	v_add_u32_e32 v64, v17, v101
	s_waitcnt lgkmcnt(0)
	v_mfma_f32_32x32x16_bf16 v[0:15], v[56:59], v[60:63], v[0:15]
	ds_read_b128 v[56:59], v64
	v_add_u32_e32 v60, v94, v101
	ds_read_b128 v[60:63], v60 offset:32768
	v_add_u32_e32 v64, v17, v102
	s_waitcnt lgkmcnt(0)
	v_mfma_f32_32x32x16_bf16 v[0:15], v[56:59], v[60:63], v[0:15]
	ds_read_b128 v[56:59], v64
	v_add_u32_e32 v60, v94, v102
	ds_read_b128 v[60:63], v60 offset:32768
	v_add_u32_e32 v64, v17, v103
	s_waitcnt lgkmcnt(0)
	v_mfma_f32_32x32x16_bf16 v[0:15], v[56:59], v[60:63], v[0:15]
	ds_read_b128 v[56:59], v64
	v_add_u32_e32 v60, v94, v103
	ds_read_b128 v[60:63], v60 offset:32768
	v_add_u32_e32 v64, v17, v104
	s_waitcnt lgkmcnt(0)
	v_mfma_f32_32x32x16_bf16 v[0:15], v[56:59], v[60:63], v[0:15]
	ds_read_b128 v[56:59], v64
	v_add_u32_e32 v60, v94, v104
	ds_read_b128 v[60:63], v60 offset:32768
	v_add_u32_e32 v64, v17, v105
	s_waitcnt lgkmcnt(0)
	v_mfma_f32_32x32x16_bf16 v[0:15], v[56:59], v[60:63], v[0:15]
	ds_read_b128 v[56:59], v64
	v_add_u32_e32 v60, v94, v105
	ds_read_b128 v[60:63], v60 offset:32768
	v_add_u32_e32 v64, v17, v106
	s_waitcnt lgkmcnt(0)
	v_mfma_f32_32x32x16_bf16 v[0:15], v[56:59], v[60:63], v[0:15]
	ds_read_b128 v[56:59], v64
	v_add_u32_e32 v60, v94, v106
	ds_read_b128 v[60:63], v60 offset:32768
	v_add_u32_e32 v64, v17, v107
	s_waitcnt lgkmcnt(0)
	v_mfma_f32_32x32x16_bf16 v[0:15], v[56:59], v[60:63], v[0:15]
	ds_read_b128 v[56:59], v64
	v_add_u32_e32 v60, v94, v107
	ds_read_b128 v[60:63], v60 offset:32768
	v_add_u32_e32 v64, v17, v108
	s_waitcnt lgkmcnt(0)
	v_mfma_f32_32x32x16_bf16 v[0:15], v[56:59], v[60:63], v[0:15]
	ds_read_b128 v[56:59], v64
	v_add_u32_e32 v60, v94, v108
	ds_read_b128 v[60:63], v60 offset:32768
	v_add_u32_e32 v64, v17, v109
	s_waitcnt lgkmcnt(0)
	v_mfma_f32_32x32x16_bf16 v[0:15], v[56:59], v[60:63], v[0:15]
	ds_read_b128 v[56:59], v64
	v_add_u32_e32 v60, v94, v109
	ds_read_b128 v[60:63], v60 offset:32768
	v_add_u32_e32 v64, v17, v110
	s_waitcnt lgkmcnt(0)
	v_mfma_f32_32x32x16_bf16 v[0:15], v[56:59], v[60:63], v[0:15]
	ds_read_b128 v[56:59], v64
	v_add_u32_e32 v60, v94, v110
	ds_read_b128 v[60:63], v60 offset:32768
	s_waitcnt lgkmcnt(0)
	v_mfma_f32_32x32x16_bf16 v[0:15], v[56:59], v[60:63], v[0:15]
	s_branch .LBB0_222

.LBB0_239:
	v_add_u32_e32 v186, v198, v200
	ds_read_b128 v[206:209], v186 offset:24576
	ds_read_b128 v[210:213], v186 offset:26624
	ds_read_b128 v[214:217], v186 offset:28672
	ds_read_b128 v[238:241], v186 offset:30720
	v_add_u32_e32 v203, v201, v200
	ds_read_b128 v[244:247], v203 offset:40960
	ds_read_b128 v[248:251], v203 offset:43008
	v_mfma_f32_32x32x16_bf16 v[112:127], v[148:151], v[136:139], v[112:127]
	v_add_u32_e32 v204, v198, v202
	v_add_u32_e32 v205, v201, v202
	v_mfma_f32_32x32x16_bf16 v[96:111], v[148:151], v[132:135], v[96:111]
	v_mfma_f32_32x32x16_bf16 v[80:95], v[144:147], v[136:139], v[80:95]
	v_mfma_f32_32x32x16_bf16 v[64:79], v[144:147], v[132:135], v[64:79]
	v_mfma_f32_32x32x16_bf16 v[48:63], v[140:143], v[136:139], v[48:63]
	v_mfma_f32_32x32x16_bf16 v[32:47], v[140:143], v[132:135], v[32:47]
	v_mfma_f32_32x32x16_bf16 v[16:31], v[128:131], v[136:139], v[16:31]
	v_mfma_f32_32x32x16_bf16 v[0:15], v[128:131], v[132:135], v[0:15]
	ds_read_b128 v[128:131], v204 offset:24576
	ds_read_b128 v[132:135], v204 offset:26624
	ds_read_b128 v[136:139], v204 offset:28672
	ds_read_b128 v[140:143], v204 offset:30720
	ds_read_b128 v[144:147], v205 offset:40960
	ds_read_b128 v[148:151], v205 offset:43008
	s_waitcnt lgkmcnt(7)
	v_mfma_f32_32x32x16_bf16 v[112:127], v[206:209], v[244:247], v[112:127]
	s_waitcnt lgkmcnt(6)
	v_mfma_f32_32x32x16_bf16 v[96:111], v[206:209], v[248:251], v[96:111]
	v_mfma_f32_32x32x16_bf16 v[80:95], v[210:213], v[244:247], v[80:95]
	v_mfma_f32_32x32x16_bf16 v[64:79], v[210:213], v[248:251], v[64:79]
	v_mfma_f32_32x32x16_bf16 v[48:63], v[214:217], v[244:247], v[48:63]
	v_mfma_f32_32x32x16_bf16 v[32:47], v[214:217], v[248:251], v[32:47]
	v_mfma_f32_32x32x16_bf16 v[16:31], v[238:241], v[244:247], v[16:31]
	v_mfma_f32_32x32x16_bf16 v[0:15], v[238:241], v[248:251], v[0:15]
	s_waitcnt vmcnt(2)
	ds_write_b128 v199, v[164:167] offset:12288
	v_lshl_add_u64 v[164:165], v[196:197], 0, s[0:1]
	ds_write_b128 v199, v[152:155]
	v_add_co_u32_e32 v152, vcc, s92, v164
	ds_write_b128 v199, v[156:159] offset:4096
	s_nop 0
	v_addc_co_u32_e32 v153, vcc, 0, v165, vcc
	v_add_co_u32_e32 v156, vcc, s93, v164
	ds_write_b128 v199, v[160:163] offset:8192
	s_nop 0
	v_addc_co_u32_e32 v157, vcc, 0, v165, vcc
	v_add_co_u32_e32 v160, vcc, s88, v164
	s_waitcnt vmcnt(0)
	ds_write_b128 v199, v[172:175] offset:20480
	v_addc_co_u32_e32 v161, vcc, 0, v165, vcc
	v_add_co_u32_e32 v164, vcc, s89, v164
	v_lshl_add_u64 v[172:173], v[178:179], 0, s[0:1]
	s_nop 0
	v_addc_co_u32_e32 v165, vcc, 0, v165, vcc
	ds_write_b128 v199, v[168:171] offset:16384
	global_load_dwordx4 v[168:171], v[172:173], off offset:192
	v_add_co_u32_e32 v172, vcc, s78, v172
	global_load_dwordx4 v[152:155], v[152:153], off offset:192
	s_nop 0
	v_addc_co_u32_e32 v173, vcc, 0, v173, vcc
	global_load_dwordx4 v[156:159], v[156:157], off offset:192
	s_nop 0
	global_load_dwordx4 v[160:163], v[160:161], off offset:192
	s_nop 0
	global_load_dwordx4 v[164:167], v[164:165], off offset:192
	s_nop 0
	global_load_dwordx4 v[172:175], v[172:173], off offset:192
	s_waitcnt lgkmcnt(0)
	s_barrier
	ds_read_b128 v[206:209], v186
	ds_read_b128 v[210:213], v186 offset:2048
	ds_read_b128 v[214:217], v186 offset:4096
	ds_read_b128 v[238:241], v186 offset:6144
	ds_read_b128 v[244:247], v203 offset:16384
	ds_read_b128 v[248:251], v203 offset:18432
	v_mfma_f32_32x32x16_bf16 v[112:127], v[128:131], v[144:147], v[112:127]
	v_mfma_f32_32x32x16_bf16 v[96:111], v[128:131], v[148:151], v[96:111]
	v_mfma_f32_32x32x16_bf16 v[80:95], v[132:135], v[144:147], v[80:95]
	v_mfma_f32_32x32x16_bf16 v[64:79], v[132:135], v[148:151], v[64:79]
	v_mfma_f32_32x32x16_bf16 v[48:63], v[136:139], v[144:147], v[48:63]
	v_mfma_f32_32x32x16_bf16 v[32:47], v[136:139], v[148:151], v[32:47]
	v_mfma_f32_32x32x16_bf16 v[16:31], v[140:143], v[144:147], v[16:31]
	v_mfma_f32_32x32x16_bf16 v[0:15], v[140:143], v[148:151], v[0:15]
	ds_read_b128 v[148:151], v204
	ds_read_b128 v[144:147], v204 offset:2048
	ds_read_b128 v[140:143], v204 offset:4096
	ds_read_b128 v[128:131], v204 offset:6144
	ds_read_b128 v[136:139], v205 offset:16384
	ds_read_b128 v[132:135], v205 offset:18432
	s_waitcnt lgkmcnt(7)
	v_mfma_f32_32x32x16_bf16 v[112:127], v[206:209], v[244:247], v[112:127]
	s_waitcnt lgkmcnt(6)
	v_mfma_f32_32x32x16_bf16 v[96:111], v[206:209], v[248:251], v[96:111]
	v_mfma_f32_32x32x16_bf16 v[80:95], v[210:213], v[244:247], v[80:95]
	v_mfma_f32_32x32x16_bf16 v[64:79], v[210:213], v[248:251], v[64:79]
	v_mfma_f32_32x32x16_bf16 v[48:63], v[214:217], v[244:247], v[48:63]
	v_mfma_f32_32x32x16_bf16 v[32:47], v[214:217], v[248:251], v[32:47]
	v_mfma_f32_32x32x16_bf16 v[16:31], v[238:241], v[244:247], v[16:31]
	v_mfma_f32_32x32x16_bf16 v[0:15], v[238:241], v[248:251], v[0:15]
	s_min_u32 s7, s6, 60
	s_lshl_b32 s66, s7, 6
	s_add_i32 s8, s66, 0xc0
	s_mov_b32 s9, s67
	s_waitcnt vmcnt(4)
	ds_write_b128 v199, v[152:155] offset:24576
	s_waitcnt vmcnt(3)
	ds_write_b128 v199, v[156:159] offset:28672
	s_waitcnt vmcnt(2)
	ds_write_b128 v199, v[160:163] offset:32768
	s_waitcnt vmcnt(1)
	ds_write_b128 v199, v[164:167] offset:36864
	ds_write_b128 v199, v[168:171] offset:40960
	s_waitcnt vmcnt(0)
	ds_write_b128 v199, v[172:175] offset:45056
	v_lshl_add_u64 v[152:153], v[176:177], 0, s[66:67]
	v_lshl_add_u64 v[156:157], v[180:181], 0, s[8:9]
	v_lshl_add_u64 v[160:161], v[182:183], 0, s[8:9]
	v_lshl_add_u64 v[164:165], v[192:193], 0, s[8:9]
	v_lshl_add_u64 v[168:169], v[178:179], 0, s[66:67]
	v_lshl_add_u64 v[172:173], v[194:195], 0, s[8:9]
	global_load_dwordx4 v[152:155], v[152:153], off offset:192
	s_add_i32 s6, s6, 2
	global_load_dwordx4 v[156:159], v[156:157], off
	s_add_u32 s0, s0, 0x80
	global_load_dwordx4 v[160:163], v[160:161], off
	s_addc_u32 s1, s1, 0
	global_load_dwordx4 v[164:167], v[164:165], off
	s_cmpk_lg_i32 s0, 0xf80
	global_load_dwordx4 v[168:171], v[168:169], off offset:192
	s_nop 0
	global_load_dwordx4 v[172:175], v[172:173], off
	s_waitcnt lgkmcnt(0)
	s_barrier
	s_cbranch_scc1 .LBB0_239
	s_waitcnt vmcnt(5)
	ds_read_b128 v[152:155], v186 offset:24576
	s_waitcnt vmcnt(4)
	ds_read_b128 v[156:159], v186 offset:26624
	s_waitcnt vmcnt(3)
	ds_read_b128 v[160:163], v186 offset:28672
	s_waitcnt vmcnt(2)
	ds_read_b128 v[164:167], v186 offset:30720
	s_waitcnt vmcnt(1)
	ds_read_b128 v[168:171], v203 offset:40960
	s_waitcnt vmcnt(0)
	ds_read_b128 v[172:175], v203 offset:43008
	v_mfma_f32_32x32x16_bf16 v[112:127], v[148:151], v[136:139], v[112:127]
	v_mfma_f32_32x32x16_bf16 v[96:111], v[148:151], v[132:135], v[96:111]
	v_mfma_f32_32x32x16_bf16 v[80:95], v[144:147], v[136:139], v[80:95]
	v_mfma_f32_32x32x16_bf16 v[64:79], v[144:147], v[132:135], v[64:79]
	v_mfma_f32_32x32x16_bf16 v[48:63], v[140:143], v[136:139], v[48:63]
	v_mfma_f32_32x32x16_bf16 v[32:47], v[140:143], v[132:135], v[32:47]
	v_mfma_f32_32x32x16_bf16 v[16:31], v[128:131], v[136:139], v[16:31]
	v_mfma_f32_32x32x16_bf16 v[0:15], v[128:131], v[132:135], v[0:15]
	ds_read_b128 v[128:131], v204 offset:24576
	ds_read_b128 v[132:135], v204 offset:26624
	ds_read_b128 v[136:139], v204 offset:28672
	ds_read_b128 v[140:143], v204 offset:30720
	ds_read_b128 v[144:147], v205 offset:40960
	ds_read_b128 v[148:151], v205 offset:43008
	s_waitcnt lgkmcnt(7)
	v_mfma_f32_32x32x16_bf16 v[112:127], v[152:155], v[168:171], v[112:127]
	s_waitcnt lgkmcnt(6)
	v_mfma_f32_32x32x16_bf16 v[96:111], v[152:155], v[172:175], v[96:111]
	v_mfma_f32_32x32x16_bf16 v[80:95], v[156:159], v[168:171], v[80:95]
	v_mfma_f32_32x32x16_bf16 v[64:79], v[156:159], v[172:175], v[64:79]
	v_mfma_f32_32x32x16_bf16 v[48:63], v[160:163], v[168:171], v[48:63]
	v_mfma_f32_32x32x16_bf16 v[32:47], v[160:163], v[172:175], v[32:47]
	v_mfma_f32_32x32x16_bf16 v[16:31], v[164:167], v[168:171], v[16:31]
	v_mfma_f32_32x32x16_bf16 v[0:15], v[164:167], v[172:175], v[0:15]
	s_waitcnt lgkmcnt(1)
	v_mfma_f32_32x32x16_bf16 v[112:127], v[128:131], v[144:147], v[112:127]
	s_waitcnt lgkmcnt(0)
	s_barrier
	s_mov_b32 s6, 0x9ffe000
	s_mov_b64 s[0:1], 0x8000
	v_mfma_f32_32x32x16_bf16 v[96:111], v[128:131], v[148:151], v[96:111]
	v_and_b32_e32 v152, 63, v189
	v_lshrrev_b32_e32 v153, 6, v189
	v_and_b32_e32 v154, 31, v152
	v_lshrrev_b32_e32 v155, 5, v152
	v_lshrrev_b32_e32 v156, 3, v154
	v_mfma_f32_32x32x16_bf16 v[80:95], v[132:135], v[144:147], v[80:95]
	v_and_b32_e32 v157, 7, v154
	v_lshlrev_b32_e32 v158, 14, v153
	v_lshl_add_u32 v159, v155, 9, v158
	v_lshl_add_u32 v159, v157, 1, v159
	v_lshl_add_u32 v160, v155, 2, v156
	v_mfma_f32_32x32x16_bf16 v[64:79], v[132:135], v[148:151], v[64:79]
	v_xor_b32_e32 v161, 4, v160
	v_lshl_add_u32 v160, v160, 4, v159
	v_lshl_add_u32 v161, v161, 4, v159
	v_lshrrev_b32_e32 v162, 3, v152
	v_and_b32_e32 v163, 7, v152
	v_mfma_f32_32x32x16_bf16 v[48:63], v[136:139], v[144:147], v[48:63]
	v_lshlrev_b32_e32 v164, 2, v155
	v_xor_b32_e32 v164, v163, v164
	v_lshl_add_u32 v165, v162, 7, v158
	v_lshl_add_u32 v166, v164, 4, v165
	v_lshrrev_b32_e32 v167, 1, v153
	v_mfma_f32_32x32x16_bf16 v[32:47], v[136:139], v[148:151], v[32:47]
	v_lshl_add_u32 v167, v167, 7, v162
	v_add_u32_e32 v167, s5, v167
	v_and_b32_e32 v168, 1, v153
	v_lshl_add_u32 v168, v168, 6, s4
	v_lshl_add_u32 v168, v163, 3, v168
	v_mfma_f32_32x32x16_bf16 v[16:31], v[140:143], v[144:147], v[16:31]
	v_lshlrev_b32_e32 v170, 12, v167
	v_lshl_add_u32 v170, v168, 1, v170
	v_add_u32_e32 v170, s6, v170
	v_mov_b32_e32 v171, 0
	v_lshl_add_u64 v[170:171], s[10:11], 0, v[170:171]
	v_mfma_f32_32x32x16_bf16 v[0:15], v[140:143], v[148:151], v[0:15]
	v_mul_f32_e32 v172, 0xbfb8aa3b, v112
	v_mul_f32_e32 v173, 0xbfb8aa3b, v113
	v_mul_f32_e32 v174, 0xbfb8aa3b, v114
	v_mul_f32_e32 v175, 0xbfb8aa3b, v115
	v_exp_f32_e32 v172, v172
	v_exp_f32_e32 v173, v173
	v_exp_f32_e32 v174, v174
	v_exp_f32_e32 v175, v175
	v_add_f32_e32 v172, 1.0, v172
	v_add_f32_e32 v173, 1.0, v173
	v_add_f32_e32 v174, 1.0, v174
	v_add_f32_e32 v175, 1.0, v175
	v_rcp_f32_e32 v172, v172
	v_rcp_f32_e32 v173, v173
	v_rcp_f32_e32 v174, v174
	v_rcp_f32_e32 v175, v175
	v_mul_f32_e32 v112, v112, v172
	v_mul_f32_e32 v113, v113, v173
	v_mul_f32_e32 v114, v114, v174
	v_mul_f32_e32 v115, v115, v175
	v_cvt_pk_bf16_f32 v112, v112, v113
	v_cvt_pk_bf16_f32 v114, v114, v115
	ds_write_b16 v160, v112 offset:0
	ds_write_b16_d16_hi v160, v112 offset:128
	ds_write_b16 v160, v114 offset:256
	ds_write_b16_d16_hi v160, v114 offset:384
	v_mul_f32_e32 v172, 0xbfb8aa3b, v116
	v_mul_f32_e32 v173, 0xbfb8aa3b, v117
	v_mul_f32_e32 v174, 0xbfb8aa3b, v118
	v_mul_f32_e32 v175, 0xbfb8aa3b, v119
	v_exp_f32_e32 v172, v172
	v_exp_f32_e32 v173, v173
	v_exp_f32_e32 v174, v174
	v_exp_f32_e32 v175, v175
	v_add_f32_e32 v172, 1.0, v172
	v_add_f32_e32 v173, 1.0, v173
	v_add_f32_e32 v174, 1.0, v174
	v_add_f32_e32 v175, 1.0, v175
	v_rcp_f32_e32 v172, v172
	v_rcp_f32_e32 v173, v173
	v_rcp_f32_e32 v174, v174
	v_rcp_f32_e32 v175, v175
	v_mul_f32_e32 v116, v116, v172
	v_mul_f32_e32 v117, v117, v173
	v_mul_f32_e32 v118, v118, v174
	v_mul_f32_e32 v119, v119, v175
	v_cvt_pk_bf16_f32 v116, v116, v117
	v_cvt_pk_bf16_f32 v118, v118, v119
	ds_write_b16 v160, v116 offset:1024
	ds_write_b16_d16_hi v160, v116 offset:1152
	ds_write_b16 v160, v118 offset:1280
	ds_write_b16_d16_hi v160, v118 offset:1408
	v_mul_f32_e32 v172, 0xbfb8aa3b, v120
	v_mul_f32_e32 v173, 0xbfb8aa3b, v121
	v_mul_f32_e32 v174, 0xbfb8aa3b, v122
	v_mul_f32_e32 v175, 0xbfb8aa3b, v123
	v_exp_f32_e32 v172, v172
	v_exp_f32_e32 v173, v173
	v_exp_f32_e32 v174, v174
	v_exp_f32_e32 v175, v175
	v_add_f32_e32 v172, 1.0, v172
	v_add_f32_e32 v173, 1.0, v173
	v_add_f32_e32 v174, 1.0, v174
	v_add_f32_e32 v175, 1.0, v175
	v_rcp_f32_e32 v172, v172
	v_rcp_f32_e32 v173, v173
	v_rcp_f32_e32 v174, v174
	v_rcp_f32_e32 v175, v175
	v_mul_f32_e32 v120, v120, v172
	v_mul_f32_e32 v121, v121, v173
	v_mul_f32_e32 v122, v122, v174
	v_mul_f32_e32 v123, v123, v175
	v_cvt_pk_bf16_f32 v120, v120, v121
	v_cvt_pk_bf16_f32 v122, v122, v123
	ds_write_b16 v160, v120 offset:2048
	ds_write_b16_d16_hi v160, v120 offset:2176
	ds_write_b16 v160, v122 offset:2304
	ds_write_b16_d16_hi v160, v122 offset:2432
	v_mul_f32_e32 v172, 0xbfb8aa3b, v124
	v_mul_f32_e32 v173, 0xbfb8aa3b, v125
	v_mul_f32_e32 v174, 0xbfb8aa3b, v126
	v_mul_f32_e32 v175, 0xbfb8aa3b, v127
	v_exp_f32_e32 v172, v172
	v_exp_f32_e32 v173, v173
	v_exp_f32_e32 v174, v174
	v_exp_f32_e32 v175, v175
	v_add_f32_e32 v172, 1.0, v172
	v_add_f32_e32 v173, 1.0, v173
	v_add_f32_e32 v174, 1.0, v174
	v_add_f32_e32 v175, 1.0, v175
	v_rcp_f32_e32 v172, v172
	v_rcp_f32_e32 v173, v173
	v_rcp_f32_e32 v174, v174
	v_rcp_f32_e32 v175, v175
	v_mul_f32_e32 v124, v124, v172
	v_mul_f32_e32 v125, v125, v173
	v_mul_f32_e32 v126, v126, v174
	v_mul_f32_e32 v127, v127, v175
	v_cvt_pk_bf16_f32 v124, v124, v125
	v_cvt_pk_bf16_f32 v126, v126, v127
	ds_write_b16 v160, v124 offset:3072
	ds_write_b16_d16_hi v160, v124 offset:3200
	ds_write_b16 v160, v126 offset:3328
	ds_write_b16_d16_hi v160, v126 offset:3456
	v_mul_f32_e32 v172, 0xbfb8aa3b, v96
	v_mul_f32_e32 v173, 0xbfb8aa3b, v97
	v_mul_f32_e32 v174, 0xbfb8aa3b, v98
	v_mul_f32_e32 v175, 0xbfb8aa3b, v99
	v_exp_f32_e32 v172, v172
	v_exp_f32_e32 v173, v173
	v_exp_f32_e32 v174, v174
	v_exp_f32_e32 v175, v175
	v_add_f32_e32 v172, 1.0, v172
	v_add_f32_e32 v173, 1.0, v173
	v_add_f32_e32 v174, 1.0, v174
	v_add_f32_e32 v175, 1.0, v175
	v_rcp_f32_e32 v172, v172
	v_rcp_f32_e32 v173, v173
	v_rcp_f32_e32 v174, v174
	v_rcp_f32_e32 v175, v175
	v_mul_f32_e32 v96, v96, v172
	v_mul_f32_e32 v97, v97, v173
	v_mul_f32_e32 v98, v98, v174
	v_mul_f32_e32 v99, v99, v175
	v_cvt_pk_bf16_f32 v96, v96, v97
	v_cvt_pk_bf16_f32 v98, v98, v99
	ds_write_b16 v161, v96 offset:0
	ds_write_b16_d16_hi v161, v96 offset:128
	ds_write_b16 v161, v98 offset:256
	ds_write_b16_d16_hi v161, v98 offset:384
	v_mul_f32_e32 v172, 0xbfb8aa3b, v100
	v_mul_f32_e32 v173, 0xbfb8aa3b, v101
	v_mul_f32_e32 v174, 0xbfb8aa3b, v102
	v_mul_f32_e32 v175, 0xbfb8aa3b, v103
	v_exp_f32_e32 v172, v172
	v_exp_f32_e32 v173, v173
	v_exp_f32_e32 v174, v174
	v_exp_f32_e32 v175, v175
	v_add_f32_e32 v172, 1.0, v172
	v_add_f32_e32 v173, 1.0, v173
	v_add_f32_e32 v174, 1.0, v174
	v_add_f32_e32 v175, 1.0, v175
	v_rcp_f32_e32 v172, v172
	v_rcp_f32_e32 v173, v173
	v_rcp_f32_e32 v174, v174
	v_rcp_f32_e32 v175, v175
	v_mul_f32_e32 v100, v100, v172
	v_mul_f32_e32 v101, v101, v173
	v_mul_f32_e32 v102, v102, v174
	v_mul_f32_e32 v103, v103, v175
	v_cvt_pk_bf16_f32 v100, v100, v101
	v_cvt_pk_bf16_f32 v102, v102, v103
	ds_write_b16 v161, v100 offset:1024
	ds_write_b16_d16_hi v161, v100 offset:1152
	ds_write_b16 v161, v102 offset:1280
	ds_write_b16_d16_hi v161, v102 offset:1408
	v_mul_f32_e32 v172, 0xbfb8aa3b, v104
	v_mul_f32_e32 v173, 0xbfb8aa3b, v105
	v_mul_f32_e32 v174, 0xbfb8aa3b, v106
	v_mul_f32_e32 v175, 0xbfb8aa3b, v107
	v_exp_f32_e32 v172, v172
	v_exp_f32_e32 v173, v173
	v_exp_f32_e32 v174, v174
	v_exp_f32_e32 v175, v175
	v_add_f32_e32 v172, 1.0, v172
	v_add_f32_e32 v173, 1.0, v173
	v_add_f32_e32 v174, 1.0, v174
	v_add_f32_e32 v175, 1.0, v175
	v_rcp_f32_e32 v172, v172
	v_rcp_f32_e32 v173, v173
	v_rcp_f32_e32 v174, v174
	v_rcp_f32_e32 v175, v175
	v_mul_f32_e32 v104, v104, v172
	v_mul_f32_e32 v105, v105, v173
	v_mul_f32_e32 v106, v106, v174
	v_mul_f32_e32 v107, v107, v175
	v_cvt_pk_bf16_f32 v104, v104, v105
	v_cvt_pk_bf16_f32 v106, v106, v107
	ds_write_b16 v161, v104 offset:2048
	ds_write_b16_d16_hi v161, v104 offset:2176
	ds_write_b16 v161, v106 offset:2304
	ds_write_b16_d16_hi v161, v106 offset:2432
	v_mul_f32_e32 v172, 0xbfb8aa3b, v108
	v_mul_f32_e32 v173, 0xbfb8aa3b, v109
	v_mul_f32_e32 v174, 0xbfb8aa3b, v110
	v_mul_f32_e32 v175, 0xbfb8aa3b, v111
	v_exp_f32_e32 v172, v172
	v_exp_f32_e32 v173, v173
	v_exp_f32_e32 v174, v174
	v_exp_f32_e32 v175, v175
	v_add_f32_e32 v172, 1.0, v172
	v_add_f32_e32 v173, 1.0, v173
	v_add_f32_e32 v174, 1.0, v174
	v_add_f32_e32 v175, 1.0, v175
	v_rcp_f32_e32 v172, v172
	v_rcp_f32_e32 v173, v173
	v_rcp_f32_e32 v174, v174
	v_rcp_f32_e32 v175, v175
	v_mul_f32_e32 v108, v108, v172
	v_mul_f32_e32 v109, v109, v173
	v_mul_f32_e32 v110, v110, v174
	v_mul_f32_e32 v111, v111, v175
	v_cvt_pk_bf16_f32 v108, v108, v109
	v_cvt_pk_bf16_f32 v110, v110, v111
	ds_write_b16 v161, v108 offset:3072
	ds_write_b16_d16_hi v161, v108 offset:3200
	ds_write_b16 v161, v110 offset:3328
	ds_write_b16_d16_hi v161, v110 offset:3456
	v_mul_f32_e32 v172, 0xbfb8aa3b, v80
	v_mul_f32_e32 v173, 0xbfb8aa3b, v81
	v_mul_f32_e32 v174, 0xbfb8aa3b, v82
	v_mul_f32_e32 v175, 0xbfb8aa3b, v83
	v_exp_f32_e32 v172, v172
	v_exp_f32_e32 v173, v173
	v_exp_f32_e32 v174, v174
	v_exp_f32_e32 v175, v175
	v_add_f32_e32 v172, 1.0, v172
	v_add_f32_e32 v173, 1.0, v173
	v_add_f32_e32 v174, 1.0, v174
	v_add_f32_e32 v175, 1.0, v175
	v_rcp_f32_e32 v172, v172
	v_rcp_f32_e32 v173, v173
	v_rcp_f32_e32 v174, v174
	v_rcp_f32_e32 v175, v175
	v_mul_f32_e32 v80, v80, v172
	v_mul_f32_e32 v81, v81, v173
	v_mul_f32_e32 v82, v82, v174
	v_mul_f32_e32 v83, v83, v175
	v_cvt_pk_bf16_f32 v80, v80, v81
	v_cvt_pk_bf16_f32 v82, v82, v83
	ds_write_b16 v160, v80 offset:4096
	ds_write_b16_d16_hi v160, v80 offset:4224
	ds_write_b16 v160, v82 offset:4352
	ds_write_b16_d16_hi v160, v82 offset:4480
	v_mul_f32_e32 v172, 0xbfb8aa3b, v84
	v_mul_f32_e32 v173, 0xbfb8aa3b, v85
	v_mul_f32_e32 v174, 0xbfb8aa3b, v86
	v_mul_f32_e32 v175, 0xbfb8aa3b, v87
	v_exp_f32_e32 v172, v172
	v_exp_f32_e32 v173, v173
	v_exp_f32_e32 v174, v174
	v_exp_f32_e32 v175, v175
	v_add_f32_e32 v172, 1.0, v172
	v_add_f32_e32 v173, 1.0, v173
	v_add_f32_e32 v174, 1.0, v174
	v_add_f32_e32 v175, 1.0, v175
	v_rcp_f32_e32 v172, v172
	v_rcp_f32_e32 v173, v173
	v_rcp_f32_e32 v174, v174
	v_rcp_f32_e32 v175, v175
	v_mul_f32_e32 v84, v84, v172
	v_mul_f32_e32 v85, v85, v173
	v_mul_f32_e32 v86, v86, v174
	v_mul_f32_e32 v87, v87, v175
	v_cvt_pk_bf16_f32 v84, v84, v85
	v_cvt_pk_bf16_f32 v86, v86, v87
	ds_write_b16 v160, v84 offset:5120
	ds_write_b16_d16_hi v160, v84 offset:5248
	ds_write_b16 v160, v86 offset:5376
	ds_write_b16_d16_hi v160, v86 offset:5504
	v_mul_f32_e32 v172, 0xbfb8aa3b, v88
	v_mul_f32_e32 v173, 0xbfb8aa3b, v89
	v_mul_f32_e32 v174, 0xbfb8aa3b, v90
	v_mul_f32_e32 v175, 0xbfb8aa3b, v91
	v_exp_f32_e32 v172, v172
	v_exp_f32_e32 v173, v173
	v_exp_f32_e32 v174, v174
	v_exp_f32_e32 v175, v175
	v_add_f32_e32 v172, 1.0, v172
	v_add_f32_e32 v173, 1.0, v173
	v_add_f32_e32 v174, 1.0, v174
	v_add_f32_e32 v175, 1.0, v175
	v_rcp_f32_e32 v172, v172
	v_rcp_f32_e32 v173, v173
	v_rcp_f32_e32 v174, v174
	v_rcp_f32_e32 v175, v175
	v_mul_f32_e32 v88, v88, v172
	v_mul_f32_e32 v89, v89, v173
	v_mul_f32_e32 v90, v90, v174
	v_mul_f32_e32 v91, v91, v175
	v_cvt_pk_bf16_f32 v88, v88, v89
	v_cvt_pk_bf16_f32 v90, v90, v91
	ds_write_b16 v160, v88 offset:6144
	ds_write_b16_d16_hi v160, v88 offset:6272
	ds_write_b16 v160, v90 offset:6400
	ds_write_b16_d16_hi v160, v90 offset:6528
	v_mul_f32_e32 v172, 0xbfb8aa3b, v92
	v_mul_f32_e32 v173, 0xbfb8aa3b, v93
	v_mul_f32_e32 v174, 0xbfb8aa3b, v94
	v_mul_f32_e32 v175, 0xbfb8aa3b, v95
	v_exp_f32_e32 v172, v172
	v_exp_f32_e32 v173, v173
	v_exp_f32_e32 v174, v174
	v_exp_f32_e32 v175, v175
	v_add_f32_e32 v172, 1.0, v172
	v_add_f32_e32 v173, 1.0, v173
	v_add_f32_e32 v174, 1.0, v174
	v_add_f32_e32 v175, 1.0, v175
	v_rcp_f32_e32 v172, v172
	v_rcp_f32_e32 v173, v173
	v_rcp_f32_e32 v174, v174
	v_rcp_f32_e32 v175, v175
	v_mul_f32_e32 v92, v92, v172
	v_mul_f32_e32 v93, v93, v173
	v_mul_f32_e32 v94, v94, v174
	v_mul_f32_e32 v95, v95, v175
	v_cvt_pk_bf16_f32 v92, v92, v93
	v_cvt_pk_bf16_f32 v94, v94, v95
	ds_write_b16 v160, v92 offset:7168
	ds_write_b16_d16_hi v160, v92 offset:7296
	ds_write_b16 v160, v94 offset:7424
	ds_write_b16_d16_hi v160, v94 offset:7552
	v_mul_f32_e32 v172, 0xbfb8aa3b, v64
	v_mul_f32_e32 v173, 0xbfb8aa3b, v65
	v_mul_f32_e32 v174, 0xbfb8aa3b, v66
	v_mul_f32_e32 v175, 0xbfb8aa3b, v67
	v_exp_f32_e32 v172, v172
	v_exp_f32_e32 v173, v173
	v_exp_f32_e32 v174, v174
	v_exp_f32_e32 v175, v175
	v_add_f32_e32 v172, 1.0, v172
	v_add_f32_e32 v173, 1.0, v173
	v_add_f32_e32 v174, 1.0, v174
	v_add_f32_e32 v175, 1.0, v175
	v_rcp_f32_e32 v172, v172
	v_rcp_f32_e32 v173, v173
	v_rcp_f32_e32 v174, v174
	v_rcp_f32_e32 v175, v175
	v_mul_f32_e32 v64, v64, v172
	v_mul_f32_e32 v65, v65, v173
	v_mul_f32_e32 v66, v66, v174
	v_mul_f32_e32 v67, v67, v175
	v_cvt_pk_bf16_f32 v64, v64, v65
	v_cvt_pk_bf16_f32 v66, v66, v67
	ds_write_b16 v161, v64 offset:4096
	ds_write_b16_d16_hi v161, v64 offset:4224
	ds_write_b16 v161, v66 offset:4352
	ds_write_b16_d16_hi v161, v66 offset:4480
	v_mul_f32_e32 v172, 0xbfb8aa3b, v68
	v_mul_f32_e32 v173, 0xbfb8aa3b, v69
	v_mul_f32_e32 v174, 0xbfb8aa3b, v70
	v_mul_f32_e32 v175, 0xbfb8aa3b, v71
	v_exp_f32_e32 v172, v172
	v_exp_f32_e32 v173, v173
	v_exp_f32_e32 v174, v174
	v_exp_f32_e32 v175, v175
	v_add_f32_e32 v172, 1.0, v172
	v_add_f32_e32 v173, 1.0, v173
	v_add_f32_e32 v174, 1.0, v174
	v_add_f32_e32 v175, 1.0, v175
	v_rcp_f32_e32 v172, v172
	v_rcp_f32_e32 v173, v173
	v_rcp_f32_e32 v174, v174
	v_rcp_f32_e32 v175, v175
	v_mul_f32_e32 v68, v68, v172
	v_mul_f32_e32 v69, v69, v173
	v_mul_f32_e32 v70, v70, v174
	v_mul_f32_e32 v71, v71, v175
	v_cvt_pk_bf16_f32 v68, v68, v69
	v_cvt_pk_bf16_f32 v70, v70, v71
	ds_write_b16 v161, v68 offset:5120
	ds_write_b16_d16_hi v161, v68 offset:5248
	ds_write_b16 v161, v70 offset:5376
	ds_write_b16_d16_hi v161, v70 offset:5504
	v_mul_f32_e32 v172, 0xbfb8aa3b, v72
	v_mul_f32_e32 v173, 0xbfb8aa3b, v73
	v_mul_f32_e32 v174, 0xbfb8aa3b, v74
	v_mul_f32_e32 v175, 0xbfb8aa3b, v75
	v_exp_f32_e32 v172, v172
	v_exp_f32_e32 v173, v173
	v_exp_f32_e32 v174, v174
	v_exp_f32_e32 v175, v175
	v_add_f32_e32 v172, 1.0, v172
	v_add_f32_e32 v173, 1.0, v173
	v_add_f32_e32 v174, 1.0, v174
	v_add_f32_e32 v175, 1.0, v175
	v_rcp_f32_e32 v172, v172
	v_rcp_f32_e32 v173, v173
	v_rcp_f32_e32 v174, v174
	v_rcp_f32_e32 v175, v175
	v_mul_f32_e32 v72, v72, v172
	v_mul_f32_e32 v73, v73, v173
	v_mul_f32_e32 v74, v74, v174
	v_mul_f32_e32 v75, v75, v175
	v_cvt_pk_bf16_f32 v72, v72, v73
	v_cvt_pk_bf16_f32 v74, v74, v75
	ds_write_b16 v161, v72 offset:6144
	ds_write_b16_d16_hi v161, v72 offset:6272
	ds_write_b16 v161, v74 offset:6400
	ds_write_b16_d16_hi v161, v74 offset:6528
	v_mul_f32_e32 v172, 0xbfb8aa3b, v76
	v_mul_f32_e32 v173, 0xbfb8aa3b, v77
	v_mul_f32_e32 v174, 0xbfb8aa3b, v78
	v_mul_f32_e32 v175, 0xbfb8aa3b, v79
	v_exp_f32_e32 v172, v172
	v_exp_f32_e32 v173, v173
	v_exp_f32_e32 v174, v174
	v_exp_f32_e32 v175, v175
	v_add_f32_e32 v172, 1.0, v172
	v_add_f32_e32 v173, 1.0, v173
	v_add_f32_e32 v174, 1.0, v174
	v_add_f32_e32 v175, 1.0, v175
	v_rcp_f32_e32 v172, v172
	v_rcp_f32_e32 v173, v173
	v_rcp_f32_e32 v174, v174
	v_rcp_f32_e32 v175, v175
	v_mul_f32_e32 v76, v76, v172
	v_mul_f32_e32 v77, v77, v173
	v_mul_f32_e32 v78, v78, v174
	v_mul_f32_e32 v79, v79, v175
	v_cvt_pk_bf16_f32 v76, v76, v77
	v_cvt_pk_bf16_f32 v78, v78, v79
	ds_write_b16 v161, v76 offset:7168
	ds_write_b16_d16_hi v161, v76 offset:7296
	ds_write_b16 v161, v78 offset:7424
	ds_write_b16_d16_hi v161, v78 offset:7552
	v_mul_f32_e32 v172, 0xbfb8aa3b, v48
	v_mul_f32_e32 v173, 0xbfb8aa3b, v49
	v_mul_f32_e32 v174, 0xbfb8aa3b, v50
	v_mul_f32_e32 v175, 0xbfb8aa3b, v51
	v_exp_f32_e32 v172, v172
	v_exp_f32_e32 v173, v173
	v_exp_f32_e32 v174, v174
	v_exp_f32_e32 v175, v175
	v_add_f32_e32 v172, 1.0, v172
	v_add_f32_e32 v173, 1.0, v173
	v_add_f32_e32 v174, 1.0, v174
	v_add_f32_e32 v175, 1.0, v175
	v_rcp_f32_e32 v172, v172
	v_rcp_f32_e32 v173, v173
	v_rcp_f32_e32 v174, v174
	v_rcp_f32_e32 v175, v175
	v_mul_f32_e32 v48, v48, v172
	v_mul_f32_e32 v49, v49, v173
	v_mul_f32_e32 v50, v50, v174
	v_mul_f32_e32 v51, v51, v175
	v_cvt_pk_bf16_f32 v48, v48, v49
	v_cvt_pk_bf16_f32 v50, v50, v51
	ds_write_b16 v160, v48 offset:8192
	ds_write_b16_d16_hi v160, v48 offset:8320
	ds_write_b16 v160, v50 offset:8448
	ds_write_b16_d16_hi v160, v50 offset:8576
	v_mul_f32_e32 v172, 0xbfb8aa3b, v52
	v_mul_f32_e32 v173, 0xbfb8aa3b, v53
	v_mul_f32_e32 v174, 0xbfb8aa3b, v54
	v_mul_f32_e32 v175, 0xbfb8aa3b, v55
	v_exp_f32_e32 v172, v172
	v_exp_f32_e32 v173, v173
	v_exp_f32_e32 v174, v174
	v_exp_f32_e32 v175, v175
	v_add_f32_e32 v172, 1.0, v172
	v_add_f32_e32 v173, 1.0, v173
	v_add_f32_e32 v174, 1.0, v174
	v_add_f32_e32 v175, 1.0, v175
	v_rcp_f32_e32 v172, v172
	v_rcp_f32_e32 v173, v173
	v_rcp_f32_e32 v174, v174
	v_rcp_f32_e32 v175, v175
	v_mul_f32_e32 v52, v52, v172
	v_mul_f32_e32 v53, v53, v173
	v_mul_f32_e32 v54, v54, v174
	v_mul_f32_e32 v55, v55, v175
	v_cvt_pk_bf16_f32 v52, v52, v53
	v_cvt_pk_bf16_f32 v54, v54, v55
	ds_write_b16 v160, v52 offset:9216
	ds_write_b16_d16_hi v160, v52 offset:9344
	ds_write_b16 v160, v54 offset:9472
	ds_write_b16_d16_hi v160, v54 offset:9600
	v_mul_f32_e32 v172, 0xbfb8aa3b, v56
	v_mul_f32_e32 v173, 0xbfb8aa3b, v57
	v_mul_f32_e32 v174, 0xbfb8aa3b, v58
	v_mul_f32_e32 v175, 0xbfb8aa3b, v59
	v_exp_f32_e32 v172, v172
	v_exp_f32_e32 v173, v173
	v_exp_f32_e32 v174, v174
	v_exp_f32_e32 v175, v175
	v_add_f32_e32 v172, 1.0, v172
	v_add_f32_e32 v173, 1.0, v173
	v_add_f32_e32 v174, 1.0, v174
	v_add_f32_e32 v175, 1.0, v175
	v_rcp_f32_e32 v172, v172
	v_rcp_f32_e32 v173, v173
	v_rcp_f32_e32 v174, v174
	v_rcp_f32_e32 v175, v175
	v_mul_f32_e32 v56, v56, v172
	v_mul_f32_e32 v57, v57, v173
	v_mul_f32_e32 v58, v58, v174
	v_mul_f32_e32 v59, v59, v175
	v_cvt_pk_bf16_f32 v56, v56, v57
	v_cvt_pk_bf16_f32 v58, v58, v59
	ds_write_b16 v160, v56 offset:10240
	ds_write_b16_d16_hi v160, v56 offset:10368
	ds_write_b16 v160, v58 offset:10496
	ds_write_b16_d16_hi v160, v58 offset:10624
	v_mul_f32_e32 v172, 0xbfb8aa3b, v60
	v_mul_f32_e32 v173, 0xbfb8aa3b, v61
	v_mul_f32_e32 v174, 0xbfb8aa3b, v62
	v_mul_f32_e32 v175, 0xbfb8aa3b, v63
	v_exp_f32_e32 v172, v172
	v_exp_f32_e32 v173, v173
	v_exp_f32_e32 v174, v174
	v_exp_f32_e32 v175, v175
	v_add_f32_e32 v172, 1.0, v172
	v_add_f32_e32 v173, 1.0, v173
	v_add_f32_e32 v174, 1.0, v174
	v_add_f32_e32 v175, 1.0, v175
	v_rcp_f32_e32 v172, v172
	v_rcp_f32_e32 v173, v173
	v_rcp_f32_e32 v174, v174
	v_rcp_f32_e32 v175, v175
	v_mul_f32_e32 v60, v60, v172
	v_mul_f32_e32 v61, v61, v173
	v_mul_f32_e32 v62, v62, v174
	v_mul_f32_e32 v63, v63, v175
	v_cvt_pk_bf16_f32 v60, v60, v61
	v_cvt_pk_bf16_f32 v62, v62, v63
	ds_write_b16 v160, v60 offset:11264
	ds_write_b16_d16_hi v160, v60 offset:11392
	ds_write_b16 v160, v62 offset:11520
	ds_write_b16_d16_hi v160, v62 offset:11648
	v_mul_f32_e32 v172, 0xbfb8aa3b, v32
	v_mul_f32_e32 v173, 0xbfb8aa3b, v33
	v_mul_f32_e32 v174, 0xbfb8aa3b, v34
	v_mul_f32_e32 v175, 0xbfb8aa3b, v35
	v_exp_f32_e32 v172, v172
	v_exp_f32_e32 v173, v173
	v_exp_f32_e32 v174, v174
	v_exp_f32_e32 v175, v175
	v_add_f32_e32 v172, 1.0, v172
	v_add_f32_e32 v173, 1.0, v173
	v_add_f32_e32 v174, 1.0, v174
	v_add_f32_e32 v175, 1.0, v175
	v_rcp_f32_e32 v172, v172
	v_rcp_f32_e32 v173, v173
	v_rcp_f32_e32 v174, v174
	v_rcp_f32_e32 v175, v175
	v_mul_f32_e32 v32, v32, v172
	v_mul_f32_e32 v33, v33, v173
	v_mul_f32_e32 v34, v34, v174
	v_mul_f32_e32 v35, v35, v175
	v_cvt_pk_bf16_f32 v32, v32, v33
	v_cvt_pk_bf16_f32 v34, v34, v35
	ds_write_b16 v161, v32 offset:8192
	ds_write_b16_d16_hi v161, v32 offset:8320
	ds_write_b16 v161, v34 offset:8448
	ds_write_b16_d16_hi v161, v34 offset:8576
	v_mul_f32_e32 v172, 0xbfb8aa3b, v36
	v_mul_f32_e32 v173, 0xbfb8aa3b, v37
	v_mul_f32_e32 v174, 0xbfb8aa3b, v38
	v_mul_f32_e32 v175, 0xbfb8aa3b, v39
	v_exp_f32_e32 v172, v172
	v_exp_f32_e32 v173, v173
	v_exp_f32_e32 v174, v174
	v_exp_f32_e32 v175, v175
	v_add_f32_e32 v172, 1.0, v172
	v_add_f32_e32 v173, 1.0, v173
	v_add_f32_e32 v174, 1.0, v174
	v_add_f32_e32 v175, 1.0, v175
	v_rcp_f32_e32 v172, v172
	v_rcp_f32_e32 v173, v173
	v_rcp_f32_e32 v174, v174
	v_rcp_f32_e32 v175, v175
	v_mul_f32_e32 v36, v36, v172
	v_mul_f32_e32 v37, v37, v173
	v_mul_f32_e32 v38, v38, v174
	v_mul_f32_e32 v39, v39, v175
	v_cvt_pk_bf16_f32 v36, v36, v37
	v_cvt_pk_bf16_f32 v38, v38, v39
	ds_write_b16 v161, v36 offset:9216
	ds_write_b16_d16_hi v161, v36 offset:9344
	ds_write_b16 v161, v38 offset:9472
	ds_write_b16_d16_hi v161, v38 offset:9600
	v_mul_f32_e32 v172, 0xbfb8aa3b, v40
	v_mul_f32_e32 v173, 0xbfb8aa3b, v41
	v_mul_f32_e32 v174, 0xbfb8aa3b, v42
	v_mul_f32_e32 v175, 0xbfb8aa3b, v43
	v_exp_f32_e32 v172, v172
	v_exp_f32_e32 v173, v173
	v_exp_f32_e32 v174, v174
	v_exp_f32_e32 v175, v175
	v_add_f32_e32 v172, 1.0, v172
	v_add_f32_e32 v173, 1.0, v173
	v_add_f32_e32 v174, 1.0, v174
	v_add_f32_e32 v175, 1.0, v175
	v_rcp_f32_e32 v172, v172
	v_rcp_f32_e32 v173, v173
	v_rcp_f32_e32 v174, v174
	v_rcp_f32_e32 v175, v175
	v_mul_f32_e32 v40, v40, v172
	v_mul_f32_e32 v41, v41, v173
	v_mul_f32_e32 v42, v42, v174
	v_mul_f32_e32 v43, v43, v175
	v_cvt_pk_bf16_f32 v40, v40, v41
	v_cvt_pk_bf16_f32 v42, v42, v43
	ds_write_b16 v161, v40 offset:10240
	ds_write_b16_d16_hi v161, v40 offset:10368
	ds_write_b16 v161, v42 offset:10496
	ds_write_b16_d16_hi v161, v42 offset:10624
	v_mul_f32_e32 v172, 0xbfb8aa3b, v44
	v_mul_f32_e32 v173, 0xbfb8aa3b, v45
	v_mul_f32_e32 v174, 0xbfb8aa3b, v46
	v_mul_f32_e32 v175, 0xbfb8aa3b, v47
	v_exp_f32_e32 v172, v172
	v_exp_f32_e32 v173, v173
	v_exp_f32_e32 v174, v174
	v_exp_f32_e32 v175, v175
	v_add_f32_e32 v172, 1.0, v172
	v_add_f32_e32 v173, 1.0, v173
	v_add_f32_e32 v174, 1.0, v174
	v_add_f32_e32 v175, 1.0, v175
	v_rcp_f32_e32 v172, v172
	v_rcp_f32_e32 v173, v173
	v_rcp_f32_e32 v174, v174
	v_rcp_f32_e32 v175, v175
	v_mul_f32_e32 v44, v44, v172
	v_mul_f32_e32 v45, v45, v173
	v_mul_f32_e32 v46, v46, v174
	v_mul_f32_e32 v47, v47, v175
	v_cvt_pk_bf16_f32 v44, v44, v45
	v_cvt_pk_bf16_f32 v46, v46, v47
	ds_write_b16 v161, v44 offset:11264
	ds_write_b16_d16_hi v161, v44 offset:11392
	ds_write_b16 v161, v46 offset:11520
	ds_write_b16_d16_hi v161, v46 offset:11648
	v_mul_f32_e32 v172, 0xbfb8aa3b, v16
	v_mul_f32_e32 v173, 0xbfb8aa3b, v17
	v_mul_f32_e32 v174, 0xbfb8aa3b, v18
	v_mul_f32_e32 v175, 0xbfb8aa3b, v19
	v_exp_f32_e32 v172, v172
	v_exp_f32_e32 v173, v173
	v_exp_f32_e32 v174, v174
	v_exp_f32_e32 v175, v175
	v_add_f32_e32 v172, 1.0, v172
	v_add_f32_e32 v173, 1.0, v173
	v_add_f32_e32 v174, 1.0, v174
	v_add_f32_e32 v175, 1.0, v175
	v_rcp_f32_e32 v172, v172
	v_rcp_f32_e32 v173, v173
	v_rcp_f32_e32 v174, v174
	v_rcp_f32_e32 v175, v175
	v_mul_f32_e32 v16, v16, v172
	v_mul_f32_e32 v17, v17, v173
	v_mul_f32_e32 v18, v18, v174
	v_mul_f32_e32 v19, v19, v175
	v_cvt_pk_bf16_f32 v16, v16, v17
	v_cvt_pk_bf16_f32 v18, v18, v19
	ds_write_b16 v160, v16 offset:12288
	ds_write_b16_d16_hi v160, v16 offset:12416
	ds_write_b16 v160, v18 offset:12544
	ds_write_b16_d16_hi v160, v18 offset:12672
	v_mul_f32_e32 v172, 0xbfb8aa3b, v20
	v_mul_f32_e32 v173, 0xbfb8aa3b, v21
	v_mul_f32_e32 v174, 0xbfb8aa3b, v22
	v_mul_f32_e32 v175, 0xbfb8aa3b, v23
	v_exp_f32_e32 v172, v172
	v_exp_f32_e32 v173, v173
	v_exp_f32_e32 v174, v174
	v_exp_f32_e32 v175, v175
	v_add_f32_e32 v172, 1.0, v172
	v_add_f32_e32 v173, 1.0, v173
	v_add_f32_e32 v174, 1.0, v174
	v_add_f32_e32 v175, 1.0, v175
	v_rcp_f32_e32 v172, v172
	v_rcp_f32_e32 v173, v173
	v_rcp_f32_e32 v174, v174
	v_rcp_f32_e32 v175, v175
	v_mul_f32_e32 v20, v20, v172
	v_mul_f32_e32 v21, v21, v173
	v_mul_f32_e32 v22, v22, v174
	v_mul_f32_e32 v23, v23, v175
	v_cvt_pk_bf16_f32 v20, v20, v21
	v_cvt_pk_bf16_f32 v22, v22, v23
	ds_write_b16 v160, v20 offset:13312
	ds_write_b16_d16_hi v160, v20 offset:13440
	ds_write_b16 v160, v22 offset:13568
	ds_write_b16_d16_hi v160, v22 offset:13696
	v_mul_f32_e32 v172, 0xbfb8aa3b, v24
	v_mul_f32_e32 v173, 0xbfb8aa3b, v25
	v_mul_f32_e32 v174, 0xbfb8aa3b, v26
	v_mul_f32_e32 v175, 0xbfb8aa3b, v27
	v_exp_f32_e32 v172, v172
	v_exp_f32_e32 v173, v173
	v_exp_f32_e32 v174, v174
	v_exp_f32_e32 v175, v175
	v_add_f32_e32 v172, 1.0, v172
	v_add_f32_e32 v173, 1.0, v173
	v_add_f32_e32 v174, 1.0, v174
	v_add_f32_e32 v175, 1.0, v175
	v_rcp_f32_e32 v172, v172
	v_rcp_f32_e32 v173, v173
	v_rcp_f32_e32 v174, v174
	v_rcp_f32_e32 v175, v175
	v_mul_f32_e32 v24, v24, v172
	v_mul_f32_e32 v25, v25, v173
	v_mul_f32_e32 v26, v26, v174
	v_mul_f32_e32 v27, v27, v175
	v_cvt_pk_bf16_f32 v24, v24, v25
	v_cvt_pk_bf16_f32 v26, v26, v27
	ds_write_b16 v160, v24 offset:14336
	ds_write_b16_d16_hi v160, v24 offset:14464
	ds_write_b16 v160, v26 offset:14592
	ds_write_b16_d16_hi v160, v26 offset:14720
	v_mul_f32_e32 v172, 0xbfb8aa3b, v28
	v_mul_f32_e32 v173, 0xbfb8aa3b, v29
	v_mul_f32_e32 v174, 0xbfb8aa3b, v30
	v_mul_f32_e32 v175, 0xbfb8aa3b, v31
	v_exp_f32_e32 v172, v172
	v_exp_f32_e32 v173, v173
	v_exp_f32_e32 v174, v174
	v_exp_f32_e32 v175, v175
	v_add_f32_e32 v172, 1.0, v172
	v_add_f32_e32 v173, 1.0, v173
	v_add_f32_e32 v174, 1.0, v174
	v_add_f32_e32 v175, 1.0, v175
	v_rcp_f32_e32 v172, v172
	v_rcp_f32_e32 v173, v173
	v_rcp_f32_e32 v174, v174
	v_rcp_f32_e32 v175, v175
	v_mul_f32_e32 v28, v28, v172
	v_mul_f32_e32 v29, v29, v173
	v_mul_f32_e32 v30, v30, v174
	v_mul_f32_e32 v31, v31, v175
	v_cvt_pk_bf16_f32 v28, v28, v29
	v_cvt_pk_bf16_f32 v30, v30, v31
	ds_write_b16 v160, v28 offset:15360
	ds_write_b16_d16_hi v160, v28 offset:15488
	ds_write_b16 v160, v30 offset:15616
	ds_write_b16_d16_hi v160, v30 offset:15744
	v_mul_f32_e32 v172, 0xbfb8aa3b, v0
	v_mul_f32_e32 v173, 0xbfb8aa3b, v1
	v_mul_f32_e32 v174, 0xbfb8aa3b, v2
	v_mul_f32_e32 v175, 0xbfb8aa3b, v3
	v_exp_f32_e32 v172, v172
	v_exp_f32_e32 v173, v173
	v_exp_f32_e32 v174, v174
	v_exp_f32_e32 v175, v175
	v_add_f32_e32 v172, 1.0, v172
	v_add_f32_e32 v173, 1.0, v173
	v_add_f32_e32 v174, 1.0, v174
	v_add_f32_e32 v175, 1.0, v175
	v_rcp_f32_e32 v172, v172
	v_rcp_f32_e32 v173, v173
	v_rcp_f32_e32 v174, v174
	v_rcp_f32_e32 v175, v175
	v_mul_f32_e32 v0, v0, v172
	v_mul_f32_e32 v1, v1, v173
	v_mul_f32_e32 v2, v2, v174
	v_mul_f32_e32 v3, v3, v175
	v_cvt_pk_bf16_f32 v0, v0, v1
	v_cvt_pk_bf16_f32 v2, v2, v3
	ds_write_b16 v161, v0 offset:12288
	ds_write_b16_d16_hi v161, v0 offset:12416
	ds_write_b16 v161, v2 offset:12544
	ds_write_b16_d16_hi v161, v2 offset:12672
	v_mul_f32_e32 v172, 0xbfb8aa3b, v4
	v_mul_f32_e32 v173, 0xbfb8aa3b, v5
	v_mul_f32_e32 v174, 0xbfb8aa3b, v6
	v_mul_f32_e32 v175, 0xbfb8aa3b, v7
	v_exp_f32_e32 v172, v172
	v_exp_f32_e32 v173, v173
	v_exp_f32_e32 v174, v174
	v_exp_f32_e32 v175, v175
	v_add_f32_e32 v172, 1.0, v172
	v_add_f32_e32 v173, 1.0, v173
	v_add_f32_e32 v174, 1.0, v174
	v_add_f32_e32 v175, 1.0, v175
	v_rcp_f32_e32 v172, v172
	v_rcp_f32_e32 v173, v173
	v_rcp_f32_e32 v174, v174
	v_rcp_f32_e32 v175, v175
	v_mul_f32_e32 v4, v4, v172
	v_mul_f32_e32 v5, v5, v173
	v_mul_f32_e32 v6, v6, v174
	v_mul_f32_e32 v7, v7, v175
	v_cvt_pk_bf16_f32 v4, v4, v5
	v_cvt_pk_bf16_f32 v6, v6, v7
	ds_write_b16 v161, v4 offset:13312
	ds_write_b16_d16_hi v161, v4 offset:13440
	ds_write_b16 v161, v6 offset:13568
	ds_write_b16_d16_hi v161, v6 offset:13696
	v_mul_f32_e32 v172, 0xbfb8aa3b, v8
	v_mul_f32_e32 v173, 0xbfb8aa3b, v9
	v_mul_f32_e32 v174, 0xbfb8aa3b, v10
	v_mul_f32_e32 v175, 0xbfb8aa3b, v11
	v_exp_f32_e32 v172, v172
	v_exp_f32_e32 v173, v173
	v_exp_f32_e32 v174, v174
	v_exp_f32_e32 v175, v175
	v_add_f32_e32 v172, 1.0, v172
	v_add_f32_e32 v173, 1.0, v173
	v_add_f32_e32 v174, 1.0, v174
	v_add_f32_e32 v175, 1.0, v175
	v_rcp_f32_e32 v172, v172
	v_rcp_f32_e32 v173, v173
	v_rcp_f32_e32 v174, v174
	v_rcp_f32_e32 v175, v175
	v_mul_f32_e32 v8, v8, v172
	v_mul_f32_e32 v9, v9, v173
	v_mul_f32_e32 v10, v10, v174
	v_mul_f32_e32 v11, v11, v175
	v_cvt_pk_bf16_f32 v8, v8, v9
	v_cvt_pk_bf16_f32 v10, v10, v11
	ds_write_b16 v161, v8 offset:14336
	ds_write_b16_d16_hi v161, v8 offset:14464
	ds_write_b16 v161, v10 offset:14592
	ds_write_b16_d16_hi v161, v10 offset:14720
	v_mul_f32_e32 v172, 0xbfb8aa3b, v12
	v_mul_f32_e32 v173, 0xbfb8aa3b, v13
	v_mul_f32_e32 v174, 0xbfb8aa3b, v14
	v_mul_f32_e32 v175, 0xbfb8aa3b, v15
	v_exp_f32_e32 v172, v172
	v_exp_f32_e32 v173, v173
	v_exp_f32_e32 v174, v174
	v_exp_f32_e32 v175, v175
	v_add_f32_e32 v172, 1.0, v172
	v_add_f32_e32 v173, 1.0, v173
	v_add_f32_e32 v174, 1.0, v174
	v_add_f32_e32 v175, 1.0, v175
	v_rcp_f32_e32 v172, v172
	v_rcp_f32_e32 v173, v173
	v_rcp_f32_e32 v174, v174
	v_rcp_f32_e32 v175, v175
	v_mul_f32_e32 v12, v12, v172
	v_mul_f32_e32 v13, v13, v173
	v_mul_f32_e32 v14, v14, v174
	v_mul_f32_e32 v15, v15, v175
	v_cvt_pk_bf16_f32 v12, v12, v13
	v_cvt_pk_bf16_f32 v14, v14, v15
	ds_write_b16 v161, v12 offset:15360
	ds_write_b16_d16_hi v161, v12 offset:15488
	ds_write_b16 v161, v14 offset:15616
	ds_write_b16_d16_hi v161, v14 offset:15744
	s_waitcnt lgkmcnt(0)
	ds_read_b128 v[128:131], v166 offset:0
	ds_read_b128 v[132:135], v166 offset:1024
	ds_read_b128 v[136:139], v166 offset:2048
	ds_read_b128 v[140:143], v166 offset:3072
	s_waitcnt lgkmcnt(3)
	global_store_dwordx4 v[170:171], v[128:131], off
	v_lshl_add_u64 v[170:171], v[170:171], 0, s[0:1]
	s_waitcnt lgkmcnt(2)
	global_store_dwordx4 v[170:171], v[132:135], off
	v_lshl_add_u64 v[170:171], v[170:171], 0, s[0:1]
	s_waitcnt lgkmcnt(1)
	global_store_dwordx4 v[170:171], v[136:139], off
	v_lshl_add_u64 v[170:171], v[170:171], 0, s[0:1]
	s_waitcnt lgkmcnt(0)
	global_store_dwordx4 v[170:171], v[140:143], off
	v_lshl_add_u64 v[170:171], v[170:171], 0, s[0:1]
	ds_read_b128 v[128:131], v166 offset:4096
	ds_read_b128 v[132:135], v166 offset:5120
	ds_read_b128 v[136:139], v166 offset:6144
	ds_read_b128 v[140:143], v166 offset:7168
	s_waitcnt lgkmcnt(3)
	global_store_dwordx4 v[170:171], v[128:131], off
	v_lshl_add_u64 v[170:171], v[170:171], 0, s[0:1]
	s_waitcnt lgkmcnt(2)
	global_store_dwordx4 v[170:171], v[132:135], off
	v_lshl_add_u64 v[170:171], v[170:171], 0, s[0:1]
	s_waitcnt lgkmcnt(1)
	global_store_dwordx4 v[170:171], v[136:139], off
	v_lshl_add_u64 v[170:171], v[170:171], 0, s[0:1]
	s_waitcnt lgkmcnt(0)
	global_store_dwordx4 v[170:171], v[140:143], off
	v_lshl_add_u64 v[170:171], v[170:171], 0, s[0:1]
	ds_read_b128 v[128:131], v166 offset:8192
	ds_read_b128 v[132:135], v166 offset:9216
	ds_read_b128 v[136:139], v166 offset:10240
	ds_read_b128 v[140:143], v166 offset:11264
	s_waitcnt lgkmcnt(3)
	global_store_dwordx4 v[170:171], v[128:131], off
	v_lshl_add_u64 v[170:171], v[170:171], 0, s[0:1]
	s_waitcnt lgkmcnt(2)
	global_store_dwordx4 v[170:171], v[132:135], off
	v_lshl_add_u64 v[170:171], v[170:171], 0, s[0:1]
	s_waitcnt lgkmcnt(1)
	global_store_dwordx4 v[170:171], v[136:139], off
	v_lshl_add_u64 v[170:171], v[170:171], 0, s[0:1]
	s_waitcnt lgkmcnt(0)
	global_store_dwordx4 v[170:171], v[140:143], off
	v_lshl_add_u64 v[170:171], v[170:171], 0, s[0:1]
	ds_read_b128 v[128:131], v166 offset:12288
	ds_read_b128 v[132:135], v166 offset:13312
	ds_read_b128 v[136:139], v166 offset:14336
	ds_read_b128 v[140:143], v166 offset:15360
	s_waitcnt lgkmcnt(3)
	global_store_dwordx4 v[170:171], v[128:131], off
	v_lshl_add_u64 v[170:171], v[170:171], 0, s[0:1]
	s_waitcnt lgkmcnt(2)
	global_store_dwordx4 v[170:171], v[132:135], off
	v_lshl_add_u64 v[170:171], v[170:171], 0, s[0:1]
	s_waitcnt lgkmcnt(1)
	global_store_dwordx4 v[170:171], v[136:139], off
	v_lshl_add_u64 v[170:171], v[170:171], 0, s[0:1]
	s_waitcnt lgkmcnt(0)
	global_store_dwordx4 v[170:171], v[140:143], off
	v_lshl_add_u64 v[170:171], v[170:171], 0, s[0:1]
	s_mov_b64 s[0:1], 0
	s_barrier
